# v66 with the k-vector LDS reads of each scan step issued right after the a-wait (13 LDS ops in flight)
# baseline (speedup 1.0000x reference)
.LBB0_965:
	s_add_i32 s82, s67, s99
	s_ashr_i32 s83, s82, 31
	s_lshl_b64 s[82:83], s[82:83], 7
	v_lshl_add_u64 v[238:239], v[124:125], 0, s[82:83]
	v_add_u32_e32 v218, s97, v232
	v_lshl_add_u32 v222, v114, 2, s57
	v_add_u32_e32 v219, s98, v218
	v_add_u32_e32 v222, s97, v222
	v_add_u32_e32 v220, s98, v219
	v_add_u32_e32 v223, s98, v222
	v_add_u32_e32 v221, s98, v220
	v_add_u32_e32 v236, s98, v223
	v_add_u32_e32 v237, s98, v236
	ds_read_b128 v[92:95], v218 offset:256
	ds_read_b128 v[96:99], v218 offset:272
	ds_read_b128 v[100:103], v218 offset:288
	ds_read_b128 v[104:107], v218 offset:304
	ds_read_b128 v[108:111], v218 offset:512
	ds_read_b128 v[170:173], v218 offset:528
	ds_read_b128 v[174:177], v218 offset:544
	ds_read_b128 v[178:181], v218 offset:560
	ds_read_b128 v[198:201], v222 offset:1280
	s_waitcnt lgkmcnt(9)
	ds_read_b128 v[182:185], v218 offset:768
	ds_read_b128 v[186:189], v218 offset:784
	ds_read_b128 v[190:193], v218 offset:800
	ds_read_b128 v[194:197], v218 offset:816
	v_pk_mul_f32 v[202:203], v[72:73], v[76:77]
	v_pk_mul_f32 v[204:205], v[74:75], v[78:79]
	v_pk_mul_f32 v[206:207], v[60:61], v[76:77]
	v_pk_mul_f32 v[208:209], v[62:63], v[78:79]
	v_pk_mul_f32 v[210:211], v[48:49], v[76:77]
	v_pk_mul_f32 v[212:213], v[50:51], v[78:79]
	v_pk_mul_f32 v[214:215], v[32:33], v[76:77]
	v_pk_mul_f32 v[216:217], v[34:35], v[78:79]
	v_pk_fma_f32 v[202:203], v[68:69], v[80:81], v[202:203]
	v_pk_fma_f32 v[204:205], v[70:71], v[82:83], v[204:205]
	v_pk_fma_f32 v[206:207], v[52:53], v[80:81], v[206:207]
	v_pk_fma_f32 v[208:209], v[54:55], v[82:83], v[208:209]
	v_pk_fma_f32 v[210:211], v[40:41], v[80:81], v[210:211]
	v_pk_fma_f32 v[212:213], v[42:43], v[82:83], v[212:213]
	v_pk_fma_f32 v[214:215], v[24:25], v[80:81], v[214:215]
	v_pk_fma_f32 v[216:217], v[26:27], v[82:83], v[216:217]
	v_pk_fma_f32 v[202:203], v[64:65], v[84:85], v[202:203]
	v_pk_fma_f32 v[204:205], v[66:67], v[86:87], v[204:205]
	v_pk_fma_f32 v[206:207], v[44:45], v[84:85], v[206:207]
	v_pk_fma_f32 v[208:209], v[46:47], v[86:87], v[208:209]
	v_pk_fma_f32 v[210:211], v[28:29], v[84:85], v[210:211]
	v_pk_fma_f32 v[212:213], v[30:31], v[86:87], v[212:213]
	v_pk_fma_f32 v[214:215], v[16:17], v[84:85], v[214:215]
	v_pk_fma_f32 v[216:217], v[18:19], v[86:87], v[216:217]
	v_pk_fma_f32 v[202:203], v[56:57], v[88:89], v[202:203]
	v_pk_fma_f32 v[204:205], v[58:59], v[90:91], v[204:205]
	v_pk_fma_f32 v[206:207], v[36:37], v[88:89], v[206:207]
	v_pk_fma_f32 v[208:209], v[38:39], v[90:91], v[208:209]
	v_pk_fma_f32 v[210:211], v[20:21], v[88:89], v[210:211]
	v_pk_fma_f32 v[212:213], v[22:23], v[90:91], v[212:213]
	v_pk_fma_f32 v[214:215], v[12:13], v[88:89], v[214:215]
	v_pk_fma_f32 v[216:217], v[14:15], v[90:91], v[216:217]
	s_waitcnt lgkmcnt(5)
	v_pk_add_f32 v[202:203], v[202:203], v[204:205]
	v_pk_add_f32 v[206:207], v[206:207], v[208:209]
	v_pk_add_f32 v[210:211], v[210:211], v[212:213]
	v_pk_add_f32 v[214:215], v[214:215], v[216:217]
	v_add_f32_e32 v202, v202, v203
	v_add_f32_e32 v206, v206, v207
	v_add_f32_e32 v210, v210, v211
	v_add_f32_e32 v214, v214, v215
	v_add_f32_dpp v202, v202, v202 quad_perm:[1,0,3,2] row_mask:0xf bank_mask:0xf bound_ctrl:1
	v_add_f32_dpp v206, v206, v206 quad_perm:[1,0,3,2] row_mask:0xf bank_mask:0xf bound_ctrl:1
	v_add_f32_dpp v210, v210, v210 quad_perm:[1,0,3,2] row_mask:0xf bank_mask:0xf bound_ctrl:1
	v_add_f32_dpp v214, v214, v214 quad_perm:[1,0,3,2] row_mask:0xf bank_mask:0xf bound_ctrl:1
	v_add_f32_dpp v202, v202, v202 quad_perm:[2,3,0,1] row_mask:0xf bank_mask:0xf bound_ctrl:1
	v_add_f32_dpp v206, v206, v206 quad_perm:[2,3,0,1] row_mask:0xf bank_mask:0xf bound_ctrl:1
	v_add_f32_dpp v210, v210, v210 quad_perm:[2,3,0,1] row_mask:0xf bank_mask:0xf bound_ctrl:1
	v_add_f32_dpp v214, v214, v214 quad_perm:[2,3,0,1] row_mask:0xf bank_mask:0xf bound_ctrl:1
	v_pk_mul_f32 v[204:205], v[108:109], v[202:203] op_sel_hi:[1,0]
	v_pk_mul_f32 v[208:209], v[108:109], v[206:207] op_sel_hi:[1,0]
	v_pk_mul_f32 v[212:213], v[108:109], v[210:211] op_sel_hi:[1,0]
	v_pk_mul_f32 v[108:109], v[108:109], v[214:215] op_sel_hi:[1,0]
	v_pk_fma_f32 v[72:73], v[72:73], v[92:93], v[204:205]
	v_pk_fma_f32 v[60:61], v[60:61], v[92:93], v[208:209]
	v_pk_fma_f32 v[48:49], v[48:49], v[92:93], v[212:213]
	v_pk_fma_f32 v[32:33], v[32:33], v[92:93], v[108:109]
	v_pk_mul_f32 v[216:217], v[110:111], v[202:203] op_sel_hi:[1,0]
	v_pk_mul_f32 v[242:243], v[110:111], v[206:207] op_sel_hi:[1,0]
	v_pk_mul_f32 v[244:245], v[110:111], v[210:211] op_sel_hi:[1,0]
	v_pk_mul_f32 v[110:111], v[110:111], v[214:215] op_sel_hi:[1,0]
	v_pk_fma_f32 v[74:75], v[74:75], v[94:95], v[216:217]
	v_pk_fma_f32 v[62:63], v[62:63], v[94:95], v[242:243]
	v_pk_fma_f32 v[50:51], v[50:51], v[94:95], v[244:245]
	v_pk_fma_f32 v[34:35], v[34:35], v[94:95], v[110:111]
	v_pk_mul_f32 v[204:205], v[170:171], v[202:203] op_sel_hi:[1,0]
	v_pk_mul_f32 v[208:209], v[170:171], v[206:207] op_sel_hi:[1,0]
	v_pk_mul_f32 v[212:213], v[170:171], v[210:211] op_sel_hi:[1,0]
	v_pk_mul_f32 v[170:171], v[170:171], v[214:215] op_sel_hi:[1,0]
	v_pk_fma_f32 v[68:69], v[68:69], v[96:97], v[204:205]
	v_pk_fma_f32 v[52:53], v[52:53], v[96:97], v[208:209]
	v_pk_fma_f32 v[40:41], v[40:41], v[96:97], v[212:213]
	v_pk_fma_f32 v[24:25], v[24:25], v[96:97], v[170:171]
	v_pk_mul_f32 v[216:217], v[172:173], v[202:203] op_sel_hi:[1,0]
	v_pk_mul_f32 v[242:243], v[172:173], v[206:207] op_sel_hi:[1,0]
	v_pk_mul_f32 v[244:245], v[172:173], v[210:211] op_sel_hi:[1,0]
	v_pk_mul_f32 v[172:173], v[172:173], v[214:215] op_sel_hi:[1,0]
	v_pk_fma_f32 v[70:71], v[70:71], v[98:99], v[216:217]
	v_pk_fma_f32 v[54:55], v[54:55], v[98:99], v[242:243]
	v_pk_fma_f32 v[42:43], v[42:43], v[98:99], v[244:245]
	v_pk_fma_f32 v[26:27], v[26:27], v[98:99], v[172:173]
	v_pk_mul_f32 v[204:205], v[174:175], v[202:203] op_sel_hi:[1,0]
	v_pk_mul_f32 v[208:209], v[174:175], v[206:207] op_sel_hi:[1,0]
	v_pk_mul_f32 v[212:213], v[174:175], v[210:211] op_sel_hi:[1,0]
	v_pk_mul_f32 v[174:175], v[174:175], v[214:215] op_sel_hi:[1,0]
	v_pk_fma_f32 v[64:65], v[64:65], v[100:101], v[204:205]
	v_pk_fma_f32 v[44:45], v[44:45], v[100:101], v[208:209]
	v_pk_fma_f32 v[28:29], v[28:29], v[100:101], v[212:213]
	v_pk_fma_f32 v[16:17], v[16:17], v[100:101], v[174:175]
	v_pk_mul_f32 v[216:217], v[176:177], v[202:203] op_sel_hi:[1,0]
	v_pk_mul_f32 v[242:243], v[176:177], v[206:207] op_sel_hi:[1,0]
	v_pk_mul_f32 v[244:245], v[176:177], v[210:211] op_sel_hi:[1,0]
	v_pk_mul_f32 v[176:177], v[176:177], v[214:215] op_sel_hi:[1,0]
	v_pk_fma_f32 v[66:67], v[66:67], v[102:103], v[216:217]
	v_pk_fma_f32 v[46:47], v[46:47], v[102:103], v[242:243]
	v_pk_fma_f32 v[30:31], v[30:31], v[102:103], v[244:245]
	v_pk_fma_f32 v[18:19], v[18:19], v[102:103], v[176:177]
	v_pk_mul_f32 v[204:205], v[178:179], v[202:203] op_sel_hi:[1,0]
	v_pk_mul_f32 v[208:209], v[178:179], v[206:207] op_sel_hi:[1,0]
	v_pk_mul_f32 v[212:213], v[178:179], v[210:211] op_sel_hi:[1,0]
	v_pk_mul_f32 v[178:179], v[178:179], v[214:215] op_sel_hi:[1,0]
	v_pk_fma_f32 v[56:57], v[56:57], v[104:105], v[204:205]
	v_pk_fma_f32 v[36:37], v[36:37], v[104:105], v[208:209]
	v_pk_fma_f32 v[20:21], v[20:21], v[104:105], v[212:213]
	v_pk_fma_f32 v[12:13], v[12:13], v[104:105], v[178:179]
	v_pk_mul_f32 v[216:217], v[180:181], v[202:203] op_sel_hi:[1,0]
	v_pk_mul_f32 v[242:243], v[180:181], v[206:207] op_sel_hi:[1,0]
	v_pk_mul_f32 v[244:245], v[180:181], v[210:211] op_sel_hi:[1,0]
	v_pk_mul_f32 v[180:181], v[180:181], v[214:215] op_sel_hi:[1,0]
	v_pk_fma_f32 v[58:59], v[58:59], v[106:107], v[216:217]
	v_pk_fma_f32 v[38:39], v[38:39], v[106:107], v[242:243]
	v_pk_fma_f32 v[22:23], v[22:23], v[106:107], v[244:245]
	v_pk_fma_f32 v[14:15], v[14:15], v[106:107], v[180:181]
	ds_read_b128 v[92:95], v218 offset:1024
	ds_read_b128 v[96:99], v218 offset:1040
	ds_read_b128 v[100:103], v218 offset:1056
	ds_read_b128 v[104:107], v218 offset:1072
	ds_read_b128 v[76:79], v219 offset:0
	ds_read_b128 v[80:83], v219 offset:16
	ds_read_b128 v[84:87], v219 offset:32
	ds_read_b128 v[88:91], v219 offset:48
	s_waitcnt lgkmcnt(8)
	v_pk_fma_f32 v[72:73], v[198:199], v[182:183], v[72:73] op_sel_hi:[0,1,1]
	v_pk_fma_f32 v[60:61], v[198:199], v[182:183], v[60:61] op_sel:[1,0,0]
	v_pk_fma_f32 v[48:49], v[200:201], v[182:183], v[48:49] op_sel_hi:[0,1,1]
	v_pk_fma_f32 v[32:33], v[200:201], v[182:183], v[32:33] op_sel:[1,0,0]
	v_pk_fma_f32 v[74:75], v[198:199], v[184:185], v[74:75] op_sel_hi:[0,1,1]
	v_pk_fma_f32 v[62:63], v[198:199], v[184:185], v[62:63] op_sel:[1,0,0]
	v_pk_fma_f32 v[50:51], v[200:201], v[184:185], v[50:51] op_sel_hi:[0,1,1]
	v_pk_fma_f32 v[34:35], v[200:201], v[184:185], v[34:35] op_sel:[1,0,0]
	v_pk_fma_f32 v[68:69], v[198:199], v[186:187], v[68:69] op_sel_hi:[0,1,1]
	v_pk_fma_f32 v[52:53], v[198:199], v[186:187], v[52:53] op_sel:[1,0,0]
	v_pk_fma_f32 v[40:41], v[200:201], v[186:187], v[40:41] op_sel_hi:[0,1,1]
	v_pk_fma_f32 v[24:25], v[200:201], v[186:187], v[24:25] op_sel:[1,0,0]
	v_pk_fma_f32 v[70:71], v[198:199], v[188:189], v[70:71] op_sel_hi:[0,1,1]
	v_pk_fma_f32 v[54:55], v[198:199], v[188:189], v[54:55] op_sel:[1,0,0]
	v_pk_fma_f32 v[42:43], v[200:201], v[188:189], v[42:43] op_sel_hi:[0,1,1]
	v_pk_fma_f32 v[26:27], v[200:201], v[188:189], v[26:27] op_sel:[1,0,0]
	v_pk_fma_f32 v[64:65], v[198:199], v[190:191], v[64:65] op_sel_hi:[0,1,1]
	v_pk_fma_f32 v[44:45], v[198:199], v[190:191], v[44:45] op_sel:[1,0,0]
	v_pk_fma_f32 v[28:29], v[200:201], v[190:191], v[28:29] op_sel_hi:[0,1,1]
	v_pk_fma_f32 v[16:17], v[200:201], v[190:191], v[16:17] op_sel:[1,0,0]
	v_pk_fma_f32 v[66:67], v[198:199], v[192:193], v[66:67] op_sel_hi:[0,1,1]
	v_pk_fma_f32 v[46:47], v[198:199], v[192:193], v[46:47] op_sel:[1,0,0]
	v_pk_fma_f32 v[30:31], v[200:201], v[192:193], v[30:31] op_sel_hi:[0,1,1]
	v_pk_fma_f32 v[18:19], v[200:201], v[192:193], v[18:19] op_sel:[1,0,0]
	v_pk_fma_f32 v[56:57], v[198:199], v[194:195], v[56:57] op_sel_hi:[0,1,1]
	v_pk_fma_f32 v[36:37], v[198:199], v[194:195], v[36:37] op_sel:[1,0,0]
	v_pk_fma_f32 v[20:21], v[200:201], v[194:195], v[20:21] op_sel_hi:[0,1,1]
	v_pk_fma_f32 v[12:13], v[200:201], v[194:195], v[12:13] op_sel:[1,0,0]
	v_pk_fma_f32 v[58:59], v[198:199], v[196:197], v[58:59] op_sel_hi:[0,1,1]
	v_pk_fma_f32 v[38:39], v[198:199], v[196:197], v[38:39] op_sel:[1,0,0]
	v_pk_fma_f32 v[22:23], v[200:201], v[196:197], v[22:23] op_sel_hi:[0,1,1]
	v_pk_fma_f32 v[14:15], v[200:201], v[196:197], v[14:15] op_sel:[1,0,0]
	s_waitcnt lgkmcnt(4)
	v_pk_mul_f32 v[202:203], v[72:73], v[92:93]
	v_pk_mul_f32 v[204:205], v[74:75], v[94:95]
	v_pk_mul_f32 v[206:207], v[60:61], v[92:93]
	v_pk_mul_f32 v[208:209], v[62:63], v[94:95]
	v_pk_mul_f32 v[210:211], v[48:49], v[92:93]
	v_pk_mul_f32 v[212:213], v[50:51], v[94:95]
	v_pk_mul_f32 v[214:215], v[32:33], v[92:93]
	v_pk_mul_f32 v[216:217], v[34:35], v[94:95]
	v_pk_fma_f32 v[202:203], v[68:69], v[96:97], v[202:203]
	v_pk_fma_f32 v[204:205], v[70:71], v[98:99], v[204:205]
	v_pk_fma_f32 v[206:207], v[52:53], v[96:97], v[206:207]
	v_pk_fma_f32 v[208:209], v[54:55], v[98:99], v[208:209]
	v_pk_fma_f32 v[210:211], v[40:41], v[96:97], v[210:211]
	v_pk_fma_f32 v[212:213], v[42:43], v[98:99], v[212:213]
	v_pk_fma_f32 v[214:215], v[24:25], v[96:97], v[214:215]
	v_pk_fma_f32 v[216:217], v[26:27], v[98:99], v[216:217]
	v_pk_fma_f32 v[202:203], v[64:65], v[100:101], v[202:203]
	v_pk_fma_f32 v[204:205], v[66:67], v[102:103], v[204:205]
	v_pk_fma_f32 v[206:207], v[44:45], v[100:101], v[206:207]
	v_pk_fma_f32 v[208:209], v[46:47], v[102:103], v[208:209]
	v_pk_fma_f32 v[210:211], v[28:29], v[100:101], v[210:211]
	v_pk_fma_f32 v[212:213], v[30:31], v[102:103], v[212:213]
	v_pk_fma_f32 v[214:215], v[16:17], v[100:101], v[214:215]
	v_pk_fma_f32 v[216:217], v[18:19], v[102:103], v[216:217]
	v_pk_fma_f32 v[202:203], v[56:57], v[104:105], v[202:203]
	v_pk_fma_f32 v[204:205], v[58:59], v[106:107], v[204:205]
	v_pk_fma_f32 v[206:207], v[36:37], v[104:105], v[206:207]
	v_pk_fma_f32 v[208:209], v[38:39], v[106:107], v[208:209]
	v_pk_fma_f32 v[210:211], v[20:21], v[104:105], v[210:211]
	v_pk_fma_f32 v[212:213], v[22:23], v[106:107], v[212:213]
	v_pk_fma_f32 v[214:215], v[12:13], v[104:105], v[214:215]
	v_pk_fma_f32 v[216:217], v[14:15], v[106:107], v[216:217]
	v_pk_add_f32 v[202:203], v[202:203], v[204:205]
	v_pk_add_f32 v[206:207], v[206:207], v[208:209]
	v_pk_add_f32 v[210:211], v[210:211], v[212:213]
	v_pk_add_f32 v[214:215], v[214:215], v[216:217]
	ds_read_b128 v[92:95], v219 offset:256
	v_add_f32_e32 v202, v202, v203
	v_add_f32_e32 v206, v206, v207
	v_add_f32_e32 v210, v210, v211
	v_add_f32_e32 v214, v214, v215
	ds_read_b128 v[96:99], v219 offset:272
	v_add_f32_dpp v202, v202, v202 quad_perm:[1,0,3,2] row_mask:0xf bank_mask:0xf bound_ctrl:1
	v_add_f32_dpp v206, v206, v206 quad_perm:[1,0,3,2] row_mask:0xf bank_mask:0xf bound_ctrl:1
	v_add_f32_dpp v210, v210, v210 quad_perm:[1,0,3,2] row_mask:0xf bank_mask:0xf bound_ctrl:1
	v_add_f32_dpp v214, v214, v214 quad_perm:[1,0,3,2] row_mask:0xf bank_mask:0xf bound_ctrl:1
	ds_read_b128 v[100:103], v219 offset:288
	v_add_f32_dpp v202, v202, v202 quad_perm:[2,3,0,1] row_mask:0xf bank_mask:0xf bound_ctrl:1
	v_add_f32_dpp v206, v206, v206 quad_perm:[2,3,0,1] row_mask:0xf bank_mask:0xf bound_ctrl:1
	v_add_f32_dpp v210, v210, v210 quad_perm:[2,3,0,1] row_mask:0xf bank_mask:0xf bound_ctrl:1
	v_add_f32_dpp v214, v214, v214 quad_perm:[2,3,0,1] row_mask:0xf bank_mask:0xf bound_ctrl:1
	ds_read_b128 v[104:107], v219 offset:304
	ds_read_b128 v[108:111], v219 offset:512
	v_cvt_pk_bf16_f32 v240, v202, v206
	v_cvt_pk_bf16_f32 v241, v210, v214
	ds_read_b128 v[170:173], v219 offset:528
	ds_read_b128 v[174:177], v219 offset:544
	s_mov_b64 exec, s[6:7]
	global_store_dwordx2 v[238:239], v[240:241], off
	s_mov_b64 exec, -1
	ds_read_b128 v[178:181], v219 offset:560
	ds_read_b128 v[198:201], v223 offset:1280
	v_lshl_add_u64 v[238:239], v[238:239], 0, s[80:81]
	s_waitcnt lgkmcnt(9)
	ds_read_b128 v[182:185], v219 offset:768
	ds_read_b128 v[186:189], v219 offset:784
	ds_read_b128 v[190:193], v219 offset:800
	ds_read_b128 v[194:197], v219 offset:816
	v_pk_mul_f32 v[202:203], v[72:73], v[76:77]
	v_pk_mul_f32 v[204:205], v[74:75], v[78:79]
	v_pk_mul_f32 v[206:207], v[60:61], v[76:77]
	v_pk_mul_f32 v[208:209], v[62:63], v[78:79]
	v_pk_mul_f32 v[210:211], v[48:49], v[76:77]
	v_pk_mul_f32 v[212:213], v[50:51], v[78:79]
	v_pk_mul_f32 v[214:215], v[32:33], v[76:77]
	v_pk_mul_f32 v[216:217], v[34:35], v[78:79]
	v_pk_fma_f32 v[202:203], v[68:69], v[80:81], v[202:203]
	v_pk_fma_f32 v[204:205], v[70:71], v[82:83], v[204:205]
	v_pk_fma_f32 v[206:207], v[52:53], v[80:81], v[206:207]
	v_pk_fma_f32 v[208:209], v[54:55], v[82:83], v[208:209]
	v_pk_fma_f32 v[210:211], v[40:41], v[80:81], v[210:211]
	v_pk_fma_f32 v[212:213], v[42:43], v[82:83], v[212:213]
	v_pk_fma_f32 v[214:215], v[24:25], v[80:81], v[214:215]
	v_pk_fma_f32 v[216:217], v[26:27], v[82:83], v[216:217]
	v_pk_fma_f32 v[202:203], v[64:65], v[84:85], v[202:203]
	v_pk_fma_f32 v[204:205], v[66:67], v[86:87], v[204:205]
	v_pk_fma_f32 v[206:207], v[44:45], v[84:85], v[206:207]
	v_pk_fma_f32 v[208:209], v[46:47], v[86:87], v[208:209]
	v_pk_fma_f32 v[210:211], v[28:29], v[84:85], v[210:211]
	v_pk_fma_f32 v[212:213], v[30:31], v[86:87], v[212:213]
	v_pk_fma_f32 v[214:215], v[16:17], v[84:85], v[214:215]
	v_pk_fma_f32 v[216:217], v[18:19], v[86:87], v[216:217]
	v_pk_fma_f32 v[202:203], v[56:57], v[88:89], v[202:203]
	v_pk_fma_f32 v[204:205], v[58:59], v[90:91], v[204:205]
	v_pk_fma_f32 v[206:207], v[36:37], v[88:89], v[206:207]
	v_pk_fma_f32 v[208:209], v[38:39], v[90:91], v[208:209]
	v_pk_fma_f32 v[210:211], v[20:21], v[88:89], v[210:211]
	v_pk_fma_f32 v[212:213], v[22:23], v[90:91], v[212:213]
	v_pk_fma_f32 v[214:215], v[12:13], v[88:89], v[214:215]
	v_pk_fma_f32 v[216:217], v[14:15], v[90:91], v[216:217]
	s_waitcnt lgkmcnt(5)
	v_pk_add_f32 v[202:203], v[202:203], v[204:205]
	v_pk_add_f32 v[206:207], v[206:207], v[208:209]
	v_pk_add_f32 v[210:211], v[210:211], v[212:213]
	v_pk_add_f32 v[214:215], v[214:215], v[216:217]
	v_add_f32_e32 v202, v202, v203
	v_add_f32_e32 v206, v206, v207
	v_add_f32_e32 v210, v210, v211
	v_add_f32_e32 v214, v214, v215
	v_add_f32_dpp v202, v202, v202 quad_perm:[1,0,3,2] row_mask:0xf bank_mask:0xf bound_ctrl:1
	v_add_f32_dpp v206, v206, v206 quad_perm:[1,0,3,2] row_mask:0xf bank_mask:0xf bound_ctrl:1
	v_add_f32_dpp v210, v210, v210 quad_perm:[1,0,3,2] row_mask:0xf bank_mask:0xf bound_ctrl:1
	v_add_f32_dpp v214, v214, v214 quad_perm:[1,0,3,2] row_mask:0xf bank_mask:0xf bound_ctrl:1
	v_add_f32_dpp v202, v202, v202 quad_perm:[2,3,0,1] row_mask:0xf bank_mask:0xf bound_ctrl:1
	v_add_f32_dpp v206, v206, v206 quad_perm:[2,3,0,1] row_mask:0xf bank_mask:0xf bound_ctrl:1
	v_add_f32_dpp v210, v210, v210 quad_perm:[2,3,0,1] row_mask:0xf bank_mask:0xf bound_ctrl:1
	v_add_f32_dpp v214, v214, v214 quad_perm:[2,3,0,1] row_mask:0xf bank_mask:0xf bound_ctrl:1
	v_pk_mul_f32 v[204:205], v[108:109], v[202:203] op_sel_hi:[1,0]
	v_pk_mul_f32 v[208:209], v[108:109], v[206:207] op_sel_hi:[1,0]
	v_pk_mul_f32 v[212:213], v[108:109], v[210:211] op_sel_hi:[1,0]
	v_pk_mul_f32 v[108:109], v[108:109], v[214:215] op_sel_hi:[1,0]
	v_pk_fma_f32 v[72:73], v[72:73], v[92:93], v[204:205]
	v_pk_fma_f32 v[60:61], v[60:61], v[92:93], v[208:209]
	v_pk_fma_f32 v[48:49], v[48:49], v[92:93], v[212:213]
	v_pk_fma_f32 v[32:33], v[32:33], v[92:93], v[108:109]
	v_pk_mul_f32 v[216:217], v[110:111], v[202:203] op_sel_hi:[1,0]
	v_pk_mul_f32 v[242:243], v[110:111], v[206:207] op_sel_hi:[1,0]
	v_pk_mul_f32 v[244:245], v[110:111], v[210:211] op_sel_hi:[1,0]
	v_pk_mul_f32 v[110:111], v[110:111], v[214:215] op_sel_hi:[1,0]
	v_pk_fma_f32 v[74:75], v[74:75], v[94:95], v[216:217]
	v_pk_fma_f32 v[62:63], v[62:63], v[94:95], v[242:243]
	v_pk_fma_f32 v[50:51], v[50:51], v[94:95], v[244:245]
	v_pk_fma_f32 v[34:35], v[34:35], v[94:95], v[110:111]
	v_pk_mul_f32 v[204:205], v[170:171], v[202:203] op_sel_hi:[1,0]
	v_pk_mul_f32 v[208:209], v[170:171], v[206:207] op_sel_hi:[1,0]
	v_pk_mul_f32 v[212:213], v[170:171], v[210:211] op_sel_hi:[1,0]
	v_pk_mul_f32 v[170:171], v[170:171], v[214:215] op_sel_hi:[1,0]
	v_pk_fma_f32 v[68:69], v[68:69], v[96:97], v[204:205]
	v_pk_fma_f32 v[52:53], v[52:53], v[96:97], v[208:209]
	v_pk_fma_f32 v[40:41], v[40:41], v[96:97], v[212:213]
	v_pk_fma_f32 v[24:25], v[24:25], v[96:97], v[170:171]
	v_pk_mul_f32 v[216:217], v[172:173], v[202:203] op_sel_hi:[1,0]
	v_pk_mul_f32 v[242:243], v[172:173], v[206:207] op_sel_hi:[1,0]
	v_pk_mul_f32 v[244:245], v[172:173], v[210:211] op_sel_hi:[1,0]
	v_pk_mul_f32 v[172:173], v[172:173], v[214:215] op_sel_hi:[1,0]
	v_pk_fma_f32 v[70:71], v[70:71], v[98:99], v[216:217]
	v_pk_fma_f32 v[54:55], v[54:55], v[98:99], v[242:243]
	v_pk_fma_f32 v[42:43], v[42:43], v[98:99], v[244:245]
	v_pk_fma_f32 v[26:27], v[26:27], v[98:99], v[172:173]
	v_pk_mul_f32 v[204:205], v[174:175], v[202:203] op_sel_hi:[1,0]
	v_pk_mul_f32 v[208:209], v[174:175], v[206:207] op_sel_hi:[1,0]
	v_pk_mul_f32 v[212:213], v[174:175], v[210:211] op_sel_hi:[1,0]
	v_pk_mul_f32 v[174:175], v[174:175], v[214:215] op_sel_hi:[1,0]
	v_pk_fma_f32 v[64:65], v[64:65], v[100:101], v[204:205]
	v_pk_fma_f32 v[44:45], v[44:45], v[100:101], v[208:209]
	v_pk_fma_f32 v[28:29], v[28:29], v[100:101], v[212:213]
	v_pk_fma_f32 v[16:17], v[16:17], v[100:101], v[174:175]
	v_pk_mul_f32 v[216:217], v[176:177], v[202:203] op_sel_hi:[1,0]
	v_pk_mul_f32 v[242:243], v[176:177], v[206:207] op_sel_hi:[1,0]
	v_pk_mul_f32 v[244:245], v[176:177], v[210:211] op_sel_hi:[1,0]
	v_pk_mul_f32 v[176:177], v[176:177], v[214:215] op_sel_hi:[1,0]
	v_pk_fma_f32 v[66:67], v[66:67], v[102:103], v[216:217]
	v_pk_fma_f32 v[46:47], v[46:47], v[102:103], v[242:243]
	v_pk_fma_f32 v[30:31], v[30:31], v[102:103], v[244:245]
	v_pk_fma_f32 v[18:19], v[18:19], v[102:103], v[176:177]
	v_pk_mul_f32 v[204:205], v[178:179], v[202:203] op_sel_hi:[1,0]
	v_pk_mul_f32 v[208:209], v[178:179], v[206:207] op_sel_hi:[1,0]
	v_pk_mul_f32 v[212:213], v[178:179], v[210:211] op_sel_hi:[1,0]
	v_pk_mul_f32 v[178:179], v[178:179], v[214:215] op_sel_hi:[1,0]
	v_pk_fma_f32 v[56:57], v[56:57], v[104:105], v[204:205]
	v_pk_fma_f32 v[36:37], v[36:37], v[104:105], v[208:209]
	v_pk_fma_f32 v[20:21], v[20:21], v[104:105], v[212:213]
	v_pk_fma_f32 v[12:13], v[12:13], v[104:105], v[178:179]
	v_pk_mul_f32 v[216:217], v[180:181], v[202:203] op_sel_hi:[1,0]
	v_pk_mul_f32 v[242:243], v[180:181], v[206:207] op_sel_hi:[1,0]
	v_pk_mul_f32 v[244:245], v[180:181], v[210:211] op_sel_hi:[1,0]
	v_pk_mul_f32 v[180:181], v[180:181], v[214:215] op_sel_hi:[1,0]
	v_pk_fma_f32 v[58:59], v[58:59], v[106:107], v[216:217]
	v_pk_fma_f32 v[38:39], v[38:39], v[106:107], v[242:243]
	v_pk_fma_f32 v[22:23], v[22:23], v[106:107], v[244:245]
	v_pk_fma_f32 v[14:15], v[14:15], v[106:107], v[180:181]
	ds_read_b128 v[92:95], v219 offset:1024
	ds_read_b128 v[96:99], v219 offset:1040
	ds_read_b128 v[100:103], v219 offset:1056
	ds_read_b128 v[104:107], v219 offset:1072
	ds_read_b128 v[76:79], v220 offset:0
	ds_read_b128 v[80:83], v220 offset:16
	ds_read_b128 v[84:87], v220 offset:32
	ds_read_b128 v[88:91], v220 offset:48
	s_waitcnt lgkmcnt(8)
	v_pk_fma_f32 v[72:73], v[198:199], v[182:183], v[72:73] op_sel_hi:[0,1,1]
	v_pk_fma_f32 v[60:61], v[198:199], v[182:183], v[60:61] op_sel:[1,0,0]
	v_pk_fma_f32 v[48:49], v[200:201], v[182:183], v[48:49] op_sel_hi:[0,1,1]
	v_pk_fma_f32 v[32:33], v[200:201], v[182:183], v[32:33] op_sel:[1,0,0]
	v_pk_fma_f32 v[74:75], v[198:199], v[184:185], v[74:75] op_sel_hi:[0,1,1]
	v_pk_fma_f32 v[62:63], v[198:199], v[184:185], v[62:63] op_sel:[1,0,0]
	v_pk_fma_f32 v[50:51], v[200:201], v[184:185], v[50:51] op_sel_hi:[0,1,1]
	v_pk_fma_f32 v[34:35], v[200:201], v[184:185], v[34:35] op_sel:[1,0,0]
	v_pk_fma_f32 v[68:69], v[198:199], v[186:187], v[68:69] op_sel_hi:[0,1,1]
	v_pk_fma_f32 v[52:53], v[198:199], v[186:187], v[52:53] op_sel:[1,0,0]
	v_pk_fma_f32 v[40:41], v[200:201], v[186:187], v[40:41] op_sel_hi:[0,1,1]
	v_pk_fma_f32 v[24:25], v[200:201], v[186:187], v[24:25] op_sel:[1,0,0]
	v_pk_fma_f32 v[70:71], v[198:199], v[188:189], v[70:71] op_sel_hi:[0,1,1]
	v_pk_fma_f32 v[54:55], v[198:199], v[188:189], v[54:55] op_sel:[1,0,0]
	v_pk_fma_f32 v[42:43], v[200:201], v[188:189], v[42:43] op_sel_hi:[0,1,1]
	v_pk_fma_f32 v[26:27], v[200:201], v[188:189], v[26:27] op_sel:[1,0,0]
	v_pk_fma_f32 v[64:65], v[198:199], v[190:191], v[64:65] op_sel_hi:[0,1,1]
	v_pk_fma_f32 v[44:45], v[198:199], v[190:191], v[44:45] op_sel:[1,0,0]
	v_pk_fma_f32 v[28:29], v[200:201], v[190:191], v[28:29] op_sel_hi:[0,1,1]
	v_pk_fma_f32 v[16:17], v[200:201], v[190:191], v[16:17] op_sel:[1,0,0]
	v_pk_fma_f32 v[66:67], v[198:199], v[192:193], v[66:67] op_sel_hi:[0,1,1]
	v_pk_fma_f32 v[46:47], v[198:199], v[192:193], v[46:47] op_sel:[1,0,0]
	v_pk_fma_f32 v[30:31], v[200:201], v[192:193], v[30:31] op_sel_hi:[0,1,1]
	v_pk_fma_f32 v[18:19], v[200:201], v[192:193], v[18:19] op_sel:[1,0,0]
	v_pk_fma_f32 v[56:57], v[198:199], v[194:195], v[56:57] op_sel_hi:[0,1,1]
	v_pk_fma_f32 v[36:37], v[198:199], v[194:195], v[36:37] op_sel:[1,0,0]
	v_pk_fma_f32 v[20:21], v[200:201], v[194:195], v[20:21] op_sel_hi:[0,1,1]
	v_pk_fma_f32 v[12:13], v[200:201], v[194:195], v[12:13] op_sel:[1,0,0]
	v_pk_fma_f32 v[58:59], v[198:199], v[196:197], v[58:59] op_sel_hi:[0,1,1]
	v_pk_fma_f32 v[38:39], v[198:199], v[196:197], v[38:39] op_sel:[1,0,0]
	v_pk_fma_f32 v[22:23], v[200:201], v[196:197], v[22:23] op_sel_hi:[0,1,1]
	v_pk_fma_f32 v[14:15], v[200:201], v[196:197], v[14:15] op_sel:[1,0,0]
	s_waitcnt lgkmcnt(4)
	v_pk_mul_f32 v[202:203], v[72:73], v[92:93]
	v_pk_mul_f32 v[204:205], v[74:75], v[94:95]
	v_pk_mul_f32 v[206:207], v[60:61], v[92:93]
	v_pk_mul_f32 v[208:209], v[62:63], v[94:95]
	v_pk_mul_f32 v[210:211], v[48:49], v[92:93]
	v_pk_mul_f32 v[212:213], v[50:51], v[94:95]
	v_pk_mul_f32 v[214:215], v[32:33], v[92:93]
	v_pk_mul_f32 v[216:217], v[34:35], v[94:95]
	v_pk_fma_f32 v[202:203], v[68:69], v[96:97], v[202:203]
	v_pk_fma_f32 v[204:205], v[70:71], v[98:99], v[204:205]
	v_pk_fma_f32 v[206:207], v[52:53], v[96:97], v[206:207]
	v_pk_fma_f32 v[208:209], v[54:55], v[98:99], v[208:209]
	v_pk_fma_f32 v[210:211], v[40:41], v[96:97], v[210:211]
	v_pk_fma_f32 v[212:213], v[42:43], v[98:99], v[212:213]
	v_pk_fma_f32 v[214:215], v[24:25], v[96:97], v[214:215]
	v_pk_fma_f32 v[216:217], v[26:27], v[98:99], v[216:217]
	v_pk_fma_f32 v[202:203], v[64:65], v[100:101], v[202:203]
	v_pk_fma_f32 v[204:205], v[66:67], v[102:103], v[204:205]
	v_pk_fma_f32 v[206:207], v[44:45], v[100:101], v[206:207]
	v_pk_fma_f32 v[208:209], v[46:47], v[102:103], v[208:209]
	v_pk_fma_f32 v[210:211], v[28:29], v[100:101], v[210:211]
	v_pk_fma_f32 v[212:213], v[30:31], v[102:103], v[212:213]
	v_pk_fma_f32 v[214:215], v[16:17], v[100:101], v[214:215]
	v_pk_fma_f32 v[216:217], v[18:19], v[102:103], v[216:217]
	v_pk_fma_f32 v[202:203], v[56:57], v[104:105], v[202:203]
	v_pk_fma_f32 v[204:205], v[58:59], v[106:107], v[204:205]
	v_pk_fma_f32 v[206:207], v[36:37], v[104:105], v[206:207]
	v_pk_fma_f32 v[208:209], v[38:39], v[106:107], v[208:209]
	v_pk_fma_f32 v[210:211], v[20:21], v[104:105], v[210:211]
	v_pk_fma_f32 v[212:213], v[22:23], v[106:107], v[212:213]
	v_pk_fma_f32 v[214:215], v[12:13], v[104:105], v[214:215]
	v_pk_fma_f32 v[216:217], v[14:15], v[106:107], v[216:217]
	v_pk_add_f32 v[202:203], v[202:203], v[204:205]
	v_pk_add_f32 v[206:207], v[206:207], v[208:209]
	v_pk_add_f32 v[210:211], v[210:211], v[212:213]
	v_pk_add_f32 v[214:215], v[214:215], v[216:217]
	ds_read_b128 v[92:95], v220 offset:256
	v_add_f32_e32 v202, v202, v203
	v_add_f32_e32 v206, v206, v207
	v_add_f32_e32 v210, v210, v211
	v_add_f32_e32 v214, v214, v215
	ds_read_b128 v[96:99], v220 offset:272
	v_add_f32_dpp v202, v202, v202 quad_perm:[1,0,3,2] row_mask:0xf bank_mask:0xf bound_ctrl:1
	v_add_f32_dpp v206, v206, v206 quad_perm:[1,0,3,2] row_mask:0xf bank_mask:0xf bound_ctrl:1
	v_add_f32_dpp v210, v210, v210 quad_perm:[1,0,3,2] row_mask:0xf bank_mask:0xf bound_ctrl:1
	v_add_f32_dpp v214, v214, v214 quad_perm:[1,0,3,2] row_mask:0xf bank_mask:0xf bound_ctrl:1
	ds_read_b128 v[100:103], v220 offset:288
	v_add_f32_dpp v202, v202, v202 quad_perm:[2,3,0,1] row_mask:0xf bank_mask:0xf bound_ctrl:1
	v_add_f32_dpp v206, v206, v206 quad_perm:[2,3,0,1] row_mask:0xf bank_mask:0xf bound_ctrl:1
	v_add_f32_dpp v210, v210, v210 quad_perm:[2,3,0,1] row_mask:0xf bank_mask:0xf bound_ctrl:1
	v_add_f32_dpp v214, v214, v214 quad_perm:[2,3,0,1] row_mask:0xf bank_mask:0xf bound_ctrl:1
	ds_read_b128 v[104:107], v220 offset:304
	ds_read_b128 v[108:111], v220 offset:512
	v_cvt_pk_bf16_f32 v240, v202, v206
	v_cvt_pk_bf16_f32 v241, v210, v214
	ds_read_b128 v[170:173], v220 offset:528
	ds_read_b128 v[174:177], v220 offset:544
	s_mov_b64 exec, s[6:7]
	global_store_dwordx2 v[238:239], v[240:241], off
	s_mov_b64 exec, -1
	ds_read_b128 v[178:181], v220 offset:560
	ds_read_b128 v[198:201], v236 offset:1280
	v_lshl_add_u64 v[238:239], v[238:239], 0, s[80:81]
	s_waitcnt lgkmcnt(9)
	ds_read_b128 v[182:185], v220 offset:768
	ds_read_b128 v[186:189], v220 offset:784
	ds_read_b128 v[190:193], v220 offset:800
	ds_read_b128 v[194:197], v220 offset:816
	v_pk_mul_f32 v[202:203], v[72:73], v[76:77]
	v_pk_mul_f32 v[204:205], v[74:75], v[78:79]
	v_pk_mul_f32 v[206:207], v[60:61], v[76:77]
	v_pk_mul_f32 v[208:209], v[62:63], v[78:79]
	v_pk_mul_f32 v[210:211], v[48:49], v[76:77]
	v_pk_mul_f32 v[212:213], v[50:51], v[78:79]
	v_pk_mul_f32 v[214:215], v[32:33], v[76:77]
	v_pk_mul_f32 v[216:217], v[34:35], v[78:79]
	v_pk_fma_f32 v[202:203], v[68:69], v[80:81], v[202:203]
	v_pk_fma_f32 v[204:205], v[70:71], v[82:83], v[204:205]
	v_pk_fma_f32 v[206:207], v[52:53], v[80:81], v[206:207]
	v_pk_fma_f32 v[208:209], v[54:55], v[82:83], v[208:209]
	v_pk_fma_f32 v[210:211], v[40:41], v[80:81], v[210:211]
	v_pk_fma_f32 v[212:213], v[42:43], v[82:83], v[212:213]
	v_pk_fma_f32 v[214:215], v[24:25], v[80:81], v[214:215]
	v_pk_fma_f32 v[216:217], v[26:27], v[82:83], v[216:217]
	v_pk_fma_f32 v[202:203], v[64:65], v[84:85], v[202:203]
	v_pk_fma_f32 v[204:205], v[66:67], v[86:87], v[204:205]
	v_pk_fma_f32 v[206:207], v[44:45], v[84:85], v[206:207]
	v_pk_fma_f32 v[208:209], v[46:47], v[86:87], v[208:209]
	v_pk_fma_f32 v[210:211], v[28:29], v[84:85], v[210:211]
	v_pk_fma_f32 v[212:213], v[30:31], v[86:87], v[212:213]
	v_pk_fma_f32 v[214:215], v[16:17], v[84:85], v[214:215]
	v_pk_fma_f32 v[216:217], v[18:19], v[86:87], v[216:217]
	v_pk_fma_f32 v[202:203], v[56:57], v[88:89], v[202:203]
	v_pk_fma_f32 v[204:205], v[58:59], v[90:91], v[204:205]
	v_pk_fma_f32 v[206:207], v[36:37], v[88:89], v[206:207]
	v_pk_fma_f32 v[208:209], v[38:39], v[90:91], v[208:209]
	v_pk_fma_f32 v[210:211], v[20:21], v[88:89], v[210:211]
	v_pk_fma_f32 v[212:213], v[22:23], v[90:91], v[212:213]
	v_pk_fma_f32 v[214:215], v[12:13], v[88:89], v[214:215]
	v_pk_fma_f32 v[216:217], v[14:15], v[90:91], v[216:217]
	s_waitcnt lgkmcnt(5)
	v_pk_add_f32 v[202:203], v[202:203], v[204:205]
	v_pk_add_f32 v[206:207], v[206:207], v[208:209]
	v_pk_add_f32 v[210:211], v[210:211], v[212:213]
	v_pk_add_f32 v[214:215], v[214:215], v[216:217]
	v_add_f32_e32 v202, v202, v203
	v_add_f32_e32 v206, v206, v207
	v_add_f32_e32 v210, v210, v211
	v_add_f32_e32 v214, v214, v215
	v_add_f32_dpp v202, v202, v202 quad_perm:[1,0,3,2] row_mask:0xf bank_mask:0xf bound_ctrl:1
	v_add_f32_dpp v206, v206, v206 quad_perm:[1,0,3,2] row_mask:0xf bank_mask:0xf bound_ctrl:1
	v_add_f32_dpp v210, v210, v210 quad_perm:[1,0,3,2] row_mask:0xf bank_mask:0xf bound_ctrl:1
	v_add_f32_dpp v214, v214, v214 quad_perm:[1,0,3,2] row_mask:0xf bank_mask:0xf bound_ctrl:1
	v_add_f32_dpp v202, v202, v202 quad_perm:[2,3,0,1] row_mask:0xf bank_mask:0xf bound_ctrl:1
	v_add_f32_dpp v206, v206, v206 quad_perm:[2,3,0,1] row_mask:0xf bank_mask:0xf bound_ctrl:1
	v_add_f32_dpp v210, v210, v210 quad_perm:[2,3,0,1] row_mask:0xf bank_mask:0xf bound_ctrl:1
	v_add_f32_dpp v214, v214, v214 quad_perm:[2,3,0,1] row_mask:0xf bank_mask:0xf bound_ctrl:1
	v_pk_mul_f32 v[204:205], v[108:109], v[202:203] op_sel_hi:[1,0]
	v_pk_mul_f32 v[208:209], v[108:109], v[206:207] op_sel_hi:[1,0]
	v_pk_mul_f32 v[212:213], v[108:109], v[210:211] op_sel_hi:[1,0]
	v_pk_mul_f32 v[108:109], v[108:109], v[214:215] op_sel_hi:[1,0]
	v_pk_fma_f32 v[72:73], v[72:73], v[92:93], v[204:205]
	v_pk_fma_f32 v[60:61], v[60:61], v[92:93], v[208:209]
	v_pk_fma_f32 v[48:49], v[48:49], v[92:93], v[212:213]
	v_pk_fma_f32 v[32:33], v[32:33], v[92:93], v[108:109]
	v_pk_mul_f32 v[216:217], v[110:111], v[202:203] op_sel_hi:[1,0]
	v_pk_mul_f32 v[242:243], v[110:111], v[206:207] op_sel_hi:[1,0]
	v_pk_mul_f32 v[244:245], v[110:111], v[210:211] op_sel_hi:[1,0]
	v_pk_mul_f32 v[110:111], v[110:111], v[214:215] op_sel_hi:[1,0]
	v_pk_fma_f32 v[74:75], v[74:75], v[94:95], v[216:217]
	v_pk_fma_f32 v[62:63], v[62:63], v[94:95], v[242:243]
	v_pk_fma_f32 v[50:51], v[50:51], v[94:95], v[244:245]
	v_pk_fma_f32 v[34:35], v[34:35], v[94:95], v[110:111]
	v_pk_mul_f32 v[204:205], v[170:171], v[202:203] op_sel_hi:[1,0]
	v_pk_mul_f32 v[208:209], v[170:171], v[206:207] op_sel_hi:[1,0]
	v_pk_mul_f32 v[212:213], v[170:171], v[210:211] op_sel_hi:[1,0]
	v_pk_mul_f32 v[170:171], v[170:171], v[214:215] op_sel_hi:[1,0]
	v_pk_fma_f32 v[68:69], v[68:69], v[96:97], v[204:205]
	v_pk_fma_f32 v[52:53], v[52:53], v[96:97], v[208:209]
	v_pk_fma_f32 v[40:41], v[40:41], v[96:97], v[212:213]
	v_pk_fma_f32 v[24:25], v[24:25], v[96:97], v[170:171]
	v_pk_mul_f32 v[216:217], v[172:173], v[202:203] op_sel_hi:[1,0]
	v_pk_mul_f32 v[242:243], v[172:173], v[206:207] op_sel_hi:[1,0]
	v_pk_mul_f32 v[244:245], v[172:173], v[210:211] op_sel_hi:[1,0]
	v_pk_mul_f32 v[172:173], v[172:173], v[214:215] op_sel_hi:[1,0]
	v_pk_fma_f32 v[70:71], v[70:71], v[98:99], v[216:217]
	v_pk_fma_f32 v[54:55], v[54:55], v[98:99], v[242:243]
	v_pk_fma_f32 v[42:43], v[42:43], v[98:99], v[244:245]
	v_pk_fma_f32 v[26:27], v[26:27], v[98:99], v[172:173]
	v_pk_mul_f32 v[204:205], v[174:175], v[202:203] op_sel_hi:[1,0]
	v_pk_mul_f32 v[208:209], v[174:175], v[206:207] op_sel_hi:[1,0]
	v_pk_mul_f32 v[212:213], v[174:175], v[210:211] op_sel_hi:[1,0]
	v_pk_mul_f32 v[174:175], v[174:175], v[214:215] op_sel_hi:[1,0]
	v_pk_fma_f32 v[64:65], v[64:65], v[100:101], v[204:205]
	v_pk_fma_f32 v[44:45], v[44:45], v[100:101], v[208:209]
	v_pk_fma_f32 v[28:29], v[28:29], v[100:101], v[212:213]
	v_pk_fma_f32 v[16:17], v[16:17], v[100:101], v[174:175]
	v_pk_mul_f32 v[216:217], v[176:177], v[202:203] op_sel_hi:[1,0]
	v_pk_mul_f32 v[242:243], v[176:177], v[206:207] op_sel_hi:[1,0]
	v_pk_mul_f32 v[244:245], v[176:177], v[210:211] op_sel_hi:[1,0]
	v_pk_mul_f32 v[176:177], v[176:177], v[214:215] op_sel_hi:[1,0]
	v_pk_fma_f32 v[66:67], v[66:67], v[102:103], v[216:217]
	v_pk_fma_f32 v[46:47], v[46:47], v[102:103], v[242:243]
	v_pk_fma_f32 v[30:31], v[30:31], v[102:103], v[244:245]
	v_pk_fma_f32 v[18:19], v[18:19], v[102:103], v[176:177]
	v_pk_mul_f32 v[204:205], v[178:179], v[202:203] op_sel_hi:[1,0]
	v_pk_mul_f32 v[208:209], v[178:179], v[206:207] op_sel_hi:[1,0]
	v_pk_mul_f32 v[212:213], v[178:179], v[210:211] op_sel_hi:[1,0]
	v_pk_mul_f32 v[178:179], v[178:179], v[214:215] op_sel_hi:[1,0]
	v_pk_fma_f32 v[56:57], v[56:57], v[104:105], v[204:205]
	v_pk_fma_f32 v[36:37], v[36:37], v[104:105], v[208:209]
	v_pk_fma_f32 v[20:21], v[20:21], v[104:105], v[212:213]
	v_pk_fma_f32 v[12:13], v[12:13], v[104:105], v[178:179]
	v_pk_mul_f32 v[216:217], v[180:181], v[202:203] op_sel_hi:[1,0]
	v_pk_mul_f32 v[242:243], v[180:181], v[206:207] op_sel_hi:[1,0]
	v_pk_mul_f32 v[244:245], v[180:181], v[210:211] op_sel_hi:[1,0]
	v_pk_mul_f32 v[180:181], v[180:181], v[214:215] op_sel_hi:[1,0]
	v_pk_fma_f32 v[58:59], v[58:59], v[106:107], v[216:217]
	v_pk_fma_f32 v[38:39], v[38:39], v[106:107], v[242:243]
	v_pk_fma_f32 v[22:23], v[22:23], v[106:107], v[244:245]
	v_pk_fma_f32 v[14:15], v[14:15], v[106:107], v[180:181]
	ds_read_b128 v[92:95], v220 offset:1024
	ds_read_b128 v[96:99], v220 offset:1040
	ds_read_b128 v[100:103], v220 offset:1056
	ds_read_b128 v[104:107], v220 offset:1072
	ds_read_b128 v[76:79], v221 offset:0
	ds_read_b128 v[80:83], v221 offset:16
	ds_read_b128 v[84:87], v221 offset:32
	ds_read_b128 v[88:91], v221 offset:48
	s_waitcnt lgkmcnt(8)
	v_pk_fma_f32 v[72:73], v[198:199], v[182:183], v[72:73] op_sel_hi:[0,1,1]
	v_pk_fma_f32 v[60:61], v[198:199], v[182:183], v[60:61] op_sel:[1,0,0]
	v_pk_fma_f32 v[48:49], v[200:201], v[182:183], v[48:49] op_sel_hi:[0,1,1]
	v_pk_fma_f32 v[32:33], v[200:201], v[182:183], v[32:33] op_sel:[1,0,0]
	v_pk_fma_f32 v[74:75], v[198:199], v[184:185], v[74:75] op_sel_hi:[0,1,1]
	v_pk_fma_f32 v[62:63], v[198:199], v[184:185], v[62:63] op_sel:[1,0,0]
	v_pk_fma_f32 v[50:51], v[200:201], v[184:185], v[50:51] op_sel_hi:[0,1,1]
	v_pk_fma_f32 v[34:35], v[200:201], v[184:185], v[34:35] op_sel:[1,0,0]
	v_pk_fma_f32 v[68:69], v[198:199], v[186:187], v[68:69] op_sel_hi:[0,1,1]
	v_pk_fma_f32 v[52:53], v[198:199], v[186:187], v[52:53] op_sel:[1,0,0]
	v_pk_fma_f32 v[40:41], v[200:201], v[186:187], v[40:41] op_sel_hi:[0,1,1]
	v_pk_fma_f32 v[24:25], v[200:201], v[186:187], v[24:25] op_sel:[1,0,0]
	v_pk_fma_f32 v[70:71], v[198:199], v[188:189], v[70:71] op_sel_hi:[0,1,1]
	v_pk_fma_f32 v[54:55], v[198:199], v[188:189], v[54:55] op_sel:[1,0,0]
	v_pk_fma_f32 v[42:43], v[200:201], v[188:189], v[42:43] op_sel_hi:[0,1,1]
	v_pk_fma_f32 v[26:27], v[200:201], v[188:189], v[26:27] op_sel:[1,0,0]
	v_pk_fma_f32 v[64:65], v[198:199], v[190:191], v[64:65] op_sel_hi:[0,1,1]
	v_pk_fma_f32 v[44:45], v[198:199], v[190:191], v[44:45] op_sel:[1,0,0]
	v_pk_fma_f32 v[28:29], v[200:201], v[190:191], v[28:29] op_sel_hi:[0,1,1]
	v_pk_fma_f32 v[16:17], v[200:201], v[190:191], v[16:17] op_sel:[1,0,0]
	v_pk_fma_f32 v[66:67], v[198:199], v[192:193], v[66:67] op_sel_hi:[0,1,1]
	v_pk_fma_f32 v[46:47], v[198:199], v[192:193], v[46:47] op_sel:[1,0,0]
	v_pk_fma_f32 v[30:31], v[200:201], v[192:193], v[30:31] op_sel_hi:[0,1,1]
	v_pk_fma_f32 v[18:19], v[200:201], v[192:193], v[18:19] op_sel:[1,0,0]
	v_pk_fma_f32 v[56:57], v[198:199], v[194:195], v[56:57] op_sel_hi:[0,1,1]
	v_pk_fma_f32 v[36:37], v[198:199], v[194:195], v[36:37] op_sel:[1,0,0]
	v_pk_fma_f32 v[20:21], v[200:201], v[194:195], v[20:21] op_sel_hi:[0,1,1]
	v_pk_fma_f32 v[12:13], v[200:201], v[194:195], v[12:13] op_sel:[1,0,0]
	v_pk_fma_f32 v[58:59], v[198:199], v[196:197], v[58:59] op_sel_hi:[0,1,1]
	v_pk_fma_f32 v[38:39], v[198:199], v[196:197], v[38:39] op_sel:[1,0,0]
	v_pk_fma_f32 v[22:23], v[200:201], v[196:197], v[22:23] op_sel_hi:[0,1,1]
	v_pk_fma_f32 v[14:15], v[200:201], v[196:197], v[14:15] op_sel:[1,0,0]
	s_waitcnt lgkmcnt(4)
	v_pk_mul_f32 v[202:203], v[72:73], v[92:93]
	v_pk_mul_f32 v[204:205], v[74:75], v[94:95]
	v_pk_mul_f32 v[206:207], v[60:61], v[92:93]
	v_pk_mul_f32 v[208:209], v[62:63], v[94:95]
	v_pk_mul_f32 v[210:211], v[48:49], v[92:93]
	v_pk_mul_f32 v[212:213], v[50:51], v[94:95]
	v_pk_mul_f32 v[214:215], v[32:33], v[92:93]
	v_pk_mul_f32 v[216:217], v[34:35], v[94:95]
	v_pk_fma_f32 v[202:203], v[68:69], v[96:97], v[202:203]
	v_pk_fma_f32 v[204:205], v[70:71], v[98:99], v[204:205]
	v_pk_fma_f32 v[206:207], v[52:53], v[96:97], v[206:207]
	v_pk_fma_f32 v[208:209], v[54:55], v[98:99], v[208:209]
	v_pk_fma_f32 v[210:211], v[40:41], v[96:97], v[210:211]
	v_pk_fma_f32 v[212:213], v[42:43], v[98:99], v[212:213]
	v_pk_fma_f32 v[214:215], v[24:25], v[96:97], v[214:215]
	v_pk_fma_f32 v[216:217], v[26:27], v[98:99], v[216:217]
	v_pk_fma_f32 v[202:203], v[64:65], v[100:101], v[202:203]
	v_pk_fma_f32 v[204:205], v[66:67], v[102:103], v[204:205]
	v_pk_fma_f32 v[206:207], v[44:45], v[100:101], v[206:207]
	v_pk_fma_f32 v[208:209], v[46:47], v[102:103], v[208:209]
	v_pk_fma_f32 v[210:211], v[28:29], v[100:101], v[210:211]
	v_pk_fma_f32 v[212:213], v[30:31], v[102:103], v[212:213]
	v_pk_fma_f32 v[214:215], v[16:17], v[100:101], v[214:215]
	v_pk_fma_f32 v[216:217], v[18:19], v[102:103], v[216:217]
	v_pk_fma_f32 v[202:203], v[56:57], v[104:105], v[202:203]
	v_pk_fma_f32 v[204:205], v[58:59], v[106:107], v[204:205]
	v_pk_fma_f32 v[206:207], v[36:37], v[104:105], v[206:207]
	v_pk_fma_f32 v[208:209], v[38:39], v[106:107], v[208:209]
	v_pk_fma_f32 v[210:211], v[20:21], v[104:105], v[210:211]
	v_pk_fma_f32 v[212:213], v[22:23], v[106:107], v[212:213]
	v_pk_fma_f32 v[214:215], v[12:13], v[104:105], v[214:215]
	v_pk_fma_f32 v[216:217], v[14:15], v[106:107], v[216:217]
	v_pk_add_f32 v[202:203], v[202:203], v[204:205]
	v_pk_add_f32 v[206:207], v[206:207], v[208:209]
	v_pk_add_f32 v[210:211], v[210:211], v[212:213]
	v_pk_add_f32 v[214:215], v[214:215], v[216:217]
	ds_read_b128 v[92:95], v221 offset:256
	v_add_f32_e32 v202, v202, v203
	v_add_f32_e32 v206, v206, v207
	v_add_f32_e32 v210, v210, v211
	v_add_f32_e32 v214, v214, v215
	ds_read_b128 v[96:99], v221 offset:272
	v_add_f32_dpp v202, v202, v202 quad_perm:[1,0,3,2] row_mask:0xf bank_mask:0xf bound_ctrl:1
	v_add_f32_dpp v206, v206, v206 quad_perm:[1,0,3,2] row_mask:0xf bank_mask:0xf bound_ctrl:1
	v_add_f32_dpp v210, v210, v210 quad_perm:[1,0,3,2] row_mask:0xf bank_mask:0xf bound_ctrl:1
	v_add_f32_dpp v214, v214, v214 quad_perm:[1,0,3,2] row_mask:0xf bank_mask:0xf bound_ctrl:1
	ds_read_b128 v[100:103], v221 offset:288
	v_add_f32_dpp v202, v202, v202 quad_perm:[2,3,0,1] row_mask:0xf bank_mask:0xf bound_ctrl:1
	v_add_f32_dpp v206, v206, v206 quad_perm:[2,3,0,1] row_mask:0xf bank_mask:0xf bound_ctrl:1
	v_add_f32_dpp v210, v210, v210 quad_perm:[2,3,0,1] row_mask:0xf bank_mask:0xf bound_ctrl:1
	v_add_f32_dpp v214, v214, v214 quad_perm:[2,3,0,1] row_mask:0xf bank_mask:0xf bound_ctrl:1
	ds_read_b128 v[104:107], v221 offset:304
	ds_read_b128 v[108:111], v221 offset:512
	v_cvt_pk_bf16_f32 v240, v202, v206
	v_cvt_pk_bf16_f32 v241, v210, v214
	ds_read_b128 v[170:173], v221 offset:528
	ds_read_b128 v[174:177], v221 offset:544
	s_mov_b64 exec, s[6:7]
	global_store_dwordx2 v[238:239], v[240:241], off
	s_mov_b64 exec, -1
	ds_read_b128 v[178:181], v221 offset:560
	ds_read_b128 v[198:201], v237 offset:1280
	v_lshl_add_u64 v[238:239], v[238:239], 0, s[80:81]
	s_waitcnt lgkmcnt(9)
	ds_read_b128 v[182:185], v221 offset:768
	ds_read_b128 v[186:189], v221 offset:784
	ds_read_b128 v[190:193], v221 offset:800
	ds_read_b128 v[194:197], v221 offset:816
	v_pk_mul_f32 v[202:203], v[72:73], v[76:77]
	v_pk_mul_f32 v[204:205], v[74:75], v[78:79]
	v_pk_mul_f32 v[206:207], v[60:61], v[76:77]
	v_pk_mul_f32 v[208:209], v[62:63], v[78:79]
	v_pk_mul_f32 v[210:211], v[48:49], v[76:77]
	v_pk_mul_f32 v[212:213], v[50:51], v[78:79]
	v_pk_mul_f32 v[214:215], v[32:33], v[76:77]
	v_pk_mul_f32 v[216:217], v[34:35], v[78:79]
	v_pk_fma_f32 v[202:203], v[68:69], v[80:81], v[202:203]
	v_pk_fma_f32 v[204:205], v[70:71], v[82:83], v[204:205]
	v_pk_fma_f32 v[206:207], v[52:53], v[80:81], v[206:207]
	v_pk_fma_f32 v[208:209], v[54:55], v[82:83], v[208:209]
	v_pk_fma_f32 v[210:211], v[40:41], v[80:81], v[210:211]
	v_pk_fma_f32 v[212:213], v[42:43], v[82:83], v[212:213]
	v_pk_fma_f32 v[214:215], v[24:25], v[80:81], v[214:215]
	v_pk_fma_f32 v[216:217], v[26:27], v[82:83], v[216:217]
	v_pk_fma_f32 v[202:203], v[64:65], v[84:85], v[202:203]
	v_pk_fma_f32 v[204:205], v[66:67], v[86:87], v[204:205]
	v_pk_fma_f32 v[206:207], v[44:45], v[84:85], v[206:207]
	v_pk_fma_f32 v[208:209], v[46:47], v[86:87], v[208:209]
	v_pk_fma_f32 v[210:211], v[28:29], v[84:85], v[210:211]
	v_pk_fma_f32 v[212:213], v[30:31], v[86:87], v[212:213]
	v_pk_fma_f32 v[214:215], v[16:17], v[84:85], v[214:215]
	v_pk_fma_f32 v[216:217], v[18:19], v[86:87], v[216:217]
	v_pk_fma_f32 v[202:203], v[56:57], v[88:89], v[202:203]
	v_pk_fma_f32 v[204:205], v[58:59], v[90:91], v[204:205]
	v_pk_fma_f32 v[206:207], v[36:37], v[88:89], v[206:207]
	v_pk_fma_f32 v[208:209], v[38:39], v[90:91], v[208:209]
	v_pk_fma_f32 v[210:211], v[20:21], v[88:89], v[210:211]
	v_pk_fma_f32 v[212:213], v[22:23], v[90:91], v[212:213]
	v_pk_fma_f32 v[214:215], v[12:13], v[88:89], v[214:215]
	v_pk_fma_f32 v[216:217], v[14:15], v[90:91], v[216:217]
	s_waitcnt lgkmcnt(5)
	v_pk_add_f32 v[202:203], v[202:203], v[204:205]
	v_pk_add_f32 v[206:207], v[206:207], v[208:209]
	v_pk_add_f32 v[210:211], v[210:211], v[212:213]
	v_pk_add_f32 v[214:215], v[214:215], v[216:217]
	v_add_f32_e32 v202, v202, v203
	v_add_f32_e32 v206, v206, v207
	v_add_f32_e32 v210, v210, v211
	v_add_f32_e32 v214, v214, v215
	v_add_f32_dpp v202, v202, v202 quad_perm:[1,0,3,2] row_mask:0xf bank_mask:0xf bound_ctrl:1
	v_add_f32_dpp v206, v206, v206 quad_perm:[1,0,3,2] row_mask:0xf bank_mask:0xf bound_ctrl:1
	v_add_f32_dpp v210, v210, v210 quad_perm:[1,0,3,2] row_mask:0xf bank_mask:0xf bound_ctrl:1
	v_add_f32_dpp v214, v214, v214 quad_perm:[1,0,3,2] row_mask:0xf bank_mask:0xf bound_ctrl:1
	v_add_f32_dpp v202, v202, v202 quad_perm:[2,3,0,1] row_mask:0xf bank_mask:0xf bound_ctrl:1
	v_add_f32_dpp v206, v206, v206 quad_perm:[2,3,0,1] row_mask:0xf bank_mask:0xf bound_ctrl:1
	v_add_f32_dpp v210, v210, v210 quad_perm:[2,3,0,1] row_mask:0xf bank_mask:0xf bound_ctrl:1
	v_add_f32_dpp v214, v214, v214 quad_perm:[2,3,0,1] row_mask:0xf bank_mask:0xf bound_ctrl:1
	v_pk_mul_f32 v[204:205], v[108:109], v[202:203] op_sel_hi:[1,0]
	v_pk_mul_f32 v[208:209], v[108:109], v[206:207] op_sel_hi:[1,0]
	v_pk_mul_f32 v[212:213], v[108:109], v[210:211] op_sel_hi:[1,0]
	v_pk_mul_f32 v[108:109], v[108:109], v[214:215] op_sel_hi:[1,0]
	v_pk_fma_f32 v[72:73], v[72:73], v[92:93], v[204:205]
	v_pk_fma_f32 v[60:61], v[60:61], v[92:93], v[208:209]
	v_pk_fma_f32 v[48:49], v[48:49], v[92:93], v[212:213]
	v_pk_fma_f32 v[32:33], v[32:33], v[92:93], v[108:109]
	v_pk_mul_f32 v[216:217], v[110:111], v[202:203] op_sel_hi:[1,0]
	v_pk_mul_f32 v[242:243], v[110:111], v[206:207] op_sel_hi:[1,0]
	v_pk_mul_f32 v[244:245], v[110:111], v[210:211] op_sel_hi:[1,0]
	v_pk_mul_f32 v[110:111], v[110:111], v[214:215] op_sel_hi:[1,0]
	v_pk_fma_f32 v[74:75], v[74:75], v[94:95], v[216:217]
	v_pk_fma_f32 v[62:63], v[62:63], v[94:95], v[242:243]
	v_pk_fma_f32 v[50:51], v[50:51], v[94:95], v[244:245]
	v_pk_fma_f32 v[34:35], v[34:35], v[94:95], v[110:111]
	v_pk_mul_f32 v[204:205], v[170:171], v[202:203] op_sel_hi:[1,0]
	v_pk_mul_f32 v[208:209], v[170:171], v[206:207] op_sel_hi:[1,0]
	v_pk_mul_f32 v[212:213], v[170:171], v[210:211] op_sel_hi:[1,0]
	v_pk_mul_f32 v[170:171], v[170:171], v[214:215] op_sel_hi:[1,0]
	v_pk_fma_f32 v[68:69], v[68:69], v[96:97], v[204:205]
	v_pk_fma_f32 v[52:53], v[52:53], v[96:97], v[208:209]
	v_pk_fma_f32 v[40:41], v[40:41], v[96:97], v[212:213]
	v_pk_fma_f32 v[24:25], v[24:25], v[96:97], v[170:171]
	v_pk_mul_f32 v[216:217], v[172:173], v[202:203] op_sel_hi:[1,0]
	v_pk_mul_f32 v[242:243], v[172:173], v[206:207] op_sel_hi:[1,0]
	v_pk_mul_f32 v[244:245], v[172:173], v[210:211] op_sel_hi:[1,0]
	v_pk_mul_f32 v[172:173], v[172:173], v[214:215] op_sel_hi:[1,0]
	v_pk_fma_f32 v[70:71], v[70:71], v[98:99], v[216:217]
	v_pk_fma_f32 v[54:55], v[54:55], v[98:99], v[242:243]
	v_pk_fma_f32 v[42:43], v[42:43], v[98:99], v[244:245]
	v_pk_fma_f32 v[26:27], v[26:27], v[98:99], v[172:173]
	v_pk_mul_f32 v[204:205], v[174:175], v[202:203] op_sel_hi:[1,0]
	v_pk_mul_f32 v[208:209], v[174:175], v[206:207] op_sel_hi:[1,0]
	v_pk_mul_f32 v[212:213], v[174:175], v[210:211] op_sel_hi:[1,0]
	v_pk_mul_f32 v[174:175], v[174:175], v[214:215] op_sel_hi:[1,0]
	v_pk_fma_f32 v[64:65], v[64:65], v[100:101], v[204:205]
	v_pk_fma_f32 v[44:45], v[44:45], v[100:101], v[208:209]
	v_pk_fma_f32 v[28:29], v[28:29], v[100:101], v[212:213]
	v_pk_fma_f32 v[16:17], v[16:17], v[100:101], v[174:175]
	v_pk_mul_f32 v[216:217], v[176:177], v[202:203] op_sel_hi:[1,0]
	v_pk_mul_f32 v[242:243], v[176:177], v[206:207] op_sel_hi:[1,0]
	v_pk_mul_f32 v[244:245], v[176:177], v[210:211] op_sel_hi:[1,0]
	v_pk_mul_f32 v[176:177], v[176:177], v[214:215] op_sel_hi:[1,0]
	v_pk_fma_f32 v[66:67], v[66:67], v[102:103], v[216:217]
	v_pk_fma_f32 v[46:47], v[46:47], v[102:103], v[242:243]
	v_pk_fma_f32 v[30:31], v[30:31], v[102:103], v[244:245]
	v_pk_fma_f32 v[18:19], v[18:19], v[102:103], v[176:177]
	v_pk_mul_f32 v[204:205], v[178:179], v[202:203] op_sel_hi:[1,0]
	v_pk_mul_f32 v[208:209], v[178:179], v[206:207] op_sel_hi:[1,0]
	v_pk_mul_f32 v[212:213], v[178:179], v[210:211] op_sel_hi:[1,0]
	v_pk_mul_f32 v[178:179], v[178:179], v[214:215] op_sel_hi:[1,0]
	v_pk_fma_f32 v[56:57], v[56:57], v[104:105], v[204:205]
	v_pk_fma_f32 v[36:37], v[36:37], v[104:105], v[208:209]
	v_pk_fma_f32 v[20:21], v[20:21], v[104:105], v[212:213]
	v_pk_fma_f32 v[12:13], v[12:13], v[104:105], v[178:179]
	v_pk_mul_f32 v[216:217], v[180:181], v[202:203] op_sel_hi:[1,0]
	v_pk_mul_f32 v[242:243], v[180:181], v[206:207] op_sel_hi:[1,0]
	v_pk_mul_f32 v[244:245], v[180:181], v[210:211] op_sel_hi:[1,0]
	v_pk_mul_f32 v[180:181], v[180:181], v[214:215] op_sel_hi:[1,0]
	v_pk_fma_f32 v[58:59], v[58:59], v[106:107], v[216:217]
	v_pk_fma_f32 v[38:39], v[38:39], v[106:107], v[242:243]
	v_pk_fma_f32 v[22:23], v[22:23], v[106:107], v[244:245]
	v_pk_fma_f32 v[14:15], v[14:15], v[106:107], v[180:181]
	ds_read_b128 v[92:95], v221 offset:1024
	ds_read_b128 v[96:99], v221 offset:1040
	ds_read_b128 v[100:103], v221 offset:1056
	ds_read_b128 v[104:107], v221 offset:1072
	s_waitcnt lgkmcnt(4)
	v_pk_fma_f32 v[72:73], v[198:199], v[182:183], v[72:73] op_sel_hi:[0,1,1]
	v_pk_fma_f32 v[60:61], v[198:199], v[182:183], v[60:61] op_sel:[1,0,0]
	v_pk_fma_f32 v[48:49], v[200:201], v[182:183], v[48:49] op_sel_hi:[0,1,1]
	v_pk_fma_f32 v[32:33], v[200:201], v[182:183], v[32:33] op_sel:[1,0,0]
	v_pk_fma_f32 v[74:75], v[198:199], v[184:185], v[74:75] op_sel_hi:[0,1,1]
	v_pk_fma_f32 v[62:63], v[198:199], v[184:185], v[62:63] op_sel:[1,0,0]
	v_pk_fma_f32 v[50:51], v[200:201], v[184:185], v[50:51] op_sel_hi:[0,1,1]
	v_pk_fma_f32 v[34:35], v[200:201], v[184:185], v[34:35] op_sel:[1,0,0]
	v_pk_fma_f32 v[68:69], v[198:199], v[186:187], v[68:69] op_sel_hi:[0,1,1]
	v_pk_fma_f32 v[52:53], v[198:199], v[186:187], v[52:53] op_sel:[1,0,0]
	v_pk_fma_f32 v[40:41], v[200:201], v[186:187], v[40:41] op_sel_hi:[0,1,1]
	v_pk_fma_f32 v[24:25], v[200:201], v[186:187], v[24:25] op_sel:[1,0,0]
	v_pk_fma_f32 v[70:71], v[198:199], v[188:189], v[70:71] op_sel_hi:[0,1,1]
	v_pk_fma_f32 v[54:55], v[198:199], v[188:189], v[54:55] op_sel:[1,0,0]
	v_pk_fma_f32 v[42:43], v[200:201], v[188:189], v[42:43] op_sel_hi:[0,1,1]
	v_pk_fma_f32 v[26:27], v[200:201], v[188:189], v[26:27] op_sel:[1,0,0]
	v_pk_fma_f32 v[64:65], v[198:199], v[190:191], v[64:65] op_sel_hi:[0,1,1]
	v_pk_fma_f32 v[44:45], v[198:199], v[190:191], v[44:45] op_sel:[1,0,0]
	v_pk_fma_f32 v[28:29], v[200:201], v[190:191], v[28:29] op_sel_hi:[0,1,1]
	v_pk_fma_f32 v[16:17], v[200:201], v[190:191], v[16:17] op_sel:[1,0,0]
	v_pk_fma_f32 v[66:67], v[198:199], v[192:193], v[66:67] op_sel_hi:[0,1,1]
	v_pk_fma_f32 v[46:47], v[198:199], v[192:193], v[46:47] op_sel:[1,0,0]
	v_pk_fma_f32 v[30:31], v[200:201], v[192:193], v[30:31] op_sel_hi:[0,1,1]
	v_pk_fma_f32 v[18:19], v[200:201], v[192:193], v[18:19] op_sel:[1,0,0]
	v_pk_fma_f32 v[56:57], v[198:199], v[194:195], v[56:57] op_sel_hi:[0,1,1]
	v_pk_fma_f32 v[36:37], v[198:199], v[194:195], v[36:37] op_sel:[1,0,0]
	v_pk_fma_f32 v[20:21], v[200:201], v[194:195], v[20:21] op_sel_hi:[0,1,1]
	v_pk_fma_f32 v[12:13], v[200:201], v[194:195], v[12:13] op_sel:[1,0,0]
	v_pk_fma_f32 v[58:59], v[198:199], v[196:197], v[58:59] op_sel_hi:[0,1,1]
	v_pk_fma_f32 v[38:39], v[198:199], v[196:197], v[38:39] op_sel:[1,0,0]
	v_pk_fma_f32 v[22:23], v[200:201], v[196:197], v[22:23] op_sel_hi:[0,1,1]
	v_pk_fma_f32 v[14:15], v[200:201], v[196:197], v[14:15] op_sel:[1,0,0]
	s_waitcnt lgkmcnt(0)
	v_pk_mul_f32 v[202:203], v[72:73], v[92:93]
	v_pk_mul_f32 v[204:205], v[74:75], v[94:95]
	v_pk_mul_f32 v[206:207], v[60:61], v[92:93]
	v_pk_mul_f32 v[208:209], v[62:63], v[94:95]
	v_pk_mul_f32 v[210:211], v[48:49], v[92:93]
	v_pk_mul_f32 v[212:213], v[50:51], v[94:95]
	v_pk_mul_f32 v[214:215], v[32:33], v[92:93]
	v_pk_mul_f32 v[216:217], v[34:35], v[94:95]
	v_pk_fma_f32 v[202:203], v[68:69], v[96:97], v[202:203]
	v_pk_fma_f32 v[204:205], v[70:71], v[98:99], v[204:205]
	v_pk_fma_f32 v[206:207], v[52:53], v[96:97], v[206:207]
	v_pk_fma_f32 v[208:209], v[54:55], v[98:99], v[208:209]
	v_pk_fma_f32 v[210:211], v[40:41], v[96:97], v[210:211]
	v_pk_fma_f32 v[212:213], v[42:43], v[98:99], v[212:213]
	v_pk_fma_f32 v[214:215], v[24:25], v[96:97], v[214:215]
	v_pk_fma_f32 v[216:217], v[26:27], v[98:99], v[216:217]
	v_pk_fma_f32 v[202:203], v[64:65], v[100:101], v[202:203]
	v_pk_fma_f32 v[204:205], v[66:67], v[102:103], v[204:205]
	v_pk_fma_f32 v[206:207], v[44:45], v[100:101], v[206:207]
	v_pk_fma_f32 v[208:209], v[46:47], v[102:103], v[208:209]
	v_pk_fma_f32 v[210:211], v[28:29], v[100:101], v[210:211]
	v_pk_fma_f32 v[212:213], v[30:31], v[102:103], v[212:213]
	v_pk_fma_f32 v[214:215], v[16:17], v[100:101], v[214:215]
	v_pk_fma_f32 v[216:217], v[18:19], v[102:103], v[216:217]
	v_pk_fma_f32 v[202:203], v[56:57], v[104:105], v[202:203]
	v_pk_fma_f32 v[204:205], v[58:59], v[106:107], v[204:205]
	v_pk_fma_f32 v[206:207], v[36:37], v[104:105], v[206:207]
	v_pk_fma_f32 v[208:209], v[38:39], v[106:107], v[208:209]
	v_pk_fma_f32 v[210:211], v[20:21], v[104:105], v[210:211]
	v_pk_fma_f32 v[212:213], v[22:23], v[106:107], v[212:213]
	v_pk_fma_f32 v[214:215], v[12:13], v[104:105], v[214:215]
	v_pk_fma_f32 v[216:217], v[14:15], v[106:107], v[216:217]
	v_pk_add_f32 v[202:203], v[202:203], v[204:205]
	v_pk_add_f32 v[206:207], v[206:207], v[208:209]
	v_pk_add_f32 v[210:211], v[210:211], v[212:213]
	v_pk_add_f32 v[214:215], v[214:215], v[216:217]
	v_add_f32_e32 v202, v202, v203
	v_add_f32_e32 v206, v206, v207
	v_add_f32_e32 v210, v210, v211
	v_add_f32_e32 v214, v214, v215
	v_add_f32_dpp v202, v202, v202 quad_perm:[1,0,3,2] row_mask:0xf bank_mask:0xf bound_ctrl:1
	v_add_f32_dpp v206, v206, v206 quad_perm:[1,0,3,2] row_mask:0xf bank_mask:0xf bound_ctrl:1
	v_add_f32_dpp v210, v210, v210 quad_perm:[1,0,3,2] row_mask:0xf bank_mask:0xf bound_ctrl:1
	v_add_f32_dpp v214, v214, v214 quad_perm:[1,0,3,2] row_mask:0xf bank_mask:0xf bound_ctrl:1
	v_add_f32_dpp v202, v202, v202 quad_perm:[2,3,0,1] row_mask:0xf bank_mask:0xf bound_ctrl:1
	v_add_f32_dpp v206, v206, v206 quad_perm:[2,3,0,1] row_mask:0xf bank_mask:0xf bound_ctrl:1
	v_add_f32_dpp v210, v210, v210 quad_perm:[2,3,0,1] row_mask:0xf bank_mask:0xf bound_ctrl:1
	v_add_f32_dpp v214, v214, v214 quad_perm:[2,3,0,1] row_mask:0xf bank_mask:0xf bound_ctrl:1
	s_nop 0
	v_cvt_pk_bf16_f32 v240, v202, v206
	v_cvt_pk_bf16_f32 v241, v210, v214
	s_mov_b64 exec, s[6:7]
	global_store_dwordx2 v[238:239], v[240:241], off
	s_mov_b64 exec, -1
	s_waitcnt lgkmcnt(0)

.LBB0_978:
	s_add_i32 s82, s65, s99
	s_ashr_i32 s83, s82, 31
	s_lshl_b64 s[82:83], s[82:83], 7
	v_lshl_add_u64 v[238:239], v[124:125], 0, s[82:83]
	v_add_u32_e32 v218, s97, v232
	v_lshl_add_u32 v222, v114, 2, s57
	v_add_u32_e32 v219, s98, v218
	v_add_u32_e32 v222, s97, v222
	v_add_u32_e32 v220, s98, v219
	v_add_u32_e32 v223, s98, v222
	v_add_u32_e32 v221, s98, v220
	v_add_u32_e32 v236, s98, v223
	v_add_u32_e32 v237, s98, v236
	ds_read_b128 v[92:95], v218 offset:256
	ds_read_b128 v[96:99], v218 offset:272
	ds_read_b128 v[100:103], v218 offset:288
	ds_read_b128 v[104:107], v218 offset:304
	ds_read_b128 v[108:111], v218 offset:512
	ds_read_b128 v[170:173], v218 offset:528
	ds_read_b128 v[174:177], v218 offset:544
	ds_read_b128 v[178:181], v218 offset:560
	ds_read_b128 v[198:201], v222 offset:1280
	s_waitcnt lgkmcnt(9)
	ds_read_b128 v[182:185], v218 offset:768
	ds_read_b128 v[186:189], v218 offset:784
	ds_read_b128 v[190:193], v218 offset:800
	ds_read_b128 v[194:197], v218 offset:816
	v_pk_mul_f32 v[202:203], v[72:73], v[76:77]
	v_pk_mul_f32 v[204:205], v[74:75], v[78:79]
	v_pk_mul_f32 v[206:207], v[60:61], v[76:77]
	v_pk_mul_f32 v[208:209], v[62:63], v[78:79]
	v_pk_mul_f32 v[210:211], v[48:49], v[76:77]
	v_pk_mul_f32 v[212:213], v[50:51], v[78:79]
	v_pk_mul_f32 v[214:215], v[32:33], v[76:77]
	v_pk_mul_f32 v[216:217], v[34:35], v[78:79]
	v_pk_fma_f32 v[202:203], v[68:69], v[80:81], v[202:203]
	v_pk_fma_f32 v[204:205], v[70:71], v[82:83], v[204:205]
	v_pk_fma_f32 v[206:207], v[52:53], v[80:81], v[206:207]
	v_pk_fma_f32 v[208:209], v[54:55], v[82:83], v[208:209]
	v_pk_fma_f32 v[210:211], v[40:41], v[80:81], v[210:211]
	v_pk_fma_f32 v[212:213], v[42:43], v[82:83], v[212:213]
	v_pk_fma_f32 v[214:215], v[24:25], v[80:81], v[214:215]
	v_pk_fma_f32 v[216:217], v[26:27], v[82:83], v[216:217]
	v_pk_fma_f32 v[202:203], v[64:65], v[84:85], v[202:203]
	v_pk_fma_f32 v[204:205], v[66:67], v[86:87], v[204:205]
	v_pk_fma_f32 v[206:207], v[44:45], v[84:85], v[206:207]
	v_pk_fma_f32 v[208:209], v[46:47], v[86:87], v[208:209]
	v_pk_fma_f32 v[210:211], v[28:29], v[84:85], v[210:211]
	v_pk_fma_f32 v[212:213], v[30:31], v[86:87], v[212:213]
	v_pk_fma_f32 v[214:215], v[16:17], v[84:85], v[214:215]
	v_pk_fma_f32 v[216:217], v[18:19], v[86:87], v[216:217]
	v_pk_fma_f32 v[202:203], v[56:57], v[88:89], v[202:203]
	v_pk_fma_f32 v[204:205], v[58:59], v[90:91], v[204:205]
	v_pk_fma_f32 v[206:207], v[36:37], v[88:89], v[206:207]
	v_pk_fma_f32 v[208:209], v[38:39], v[90:91], v[208:209]
	v_pk_fma_f32 v[210:211], v[20:21], v[88:89], v[210:211]
	v_pk_fma_f32 v[212:213], v[22:23], v[90:91], v[212:213]
	v_pk_fma_f32 v[214:215], v[12:13], v[88:89], v[214:215]
	v_pk_fma_f32 v[216:217], v[14:15], v[90:91], v[216:217]
	s_waitcnt lgkmcnt(5)
	v_pk_add_f32 v[202:203], v[202:203], v[204:205]
	v_pk_add_f32 v[206:207], v[206:207], v[208:209]
	v_pk_add_f32 v[210:211], v[210:211], v[212:213]
	v_pk_add_f32 v[214:215], v[214:215], v[216:217]
	v_add_f32_e32 v202, v202, v203
	v_add_f32_e32 v206, v206, v207
	v_add_f32_e32 v210, v210, v211
	v_add_f32_e32 v214, v214, v215
	v_add_f32_dpp v202, v202, v202 quad_perm:[1,0,3,2] row_mask:0xf bank_mask:0xf bound_ctrl:1
	v_add_f32_dpp v206, v206, v206 quad_perm:[1,0,3,2] row_mask:0xf bank_mask:0xf bound_ctrl:1
	v_add_f32_dpp v210, v210, v210 quad_perm:[1,0,3,2] row_mask:0xf bank_mask:0xf bound_ctrl:1
	v_add_f32_dpp v214, v214, v214 quad_perm:[1,0,3,2] row_mask:0xf bank_mask:0xf bound_ctrl:1
	v_add_f32_dpp v202, v202, v202 quad_perm:[2,3,0,1] row_mask:0xf bank_mask:0xf bound_ctrl:1
	v_add_f32_dpp v206, v206, v206 quad_perm:[2,3,0,1] row_mask:0xf bank_mask:0xf bound_ctrl:1
	v_add_f32_dpp v210, v210, v210 quad_perm:[2,3,0,1] row_mask:0xf bank_mask:0xf bound_ctrl:1
	v_add_f32_dpp v214, v214, v214 quad_perm:[2,3,0,1] row_mask:0xf bank_mask:0xf bound_ctrl:1
	v_pk_mul_f32 v[204:205], v[108:109], v[202:203] op_sel_hi:[1,0]
	v_pk_mul_f32 v[208:209], v[108:109], v[206:207] op_sel_hi:[1,0]
	v_pk_mul_f32 v[212:213], v[108:109], v[210:211] op_sel_hi:[1,0]
	v_pk_mul_f32 v[108:109], v[108:109], v[214:215] op_sel_hi:[1,0]
	v_pk_fma_f32 v[72:73], v[72:73], v[92:93], v[204:205]
	v_pk_fma_f32 v[60:61], v[60:61], v[92:93], v[208:209]
	v_pk_fma_f32 v[48:49], v[48:49], v[92:93], v[212:213]
	v_pk_fma_f32 v[32:33], v[32:33], v[92:93], v[108:109]
	v_pk_mul_f32 v[216:217], v[110:111], v[202:203] op_sel_hi:[1,0]
	v_pk_mul_f32 v[242:243], v[110:111], v[206:207] op_sel_hi:[1,0]
	v_pk_mul_f32 v[244:245], v[110:111], v[210:211] op_sel_hi:[1,0]
	v_pk_mul_f32 v[110:111], v[110:111], v[214:215] op_sel_hi:[1,0]
	v_pk_fma_f32 v[74:75], v[74:75], v[94:95], v[216:217]
	v_pk_fma_f32 v[62:63], v[62:63], v[94:95], v[242:243]
	v_pk_fma_f32 v[50:51], v[50:51], v[94:95], v[244:245]
	v_pk_fma_f32 v[34:35], v[34:35], v[94:95], v[110:111]
	v_pk_mul_f32 v[204:205], v[170:171], v[202:203] op_sel_hi:[1,0]
	v_pk_mul_f32 v[208:209], v[170:171], v[206:207] op_sel_hi:[1,0]
	v_pk_mul_f32 v[212:213], v[170:171], v[210:211] op_sel_hi:[1,0]
	v_pk_mul_f32 v[170:171], v[170:171], v[214:215] op_sel_hi:[1,0]
	v_pk_fma_f32 v[68:69], v[68:69], v[96:97], v[204:205]
	v_pk_fma_f32 v[52:53], v[52:53], v[96:97], v[208:209]
	v_pk_fma_f32 v[40:41], v[40:41], v[96:97], v[212:213]
	v_pk_fma_f32 v[24:25], v[24:25], v[96:97], v[170:171]
	v_pk_mul_f32 v[216:217], v[172:173], v[202:203] op_sel_hi:[1,0]
	v_pk_mul_f32 v[242:243], v[172:173], v[206:207] op_sel_hi:[1,0]
	v_pk_mul_f32 v[244:245], v[172:173], v[210:211] op_sel_hi:[1,0]
	v_pk_mul_f32 v[172:173], v[172:173], v[214:215] op_sel_hi:[1,0]
	v_pk_fma_f32 v[70:71], v[70:71], v[98:99], v[216:217]
	v_pk_fma_f32 v[54:55], v[54:55], v[98:99], v[242:243]
	v_pk_fma_f32 v[42:43], v[42:43], v[98:99], v[244:245]
	v_pk_fma_f32 v[26:27], v[26:27], v[98:99], v[172:173]
	v_pk_mul_f32 v[204:205], v[174:175], v[202:203] op_sel_hi:[1,0]
	v_pk_mul_f32 v[208:209], v[174:175], v[206:207] op_sel_hi:[1,0]
	v_pk_mul_f32 v[212:213], v[174:175], v[210:211] op_sel_hi:[1,0]
	v_pk_mul_f32 v[174:175], v[174:175], v[214:215] op_sel_hi:[1,0]
	v_pk_fma_f32 v[64:65], v[64:65], v[100:101], v[204:205]
	v_pk_fma_f32 v[44:45], v[44:45], v[100:101], v[208:209]
	v_pk_fma_f32 v[28:29], v[28:29], v[100:101], v[212:213]
	v_pk_fma_f32 v[16:17], v[16:17], v[100:101], v[174:175]
	v_pk_mul_f32 v[216:217], v[176:177], v[202:203] op_sel_hi:[1,0]
	v_pk_mul_f32 v[242:243], v[176:177], v[206:207] op_sel_hi:[1,0]
	v_pk_mul_f32 v[244:245], v[176:177], v[210:211] op_sel_hi:[1,0]
	v_pk_mul_f32 v[176:177], v[176:177], v[214:215] op_sel_hi:[1,0]
	v_pk_fma_f32 v[66:67], v[66:67], v[102:103], v[216:217]
	v_pk_fma_f32 v[46:47], v[46:47], v[102:103], v[242:243]
	v_pk_fma_f32 v[30:31], v[30:31], v[102:103], v[244:245]
	v_pk_fma_f32 v[18:19], v[18:19], v[102:103], v[176:177]
	v_pk_mul_f32 v[204:205], v[178:179], v[202:203] op_sel_hi:[1,0]
	v_pk_mul_f32 v[208:209], v[178:179], v[206:207] op_sel_hi:[1,0]
	v_pk_mul_f32 v[212:213], v[178:179], v[210:211] op_sel_hi:[1,0]
	v_pk_mul_f32 v[178:179], v[178:179], v[214:215] op_sel_hi:[1,0]
	v_pk_fma_f32 v[56:57], v[56:57], v[104:105], v[204:205]
	v_pk_fma_f32 v[36:37], v[36:37], v[104:105], v[208:209]
	v_pk_fma_f32 v[20:21], v[20:21], v[104:105], v[212:213]
	v_pk_fma_f32 v[12:13], v[12:13], v[104:105], v[178:179]
	v_pk_mul_f32 v[216:217], v[180:181], v[202:203] op_sel_hi:[1,0]
	v_pk_mul_f32 v[242:243], v[180:181], v[206:207] op_sel_hi:[1,0]
	v_pk_mul_f32 v[244:245], v[180:181], v[210:211] op_sel_hi:[1,0]
	v_pk_mul_f32 v[180:181], v[180:181], v[214:215] op_sel_hi:[1,0]
	v_pk_fma_f32 v[58:59], v[58:59], v[106:107], v[216:217]
	v_pk_fma_f32 v[38:39], v[38:39], v[106:107], v[242:243]
	v_pk_fma_f32 v[22:23], v[22:23], v[106:107], v[244:245]
	v_pk_fma_f32 v[14:15], v[14:15], v[106:107], v[180:181]
	ds_read_b128 v[92:95], v218 offset:1024
	ds_read_b128 v[96:99], v218 offset:1040
	ds_read_b128 v[100:103], v218 offset:1056
	ds_read_b128 v[104:107], v218 offset:1072
	ds_read_b128 v[76:79], v219 offset:0
	ds_read_b128 v[80:83], v219 offset:16
	ds_read_b128 v[84:87], v219 offset:32
	ds_read_b128 v[88:91], v219 offset:48
	s_waitcnt lgkmcnt(8)
	v_pk_fma_f32 v[72:73], v[198:199], v[182:183], v[72:73] op_sel_hi:[0,1,1]
	v_pk_fma_f32 v[60:61], v[198:199], v[182:183], v[60:61] op_sel:[1,0,0]
	v_pk_fma_f32 v[48:49], v[200:201], v[182:183], v[48:49] op_sel_hi:[0,1,1]
	v_pk_fma_f32 v[32:33], v[200:201], v[182:183], v[32:33] op_sel:[1,0,0]
	v_pk_fma_f32 v[74:75], v[198:199], v[184:185], v[74:75] op_sel_hi:[0,1,1]
	v_pk_fma_f32 v[62:63], v[198:199], v[184:185], v[62:63] op_sel:[1,0,0]
	v_pk_fma_f32 v[50:51], v[200:201], v[184:185], v[50:51] op_sel_hi:[0,1,1]
	v_pk_fma_f32 v[34:35], v[200:201], v[184:185], v[34:35] op_sel:[1,0,0]
	v_pk_fma_f32 v[68:69], v[198:199], v[186:187], v[68:69] op_sel_hi:[0,1,1]
	v_pk_fma_f32 v[52:53], v[198:199], v[186:187], v[52:53] op_sel:[1,0,0]
	v_pk_fma_f32 v[40:41], v[200:201], v[186:187], v[40:41] op_sel_hi:[0,1,1]
	v_pk_fma_f32 v[24:25], v[200:201], v[186:187], v[24:25] op_sel:[1,0,0]
	v_pk_fma_f32 v[70:71], v[198:199], v[188:189], v[70:71] op_sel_hi:[0,1,1]
	v_pk_fma_f32 v[54:55], v[198:199], v[188:189], v[54:55] op_sel:[1,0,0]
	v_pk_fma_f32 v[42:43], v[200:201], v[188:189], v[42:43] op_sel_hi:[0,1,1]
	v_pk_fma_f32 v[26:27], v[200:201], v[188:189], v[26:27] op_sel:[1,0,0]
	v_pk_fma_f32 v[64:65], v[198:199], v[190:191], v[64:65] op_sel_hi:[0,1,1]
	v_pk_fma_f32 v[44:45], v[198:199], v[190:191], v[44:45] op_sel:[1,0,0]
	v_pk_fma_f32 v[28:29], v[200:201], v[190:191], v[28:29] op_sel_hi:[0,1,1]
	v_pk_fma_f32 v[16:17], v[200:201], v[190:191], v[16:17] op_sel:[1,0,0]
	v_pk_fma_f32 v[66:67], v[198:199], v[192:193], v[66:67] op_sel_hi:[0,1,1]
	v_pk_fma_f32 v[46:47], v[198:199], v[192:193], v[46:47] op_sel:[1,0,0]
	v_pk_fma_f32 v[30:31], v[200:201], v[192:193], v[30:31] op_sel_hi:[0,1,1]
	v_pk_fma_f32 v[18:19], v[200:201], v[192:193], v[18:19] op_sel:[1,0,0]
	v_pk_fma_f32 v[56:57], v[198:199], v[194:195], v[56:57] op_sel_hi:[0,1,1]
	v_pk_fma_f32 v[36:37], v[198:199], v[194:195], v[36:37] op_sel:[1,0,0]
	v_pk_fma_f32 v[20:21], v[200:201], v[194:195], v[20:21] op_sel_hi:[0,1,1]
	v_pk_fma_f32 v[12:13], v[200:201], v[194:195], v[12:13] op_sel:[1,0,0]
	v_pk_fma_f32 v[58:59], v[198:199], v[196:197], v[58:59] op_sel_hi:[0,1,1]
	v_pk_fma_f32 v[38:39], v[198:199], v[196:197], v[38:39] op_sel:[1,0,0]
	v_pk_fma_f32 v[22:23], v[200:201], v[196:197], v[22:23] op_sel_hi:[0,1,1]
	v_pk_fma_f32 v[14:15], v[200:201], v[196:197], v[14:15] op_sel:[1,0,0]
	s_waitcnt lgkmcnt(4)
	v_pk_mul_f32 v[202:203], v[72:73], v[92:93]
	v_pk_mul_f32 v[204:205], v[74:75], v[94:95]
	v_pk_mul_f32 v[206:207], v[60:61], v[92:93]
	v_pk_mul_f32 v[208:209], v[62:63], v[94:95]
	v_pk_mul_f32 v[210:211], v[48:49], v[92:93]
	v_pk_mul_f32 v[212:213], v[50:51], v[94:95]
	v_pk_mul_f32 v[214:215], v[32:33], v[92:93]
	v_pk_mul_f32 v[216:217], v[34:35], v[94:95]
	v_pk_fma_f32 v[202:203], v[68:69], v[96:97], v[202:203]
	v_pk_fma_f32 v[204:205], v[70:71], v[98:99], v[204:205]
	v_pk_fma_f32 v[206:207], v[52:53], v[96:97], v[206:207]
	v_pk_fma_f32 v[208:209], v[54:55], v[98:99], v[208:209]
	v_pk_fma_f32 v[210:211], v[40:41], v[96:97], v[210:211]
	v_pk_fma_f32 v[212:213], v[42:43], v[98:99], v[212:213]
	v_pk_fma_f32 v[214:215], v[24:25], v[96:97], v[214:215]
	v_pk_fma_f32 v[216:217], v[26:27], v[98:99], v[216:217]
	v_pk_fma_f32 v[202:203], v[64:65], v[100:101], v[202:203]
	v_pk_fma_f32 v[204:205], v[66:67], v[102:103], v[204:205]
	v_pk_fma_f32 v[206:207], v[44:45], v[100:101], v[206:207]
	v_pk_fma_f32 v[208:209], v[46:47], v[102:103], v[208:209]
	v_pk_fma_f32 v[210:211], v[28:29], v[100:101], v[210:211]
	v_pk_fma_f32 v[212:213], v[30:31], v[102:103], v[212:213]
	v_pk_fma_f32 v[214:215], v[16:17], v[100:101], v[214:215]
	v_pk_fma_f32 v[216:217], v[18:19], v[102:103], v[216:217]
	v_pk_fma_f32 v[202:203], v[56:57], v[104:105], v[202:203]
	v_pk_fma_f32 v[204:205], v[58:59], v[106:107], v[204:205]
	v_pk_fma_f32 v[206:207], v[36:37], v[104:105], v[206:207]
	v_pk_fma_f32 v[208:209], v[38:39], v[106:107], v[208:209]
	v_pk_fma_f32 v[210:211], v[20:21], v[104:105], v[210:211]
	v_pk_fma_f32 v[212:213], v[22:23], v[106:107], v[212:213]
	v_pk_fma_f32 v[214:215], v[12:13], v[104:105], v[214:215]
	v_pk_fma_f32 v[216:217], v[14:15], v[106:107], v[216:217]
	v_pk_add_f32 v[202:203], v[202:203], v[204:205]
	v_pk_add_f32 v[206:207], v[206:207], v[208:209]
	v_pk_add_f32 v[210:211], v[210:211], v[212:213]
	v_pk_add_f32 v[214:215], v[214:215], v[216:217]
	ds_read_b128 v[92:95], v219 offset:256
	v_add_f32_e32 v202, v202, v203
	v_add_f32_e32 v206, v206, v207
	v_add_f32_e32 v210, v210, v211
	v_add_f32_e32 v214, v214, v215
	ds_read_b128 v[96:99], v219 offset:272
	v_add_f32_dpp v202, v202, v202 quad_perm:[1,0,3,2] row_mask:0xf bank_mask:0xf bound_ctrl:1
	v_add_f32_dpp v206, v206, v206 quad_perm:[1,0,3,2] row_mask:0xf bank_mask:0xf bound_ctrl:1
	v_add_f32_dpp v210, v210, v210 quad_perm:[1,0,3,2] row_mask:0xf bank_mask:0xf bound_ctrl:1
	v_add_f32_dpp v214, v214, v214 quad_perm:[1,0,3,2] row_mask:0xf bank_mask:0xf bound_ctrl:1
	ds_read_b128 v[100:103], v219 offset:288
	v_add_f32_dpp v202, v202, v202 quad_perm:[2,3,0,1] row_mask:0xf bank_mask:0xf bound_ctrl:1
	v_add_f32_dpp v206, v206, v206 quad_perm:[2,3,0,1] row_mask:0xf bank_mask:0xf bound_ctrl:1
	v_add_f32_dpp v210, v210, v210 quad_perm:[2,3,0,1] row_mask:0xf bank_mask:0xf bound_ctrl:1
	v_add_f32_dpp v214, v214, v214 quad_perm:[2,3,0,1] row_mask:0xf bank_mask:0xf bound_ctrl:1
	ds_read_b128 v[104:107], v219 offset:304
	ds_read_b128 v[108:111], v219 offset:512
	v_cvt_pk_bf16_f32 v240, v202, v206
	v_cvt_pk_bf16_f32 v241, v210, v214
	ds_read_b128 v[170:173], v219 offset:528
	ds_read_b128 v[174:177], v219 offset:544
	s_mov_b64 exec, s[6:7]
	global_store_dwordx2 v[238:239], v[240:241], off
	s_mov_b64 exec, -1
	ds_read_b128 v[178:181], v219 offset:560
	ds_read_b128 v[198:201], v223 offset:1280
	v_lshl_add_u64 v[238:239], v[238:239], 0, s[80:81]
	s_waitcnt lgkmcnt(9)
	ds_read_b128 v[182:185], v219 offset:768
	ds_read_b128 v[186:189], v219 offset:784
	ds_read_b128 v[190:193], v219 offset:800
	ds_read_b128 v[194:197], v219 offset:816
	v_pk_mul_f32 v[202:203], v[72:73], v[76:77]
	v_pk_mul_f32 v[204:205], v[74:75], v[78:79]
	v_pk_mul_f32 v[206:207], v[60:61], v[76:77]
	v_pk_mul_f32 v[208:209], v[62:63], v[78:79]
	v_pk_mul_f32 v[210:211], v[48:49], v[76:77]
	v_pk_mul_f32 v[212:213], v[50:51], v[78:79]
	v_pk_mul_f32 v[214:215], v[32:33], v[76:77]
	v_pk_mul_f32 v[216:217], v[34:35], v[78:79]
	v_pk_fma_f32 v[202:203], v[68:69], v[80:81], v[202:203]
	v_pk_fma_f32 v[204:205], v[70:71], v[82:83], v[204:205]
	v_pk_fma_f32 v[206:207], v[52:53], v[80:81], v[206:207]
	v_pk_fma_f32 v[208:209], v[54:55], v[82:83], v[208:209]
	v_pk_fma_f32 v[210:211], v[40:41], v[80:81], v[210:211]
	v_pk_fma_f32 v[212:213], v[42:43], v[82:83], v[212:213]
	v_pk_fma_f32 v[214:215], v[24:25], v[80:81], v[214:215]
	v_pk_fma_f32 v[216:217], v[26:27], v[82:83], v[216:217]
	v_pk_fma_f32 v[202:203], v[64:65], v[84:85], v[202:203]
	v_pk_fma_f32 v[204:205], v[66:67], v[86:87], v[204:205]
	v_pk_fma_f32 v[206:207], v[44:45], v[84:85], v[206:207]
	v_pk_fma_f32 v[208:209], v[46:47], v[86:87], v[208:209]
	v_pk_fma_f32 v[210:211], v[28:29], v[84:85], v[210:211]
	v_pk_fma_f32 v[212:213], v[30:31], v[86:87], v[212:213]
	v_pk_fma_f32 v[214:215], v[16:17], v[84:85], v[214:215]
	v_pk_fma_f32 v[216:217], v[18:19], v[86:87], v[216:217]
	v_pk_fma_f32 v[202:203], v[56:57], v[88:89], v[202:203]
	v_pk_fma_f32 v[204:205], v[58:59], v[90:91], v[204:205]
	v_pk_fma_f32 v[206:207], v[36:37], v[88:89], v[206:207]
	v_pk_fma_f32 v[208:209], v[38:39], v[90:91], v[208:209]
	v_pk_fma_f32 v[210:211], v[20:21], v[88:89], v[210:211]
	v_pk_fma_f32 v[212:213], v[22:23], v[90:91], v[212:213]
	v_pk_fma_f32 v[214:215], v[12:13], v[88:89], v[214:215]
	v_pk_fma_f32 v[216:217], v[14:15], v[90:91], v[216:217]
	s_waitcnt lgkmcnt(5)
	v_pk_add_f32 v[202:203], v[202:203], v[204:205]
	v_pk_add_f32 v[206:207], v[206:207], v[208:209]
	v_pk_add_f32 v[210:211], v[210:211], v[212:213]
	v_pk_add_f32 v[214:215], v[214:215], v[216:217]
	v_add_f32_e32 v202, v202, v203
	v_add_f32_e32 v206, v206, v207
	v_add_f32_e32 v210, v210, v211
	v_add_f32_e32 v214, v214, v215
	v_add_f32_dpp v202, v202, v202 quad_perm:[1,0,3,2] row_mask:0xf bank_mask:0xf bound_ctrl:1
	v_add_f32_dpp v206, v206, v206 quad_perm:[1,0,3,2] row_mask:0xf bank_mask:0xf bound_ctrl:1
	v_add_f32_dpp v210, v210, v210 quad_perm:[1,0,3,2] row_mask:0xf bank_mask:0xf bound_ctrl:1
	v_add_f32_dpp v214, v214, v214 quad_perm:[1,0,3,2] row_mask:0xf bank_mask:0xf bound_ctrl:1
	v_add_f32_dpp v202, v202, v202 quad_perm:[2,3,0,1] row_mask:0xf bank_mask:0xf bound_ctrl:1
	v_add_f32_dpp v206, v206, v206 quad_perm:[2,3,0,1] row_mask:0xf bank_mask:0xf bound_ctrl:1
	v_add_f32_dpp v210, v210, v210 quad_perm:[2,3,0,1] row_mask:0xf bank_mask:0xf bound_ctrl:1
	v_add_f32_dpp v214, v214, v214 quad_perm:[2,3,0,1] row_mask:0xf bank_mask:0xf bound_ctrl:1
	v_pk_mul_f32 v[204:205], v[108:109], v[202:203] op_sel_hi:[1,0]
	v_pk_mul_f32 v[208:209], v[108:109], v[206:207] op_sel_hi:[1,0]
	v_pk_mul_f32 v[212:213], v[108:109], v[210:211] op_sel_hi:[1,0]
	v_pk_mul_f32 v[108:109], v[108:109], v[214:215] op_sel_hi:[1,0]
	v_pk_fma_f32 v[72:73], v[72:73], v[92:93], v[204:205]
	v_pk_fma_f32 v[60:61], v[60:61], v[92:93], v[208:209]
	v_pk_fma_f32 v[48:49], v[48:49], v[92:93], v[212:213]
	v_pk_fma_f32 v[32:33], v[32:33], v[92:93], v[108:109]
	v_pk_mul_f32 v[216:217], v[110:111], v[202:203] op_sel_hi:[1,0]
	v_pk_mul_f32 v[242:243], v[110:111], v[206:207] op_sel_hi:[1,0]
	v_pk_mul_f32 v[244:245], v[110:111], v[210:211] op_sel_hi:[1,0]
	v_pk_mul_f32 v[110:111], v[110:111], v[214:215] op_sel_hi:[1,0]
	v_pk_fma_f32 v[74:75], v[74:75], v[94:95], v[216:217]
	v_pk_fma_f32 v[62:63], v[62:63], v[94:95], v[242:243]
	v_pk_fma_f32 v[50:51], v[50:51], v[94:95], v[244:245]
	v_pk_fma_f32 v[34:35], v[34:35], v[94:95], v[110:111]
	v_pk_mul_f32 v[204:205], v[170:171], v[202:203] op_sel_hi:[1,0]
	v_pk_mul_f32 v[208:209], v[170:171], v[206:207] op_sel_hi:[1,0]
	v_pk_mul_f32 v[212:213], v[170:171], v[210:211] op_sel_hi:[1,0]
	v_pk_mul_f32 v[170:171], v[170:171], v[214:215] op_sel_hi:[1,0]
	v_pk_fma_f32 v[68:69], v[68:69], v[96:97], v[204:205]
	v_pk_fma_f32 v[52:53], v[52:53], v[96:97], v[208:209]
	v_pk_fma_f32 v[40:41], v[40:41], v[96:97], v[212:213]
	v_pk_fma_f32 v[24:25], v[24:25], v[96:97], v[170:171]
	v_pk_mul_f32 v[216:217], v[172:173], v[202:203] op_sel_hi:[1,0]
	v_pk_mul_f32 v[242:243], v[172:173], v[206:207] op_sel_hi:[1,0]
	v_pk_mul_f32 v[244:245], v[172:173], v[210:211] op_sel_hi:[1,0]
	v_pk_mul_f32 v[172:173], v[172:173], v[214:215] op_sel_hi:[1,0]
	v_pk_fma_f32 v[70:71], v[70:71], v[98:99], v[216:217]
	v_pk_fma_f32 v[54:55], v[54:55], v[98:99], v[242:243]
	v_pk_fma_f32 v[42:43], v[42:43], v[98:99], v[244:245]
	v_pk_fma_f32 v[26:27], v[26:27], v[98:99], v[172:173]
	v_pk_mul_f32 v[204:205], v[174:175], v[202:203] op_sel_hi:[1,0]
	v_pk_mul_f32 v[208:209], v[174:175], v[206:207] op_sel_hi:[1,0]
	v_pk_mul_f32 v[212:213], v[174:175], v[210:211] op_sel_hi:[1,0]
	v_pk_mul_f32 v[174:175], v[174:175], v[214:215] op_sel_hi:[1,0]
	v_pk_fma_f32 v[64:65], v[64:65], v[100:101], v[204:205]
	v_pk_fma_f32 v[44:45], v[44:45], v[100:101], v[208:209]
	v_pk_fma_f32 v[28:29], v[28:29], v[100:101], v[212:213]
	v_pk_fma_f32 v[16:17], v[16:17], v[100:101], v[174:175]
	v_pk_mul_f32 v[216:217], v[176:177], v[202:203] op_sel_hi:[1,0]
	v_pk_mul_f32 v[242:243], v[176:177], v[206:207] op_sel_hi:[1,0]
	v_pk_mul_f32 v[244:245], v[176:177], v[210:211] op_sel_hi:[1,0]
	v_pk_mul_f32 v[176:177], v[176:177], v[214:215] op_sel_hi:[1,0]
	v_pk_fma_f32 v[66:67], v[66:67], v[102:103], v[216:217]
	v_pk_fma_f32 v[46:47], v[46:47], v[102:103], v[242:243]
	v_pk_fma_f32 v[30:31], v[30:31], v[102:103], v[244:245]
	v_pk_fma_f32 v[18:19], v[18:19], v[102:103], v[176:177]
	v_pk_mul_f32 v[204:205], v[178:179], v[202:203] op_sel_hi:[1,0]
	v_pk_mul_f32 v[208:209], v[178:179], v[206:207] op_sel_hi:[1,0]
	v_pk_mul_f32 v[212:213], v[178:179], v[210:211] op_sel_hi:[1,0]
	v_pk_mul_f32 v[178:179], v[178:179], v[214:215] op_sel_hi:[1,0]
	v_pk_fma_f32 v[56:57], v[56:57], v[104:105], v[204:205]
	v_pk_fma_f32 v[36:37], v[36:37], v[104:105], v[208:209]
	v_pk_fma_f32 v[20:21], v[20:21], v[104:105], v[212:213]
	v_pk_fma_f32 v[12:13], v[12:13], v[104:105], v[178:179]
	v_pk_mul_f32 v[216:217], v[180:181], v[202:203] op_sel_hi:[1,0]
	v_pk_mul_f32 v[242:243], v[180:181], v[206:207] op_sel_hi:[1,0]
	v_pk_mul_f32 v[244:245], v[180:181], v[210:211] op_sel_hi:[1,0]
	v_pk_mul_f32 v[180:181], v[180:181], v[214:215] op_sel_hi:[1,0]
	v_pk_fma_f32 v[58:59], v[58:59], v[106:107], v[216:217]
	v_pk_fma_f32 v[38:39], v[38:39], v[106:107], v[242:243]
	v_pk_fma_f32 v[22:23], v[22:23], v[106:107], v[244:245]
	v_pk_fma_f32 v[14:15], v[14:15], v[106:107], v[180:181]
	ds_read_b128 v[92:95], v219 offset:1024
	ds_read_b128 v[96:99], v219 offset:1040
	ds_read_b128 v[100:103], v219 offset:1056
	ds_read_b128 v[104:107], v219 offset:1072
	ds_read_b128 v[76:79], v220 offset:0
	ds_read_b128 v[80:83], v220 offset:16
	ds_read_b128 v[84:87], v220 offset:32
	ds_read_b128 v[88:91], v220 offset:48
	s_waitcnt lgkmcnt(8)
	v_pk_fma_f32 v[72:73], v[198:199], v[182:183], v[72:73] op_sel_hi:[0,1,1]
	v_pk_fma_f32 v[60:61], v[198:199], v[182:183], v[60:61] op_sel:[1,0,0]
	v_pk_fma_f32 v[48:49], v[200:201], v[182:183], v[48:49] op_sel_hi:[0,1,1]
	v_pk_fma_f32 v[32:33], v[200:201], v[182:183], v[32:33] op_sel:[1,0,0]
	v_pk_fma_f32 v[74:75], v[198:199], v[184:185], v[74:75] op_sel_hi:[0,1,1]
	v_pk_fma_f32 v[62:63], v[198:199], v[184:185], v[62:63] op_sel:[1,0,0]
	v_pk_fma_f32 v[50:51], v[200:201], v[184:185], v[50:51] op_sel_hi:[0,1,1]
	v_pk_fma_f32 v[34:35], v[200:201], v[184:185], v[34:35] op_sel:[1,0,0]
	v_pk_fma_f32 v[68:69], v[198:199], v[186:187], v[68:69] op_sel_hi:[0,1,1]
	v_pk_fma_f32 v[52:53], v[198:199], v[186:187], v[52:53] op_sel:[1,0,0]
	v_pk_fma_f32 v[40:41], v[200:201], v[186:187], v[40:41] op_sel_hi:[0,1,1]
	v_pk_fma_f32 v[24:25], v[200:201], v[186:187], v[24:25] op_sel:[1,0,0]
	v_pk_fma_f32 v[70:71], v[198:199], v[188:189], v[70:71] op_sel_hi:[0,1,1]
	v_pk_fma_f32 v[54:55], v[198:199], v[188:189], v[54:55] op_sel:[1,0,0]
	v_pk_fma_f32 v[42:43], v[200:201], v[188:189], v[42:43] op_sel_hi:[0,1,1]
	v_pk_fma_f32 v[26:27], v[200:201], v[188:189], v[26:27] op_sel:[1,0,0]
	v_pk_fma_f32 v[64:65], v[198:199], v[190:191], v[64:65] op_sel_hi:[0,1,1]
	v_pk_fma_f32 v[44:45], v[198:199], v[190:191], v[44:45] op_sel:[1,0,0]
	v_pk_fma_f32 v[28:29], v[200:201], v[190:191], v[28:29] op_sel_hi:[0,1,1]
	v_pk_fma_f32 v[16:17], v[200:201], v[190:191], v[16:17] op_sel:[1,0,0]
	v_pk_fma_f32 v[66:67], v[198:199], v[192:193], v[66:67] op_sel_hi:[0,1,1]
	v_pk_fma_f32 v[46:47], v[198:199], v[192:193], v[46:47] op_sel:[1,0,0]
	v_pk_fma_f32 v[30:31], v[200:201], v[192:193], v[30:31] op_sel_hi:[0,1,1]
	v_pk_fma_f32 v[18:19], v[200:201], v[192:193], v[18:19] op_sel:[1,0,0]
	v_pk_fma_f32 v[56:57], v[198:199], v[194:195], v[56:57] op_sel_hi:[0,1,1]
	v_pk_fma_f32 v[36:37], v[198:199], v[194:195], v[36:37] op_sel:[1,0,0]
	v_pk_fma_f32 v[20:21], v[200:201], v[194:195], v[20:21] op_sel_hi:[0,1,1]
	v_pk_fma_f32 v[12:13], v[200:201], v[194:195], v[12:13] op_sel:[1,0,0]
	v_pk_fma_f32 v[58:59], v[198:199], v[196:197], v[58:59] op_sel_hi:[0,1,1]
	v_pk_fma_f32 v[38:39], v[198:199], v[196:197], v[38:39] op_sel:[1,0,0]
	v_pk_fma_f32 v[22:23], v[200:201], v[196:197], v[22:23] op_sel_hi:[0,1,1]
	v_pk_fma_f32 v[14:15], v[200:201], v[196:197], v[14:15] op_sel:[1,0,0]
	s_waitcnt lgkmcnt(4)
	v_pk_mul_f32 v[202:203], v[72:73], v[92:93]
	v_pk_mul_f32 v[204:205], v[74:75], v[94:95]
	v_pk_mul_f32 v[206:207], v[60:61], v[92:93]
	v_pk_mul_f32 v[208:209], v[62:63], v[94:95]
	v_pk_mul_f32 v[210:211], v[48:49], v[92:93]
	v_pk_mul_f32 v[212:213], v[50:51], v[94:95]
	v_pk_mul_f32 v[214:215], v[32:33], v[92:93]
	v_pk_mul_f32 v[216:217], v[34:35], v[94:95]
	v_pk_fma_f32 v[202:203], v[68:69], v[96:97], v[202:203]
	v_pk_fma_f32 v[204:205], v[70:71], v[98:99], v[204:205]
	v_pk_fma_f32 v[206:207], v[52:53], v[96:97], v[206:207]
	v_pk_fma_f32 v[208:209], v[54:55], v[98:99], v[208:209]
	v_pk_fma_f32 v[210:211], v[40:41], v[96:97], v[210:211]
	v_pk_fma_f32 v[212:213], v[42:43], v[98:99], v[212:213]
	v_pk_fma_f32 v[214:215], v[24:25], v[96:97], v[214:215]
	v_pk_fma_f32 v[216:217], v[26:27], v[98:99], v[216:217]
	v_pk_fma_f32 v[202:203], v[64:65], v[100:101], v[202:203]
	v_pk_fma_f32 v[204:205], v[66:67], v[102:103], v[204:205]
	v_pk_fma_f32 v[206:207], v[44:45], v[100:101], v[206:207]
	v_pk_fma_f32 v[208:209], v[46:47], v[102:103], v[208:209]
	v_pk_fma_f32 v[210:211], v[28:29], v[100:101], v[210:211]
	v_pk_fma_f32 v[212:213], v[30:31], v[102:103], v[212:213]
	v_pk_fma_f32 v[214:215], v[16:17], v[100:101], v[214:215]
	v_pk_fma_f32 v[216:217], v[18:19], v[102:103], v[216:217]
	v_pk_fma_f32 v[202:203], v[56:57], v[104:105], v[202:203]
	v_pk_fma_f32 v[204:205], v[58:59], v[106:107], v[204:205]
	v_pk_fma_f32 v[206:207], v[36:37], v[104:105], v[206:207]
	v_pk_fma_f32 v[208:209], v[38:39], v[106:107], v[208:209]
	v_pk_fma_f32 v[210:211], v[20:21], v[104:105], v[210:211]
	v_pk_fma_f32 v[212:213], v[22:23], v[106:107], v[212:213]
	v_pk_fma_f32 v[214:215], v[12:13], v[104:105], v[214:215]
	v_pk_fma_f32 v[216:217], v[14:15], v[106:107], v[216:217]
	v_pk_add_f32 v[202:203], v[202:203], v[204:205]
	v_pk_add_f32 v[206:207], v[206:207], v[208:209]
	v_pk_add_f32 v[210:211], v[210:211], v[212:213]
	v_pk_add_f32 v[214:215], v[214:215], v[216:217]
	ds_read_b128 v[92:95], v220 offset:256
	v_add_f32_e32 v202, v202, v203
	v_add_f32_e32 v206, v206, v207
	v_add_f32_e32 v210, v210, v211
	v_add_f32_e32 v214, v214, v215
	ds_read_b128 v[96:99], v220 offset:272
	v_add_f32_dpp v202, v202, v202 quad_perm:[1,0,3,2] row_mask:0xf bank_mask:0xf bound_ctrl:1
	v_add_f32_dpp v206, v206, v206 quad_perm:[1,0,3,2] row_mask:0xf bank_mask:0xf bound_ctrl:1
	v_add_f32_dpp v210, v210, v210 quad_perm:[1,0,3,2] row_mask:0xf bank_mask:0xf bound_ctrl:1
	v_add_f32_dpp v214, v214, v214 quad_perm:[1,0,3,2] row_mask:0xf bank_mask:0xf bound_ctrl:1
	ds_read_b128 v[100:103], v220 offset:288
	v_add_f32_dpp v202, v202, v202 quad_perm:[2,3,0,1] row_mask:0xf bank_mask:0xf bound_ctrl:1
	v_add_f32_dpp v206, v206, v206 quad_perm:[2,3,0,1] row_mask:0xf bank_mask:0xf bound_ctrl:1
	v_add_f32_dpp v210, v210, v210 quad_perm:[2,3,0,1] row_mask:0xf bank_mask:0xf bound_ctrl:1
	v_add_f32_dpp v214, v214, v214 quad_perm:[2,3,0,1] row_mask:0xf bank_mask:0xf bound_ctrl:1
	ds_read_b128 v[104:107], v220 offset:304
	ds_read_b128 v[108:111], v220 offset:512
	v_cvt_pk_bf16_f32 v240, v202, v206
	v_cvt_pk_bf16_f32 v241, v210, v214
	ds_read_b128 v[170:173], v220 offset:528
	ds_read_b128 v[174:177], v220 offset:544
	s_mov_b64 exec, s[6:7]
	global_store_dwordx2 v[238:239], v[240:241], off
	s_mov_b64 exec, -1
	ds_read_b128 v[178:181], v220 offset:560
	ds_read_b128 v[198:201], v236 offset:1280
	v_lshl_add_u64 v[238:239], v[238:239], 0, s[80:81]
	s_waitcnt lgkmcnt(9)
	ds_read_b128 v[182:185], v220 offset:768
	ds_read_b128 v[186:189], v220 offset:784
	ds_read_b128 v[190:193], v220 offset:800
	ds_read_b128 v[194:197], v220 offset:816
	v_pk_mul_f32 v[202:203], v[72:73], v[76:77]
	v_pk_mul_f32 v[204:205], v[74:75], v[78:79]
	v_pk_mul_f32 v[206:207], v[60:61], v[76:77]
	v_pk_mul_f32 v[208:209], v[62:63], v[78:79]
	v_pk_mul_f32 v[210:211], v[48:49], v[76:77]
	v_pk_mul_f32 v[212:213], v[50:51], v[78:79]
	v_pk_mul_f32 v[214:215], v[32:33], v[76:77]
	v_pk_mul_f32 v[216:217], v[34:35], v[78:79]
	v_pk_fma_f32 v[202:203], v[68:69], v[80:81], v[202:203]
	v_pk_fma_f32 v[204:205], v[70:71], v[82:83], v[204:205]
	v_pk_fma_f32 v[206:207], v[52:53], v[80:81], v[206:207]
	v_pk_fma_f32 v[208:209], v[54:55], v[82:83], v[208:209]
	v_pk_fma_f32 v[210:211], v[40:41], v[80:81], v[210:211]
	v_pk_fma_f32 v[212:213], v[42:43], v[82:83], v[212:213]
	v_pk_fma_f32 v[214:215], v[24:25], v[80:81], v[214:215]
	v_pk_fma_f32 v[216:217], v[26:27], v[82:83], v[216:217]
	v_pk_fma_f32 v[202:203], v[64:65], v[84:85], v[202:203]
	v_pk_fma_f32 v[204:205], v[66:67], v[86:87], v[204:205]
	v_pk_fma_f32 v[206:207], v[44:45], v[84:85], v[206:207]
	v_pk_fma_f32 v[208:209], v[46:47], v[86:87], v[208:209]
	v_pk_fma_f32 v[210:211], v[28:29], v[84:85], v[210:211]
	v_pk_fma_f32 v[212:213], v[30:31], v[86:87], v[212:213]
	v_pk_fma_f32 v[214:215], v[16:17], v[84:85], v[214:215]
	v_pk_fma_f32 v[216:217], v[18:19], v[86:87], v[216:217]
	v_pk_fma_f32 v[202:203], v[56:57], v[88:89], v[202:203]
	v_pk_fma_f32 v[204:205], v[58:59], v[90:91], v[204:205]
	v_pk_fma_f32 v[206:207], v[36:37], v[88:89], v[206:207]
	v_pk_fma_f32 v[208:209], v[38:39], v[90:91], v[208:209]
	v_pk_fma_f32 v[210:211], v[20:21], v[88:89], v[210:211]
	v_pk_fma_f32 v[212:213], v[22:23], v[90:91], v[212:213]
	v_pk_fma_f32 v[214:215], v[12:13], v[88:89], v[214:215]
	v_pk_fma_f32 v[216:217], v[14:15], v[90:91], v[216:217]
	s_waitcnt lgkmcnt(5)
	v_pk_add_f32 v[202:203], v[202:203], v[204:205]
	v_pk_add_f32 v[206:207], v[206:207], v[208:209]
	v_pk_add_f32 v[210:211], v[210:211], v[212:213]
	v_pk_add_f32 v[214:215], v[214:215], v[216:217]
	v_add_f32_e32 v202, v202, v203
	v_add_f32_e32 v206, v206, v207
	v_add_f32_e32 v210, v210, v211
	v_add_f32_e32 v214, v214, v215
	v_add_f32_dpp v202, v202, v202 quad_perm:[1,0,3,2] row_mask:0xf bank_mask:0xf bound_ctrl:1
	v_add_f32_dpp v206, v206, v206 quad_perm:[1,0,3,2] row_mask:0xf bank_mask:0xf bound_ctrl:1
	v_add_f32_dpp v210, v210, v210 quad_perm:[1,0,3,2] row_mask:0xf bank_mask:0xf bound_ctrl:1
	v_add_f32_dpp v214, v214, v214 quad_perm:[1,0,3,2] row_mask:0xf bank_mask:0xf bound_ctrl:1
	v_add_f32_dpp v202, v202, v202 quad_perm:[2,3,0,1] row_mask:0xf bank_mask:0xf bound_ctrl:1
	v_add_f32_dpp v206, v206, v206 quad_perm:[2,3,0,1] row_mask:0xf bank_mask:0xf bound_ctrl:1
	v_add_f32_dpp v210, v210, v210 quad_perm:[2,3,0,1] row_mask:0xf bank_mask:0xf bound_ctrl:1
	v_add_f32_dpp v214, v214, v214 quad_perm:[2,3,0,1] row_mask:0xf bank_mask:0xf bound_ctrl:1
	v_pk_mul_f32 v[204:205], v[108:109], v[202:203] op_sel_hi:[1,0]
	v_pk_mul_f32 v[208:209], v[108:109], v[206:207] op_sel_hi:[1,0]
	v_pk_mul_f32 v[212:213], v[108:109], v[210:211] op_sel_hi:[1,0]
	v_pk_mul_f32 v[108:109], v[108:109], v[214:215] op_sel_hi:[1,0]
	v_pk_fma_f32 v[72:73], v[72:73], v[92:93], v[204:205]
	v_pk_fma_f32 v[60:61], v[60:61], v[92:93], v[208:209]
	v_pk_fma_f32 v[48:49], v[48:49], v[92:93], v[212:213]
	v_pk_fma_f32 v[32:33], v[32:33], v[92:93], v[108:109]
	v_pk_mul_f32 v[216:217], v[110:111], v[202:203] op_sel_hi:[1,0]
	v_pk_mul_f32 v[242:243], v[110:111], v[206:207] op_sel_hi:[1,0]
	v_pk_mul_f32 v[244:245], v[110:111], v[210:211] op_sel_hi:[1,0]
	v_pk_mul_f32 v[110:111], v[110:111], v[214:215] op_sel_hi:[1,0]
	v_pk_fma_f32 v[74:75], v[74:75], v[94:95], v[216:217]
	v_pk_fma_f32 v[62:63], v[62:63], v[94:95], v[242:243]
	v_pk_fma_f32 v[50:51], v[50:51], v[94:95], v[244:245]
	v_pk_fma_f32 v[34:35], v[34:35], v[94:95], v[110:111]
	v_pk_mul_f32 v[204:205], v[170:171], v[202:203] op_sel_hi:[1,0]
	v_pk_mul_f32 v[208:209], v[170:171], v[206:207] op_sel_hi:[1,0]
	v_pk_mul_f32 v[212:213], v[170:171], v[210:211] op_sel_hi:[1,0]
	v_pk_mul_f32 v[170:171], v[170:171], v[214:215] op_sel_hi:[1,0]
	v_pk_fma_f32 v[68:69], v[68:69], v[96:97], v[204:205]
	v_pk_fma_f32 v[52:53], v[52:53], v[96:97], v[208:209]
	v_pk_fma_f32 v[40:41], v[40:41], v[96:97], v[212:213]
	v_pk_fma_f32 v[24:25], v[24:25], v[96:97], v[170:171]
	v_pk_mul_f32 v[216:217], v[172:173], v[202:203] op_sel_hi:[1,0]
	v_pk_mul_f32 v[242:243], v[172:173], v[206:207] op_sel_hi:[1,0]
	v_pk_mul_f32 v[244:245], v[172:173], v[210:211] op_sel_hi:[1,0]
	v_pk_mul_f32 v[172:173], v[172:173], v[214:215] op_sel_hi:[1,0]
	v_pk_fma_f32 v[70:71], v[70:71], v[98:99], v[216:217]
	v_pk_fma_f32 v[54:55], v[54:55], v[98:99], v[242:243]
	v_pk_fma_f32 v[42:43], v[42:43], v[98:99], v[244:245]
	v_pk_fma_f32 v[26:27], v[26:27], v[98:99], v[172:173]
	v_pk_mul_f32 v[204:205], v[174:175], v[202:203] op_sel_hi:[1,0]
	v_pk_mul_f32 v[208:209], v[174:175], v[206:207] op_sel_hi:[1,0]
	v_pk_mul_f32 v[212:213], v[174:175], v[210:211] op_sel_hi:[1,0]
	v_pk_mul_f32 v[174:175], v[174:175], v[214:215] op_sel_hi:[1,0]
	v_pk_fma_f32 v[64:65], v[64:65], v[100:101], v[204:205]
	v_pk_fma_f32 v[44:45], v[44:45], v[100:101], v[208:209]
	v_pk_fma_f32 v[28:29], v[28:29], v[100:101], v[212:213]
	v_pk_fma_f32 v[16:17], v[16:17], v[100:101], v[174:175]
	v_pk_mul_f32 v[216:217], v[176:177], v[202:203] op_sel_hi:[1,0]
	v_pk_mul_f32 v[242:243], v[176:177], v[206:207] op_sel_hi:[1,0]
	v_pk_mul_f32 v[244:245], v[176:177], v[210:211] op_sel_hi:[1,0]
	v_pk_mul_f32 v[176:177], v[176:177], v[214:215] op_sel_hi:[1,0]
	v_pk_fma_f32 v[66:67], v[66:67], v[102:103], v[216:217]
	v_pk_fma_f32 v[46:47], v[46:47], v[102:103], v[242:243]
	v_pk_fma_f32 v[30:31], v[30:31], v[102:103], v[244:245]
	v_pk_fma_f32 v[18:19], v[18:19], v[102:103], v[176:177]
	v_pk_mul_f32 v[204:205], v[178:179], v[202:203] op_sel_hi:[1,0]
	v_pk_mul_f32 v[208:209], v[178:179], v[206:207] op_sel_hi:[1,0]
	v_pk_mul_f32 v[212:213], v[178:179], v[210:211] op_sel_hi:[1,0]
	v_pk_mul_f32 v[178:179], v[178:179], v[214:215] op_sel_hi:[1,0]
	v_pk_fma_f32 v[56:57], v[56:57], v[104:105], v[204:205]
	v_pk_fma_f32 v[36:37], v[36:37], v[104:105], v[208:209]
	v_pk_fma_f32 v[20:21], v[20:21], v[104:105], v[212:213]
	v_pk_fma_f32 v[12:13], v[12:13], v[104:105], v[178:179]
	v_pk_mul_f32 v[216:217], v[180:181], v[202:203] op_sel_hi:[1,0]
	v_pk_mul_f32 v[242:243], v[180:181], v[206:207] op_sel_hi:[1,0]
	v_pk_mul_f32 v[244:245], v[180:181], v[210:211] op_sel_hi:[1,0]
	v_pk_mul_f32 v[180:181], v[180:181], v[214:215] op_sel_hi:[1,0]
	v_pk_fma_f32 v[58:59], v[58:59], v[106:107], v[216:217]
	v_pk_fma_f32 v[38:39], v[38:39], v[106:107], v[242:243]
	v_pk_fma_f32 v[22:23], v[22:23], v[106:107], v[244:245]
	v_pk_fma_f32 v[14:15], v[14:15], v[106:107], v[180:181]
	ds_read_b128 v[92:95], v220 offset:1024
	ds_read_b128 v[96:99], v220 offset:1040
	ds_read_b128 v[100:103], v220 offset:1056
	ds_read_b128 v[104:107], v220 offset:1072
	ds_read_b128 v[76:79], v221 offset:0
	ds_read_b128 v[80:83], v221 offset:16
	ds_read_b128 v[84:87], v221 offset:32
	ds_read_b128 v[88:91], v221 offset:48
	s_waitcnt lgkmcnt(8)
	v_pk_fma_f32 v[72:73], v[198:199], v[182:183], v[72:73] op_sel_hi:[0,1,1]
	v_pk_fma_f32 v[60:61], v[198:199], v[182:183], v[60:61] op_sel:[1,0,0]
	v_pk_fma_f32 v[48:49], v[200:201], v[182:183], v[48:49] op_sel_hi:[0,1,1]
	v_pk_fma_f32 v[32:33], v[200:201], v[182:183], v[32:33] op_sel:[1,0,0]
	v_pk_fma_f32 v[74:75], v[198:199], v[184:185], v[74:75] op_sel_hi:[0,1,1]
	v_pk_fma_f32 v[62:63], v[198:199], v[184:185], v[62:63] op_sel:[1,0,0]
	v_pk_fma_f32 v[50:51], v[200:201], v[184:185], v[50:51] op_sel_hi:[0,1,1]
	v_pk_fma_f32 v[34:35], v[200:201], v[184:185], v[34:35] op_sel:[1,0,0]
	v_pk_fma_f32 v[68:69], v[198:199], v[186:187], v[68:69] op_sel_hi:[0,1,1]
	v_pk_fma_f32 v[52:53], v[198:199], v[186:187], v[52:53] op_sel:[1,0,0]
	v_pk_fma_f32 v[40:41], v[200:201], v[186:187], v[40:41] op_sel_hi:[0,1,1]
	v_pk_fma_f32 v[24:25], v[200:201], v[186:187], v[24:25] op_sel:[1,0,0]
	v_pk_fma_f32 v[70:71], v[198:199], v[188:189], v[70:71] op_sel_hi:[0,1,1]
	v_pk_fma_f32 v[54:55], v[198:199], v[188:189], v[54:55] op_sel:[1,0,0]
	v_pk_fma_f32 v[42:43], v[200:201], v[188:189], v[42:43] op_sel_hi:[0,1,1]
	v_pk_fma_f32 v[26:27], v[200:201], v[188:189], v[26:27] op_sel:[1,0,0]
	v_pk_fma_f32 v[64:65], v[198:199], v[190:191], v[64:65] op_sel_hi:[0,1,1]
	v_pk_fma_f32 v[44:45], v[198:199], v[190:191], v[44:45] op_sel:[1,0,0]
	v_pk_fma_f32 v[28:29], v[200:201], v[190:191], v[28:29] op_sel_hi:[0,1,1]
	v_pk_fma_f32 v[16:17], v[200:201], v[190:191], v[16:17] op_sel:[1,0,0]
	v_pk_fma_f32 v[66:67], v[198:199], v[192:193], v[66:67] op_sel_hi:[0,1,1]
	v_pk_fma_f32 v[46:47], v[198:199], v[192:193], v[46:47] op_sel:[1,0,0]
	v_pk_fma_f32 v[30:31], v[200:201], v[192:193], v[30:31] op_sel_hi:[0,1,1]
	v_pk_fma_f32 v[18:19], v[200:201], v[192:193], v[18:19] op_sel:[1,0,0]
	v_pk_fma_f32 v[56:57], v[198:199], v[194:195], v[56:57] op_sel_hi:[0,1,1]
	v_pk_fma_f32 v[36:37], v[198:199], v[194:195], v[36:37] op_sel:[1,0,0]
	v_pk_fma_f32 v[20:21], v[200:201], v[194:195], v[20:21] op_sel_hi:[0,1,1]
	v_pk_fma_f32 v[12:13], v[200:201], v[194:195], v[12:13] op_sel:[1,0,0]
	v_pk_fma_f32 v[58:59], v[198:199], v[196:197], v[58:59] op_sel_hi:[0,1,1]
	v_pk_fma_f32 v[38:39], v[198:199], v[196:197], v[38:39] op_sel:[1,0,0]
	v_pk_fma_f32 v[22:23], v[200:201], v[196:197], v[22:23] op_sel_hi:[0,1,1]
	v_pk_fma_f32 v[14:15], v[200:201], v[196:197], v[14:15] op_sel:[1,0,0]
	s_waitcnt lgkmcnt(4)
	v_pk_mul_f32 v[202:203], v[72:73], v[92:93]
	v_pk_mul_f32 v[204:205], v[74:75], v[94:95]
	v_pk_mul_f32 v[206:207], v[60:61], v[92:93]
	v_pk_mul_f32 v[208:209], v[62:63], v[94:95]
	v_pk_mul_f32 v[210:211], v[48:49], v[92:93]
	v_pk_mul_f32 v[212:213], v[50:51], v[94:95]
	v_pk_mul_f32 v[214:215], v[32:33], v[92:93]
	v_pk_mul_f32 v[216:217], v[34:35], v[94:95]
	v_pk_fma_f32 v[202:203], v[68:69], v[96:97], v[202:203]
	v_pk_fma_f32 v[204:205], v[70:71], v[98:99], v[204:205]
	v_pk_fma_f32 v[206:207], v[52:53], v[96:97], v[206:207]
	v_pk_fma_f32 v[208:209], v[54:55], v[98:99], v[208:209]
	v_pk_fma_f32 v[210:211], v[40:41], v[96:97], v[210:211]
	v_pk_fma_f32 v[212:213], v[42:43], v[98:99], v[212:213]
	v_pk_fma_f32 v[214:215], v[24:25], v[96:97], v[214:215]
	v_pk_fma_f32 v[216:217], v[26:27], v[98:99], v[216:217]
	v_pk_fma_f32 v[202:203], v[64:65], v[100:101], v[202:203]
	v_pk_fma_f32 v[204:205], v[66:67], v[102:103], v[204:205]
	v_pk_fma_f32 v[206:207], v[44:45], v[100:101], v[206:207]
	v_pk_fma_f32 v[208:209], v[46:47], v[102:103], v[208:209]
	v_pk_fma_f32 v[210:211], v[28:29], v[100:101], v[210:211]
	v_pk_fma_f32 v[212:213], v[30:31], v[102:103], v[212:213]
	v_pk_fma_f32 v[214:215], v[16:17], v[100:101], v[214:215]
	v_pk_fma_f32 v[216:217], v[18:19], v[102:103], v[216:217]
	v_pk_fma_f32 v[202:203], v[56:57], v[104:105], v[202:203]
	v_pk_fma_f32 v[204:205], v[58:59], v[106:107], v[204:205]
	v_pk_fma_f32 v[206:207], v[36:37], v[104:105], v[206:207]
	v_pk_fma_f32 v[208:209], v[38:39], v[106:107], v[208:209]
	v_pk_fma_f32 v[210:211], v[20:21], v[104:105], v[210:211]
	v_pk_fma_f32 v[212:213], v[22:23], v[106:107], v[212:213]
	v_pk_fma_f32 v[214:215], v[12:13], v[104:105], v[214:215]
	v_pk_fma_f32 v[216:217], v[14:15], v[106:107], v[216:217]
	v_pk_add_f32 v[202:203], v[202:203], v[204:205]
	v_pk_add_f32 v[206:207], v[206:207], v[208:209]
	v_pk_add_f32 v[210:211], v[210:211], v[212:213]
	v_pk_add_f32 v[214:215], v[214:215], v[216:217]
	ds_read_b128 v[92:95], v221 offset:256
	v_add_f32_e32 v202, v202, v203
	v_add_f32_e32 v206, v206, v207
	v_add_f32_e32 v210, v210, v211
	v_add_f32_e32 v214, v214, v215
	ds_read_b128 v[96:99], v221 offset:272
	v_add_f32_dpp v202, v202, v202 quad_perm:[1,0,3,2] row_mask:0xf bank_mask:0xf bound_ctrl:1
	v_add_f32_dpp v206, v206, v206 quad_perm:[1,0,3,2] row_mask:0xf bank_mask:0xf bound_ctrl:1
	v_add_f32_dpp v210, v210, v210 quad_perm:[1,0,3,2] row_mask:0xf bank_mask:0xf bound_ctrl:1
	v_add_f32_dpp v214, v214, v214 quad_perm:[1,0,3,2] row_mask:0xf bank_mask:0xf bound_ctrl:1
	ds_read_b128 v[100:103], v221 offset:288
	v_add_f32_dpp v202, v202, v202 quad_perm:[2,3,0,1] row_mask:0xf bank_mask:0xf bound_ctrl:1
	v_add_f32_dpp v206, v206, v206 quad_perm:[2,3,0,1] row_mask:0xf bank_mask:0xf bound_ctrl:1
	v_add_f32_dpp v210, v210, v210 quad_perm:[2,3,0,1] row_mask:0xf bank_mask:0xf bound_ctrl:1
	v_add_f32_dpp v214, v214, v214 quad_perm:[2,3,0,1] row_mask:0xf bank_mask:0xf bound_ctrl:1
	ds_read_b128 v[104:107], v221 offset:304
	ds_read_b128 v[108:111], v221 offset:512
	v_cvt_pk_bf16_f32 v240, v202, v206
	v_cvt_pk_bf16_f32 v241, v210, v214
	ds_read_b128 v[170:173], v221 offset:528
	ds_read_b128 v[174:177], v221 offset:544
	s_mov_b64 exec, s[6:7]
	global_store_dwordx2 v[238:239], v[240:241], off
	s_mov_b64 exec, -1
	ds_read_b128 v[178:181], v221 offset:560
	ds_read_b128 v[198:201], v237 offset:1280
	v_lshl_add_u64 v[238:239], v[238:239], 0, s[80:81]
	s_waitcnt lgkmcnt(9)
	ds_read_b128 v[182:185], v221 offset:768
	ds_read_b128 v[186:189], v221 offset:784
	ds_read_b128 v[190:193], v221 offset:800
	ds_read_b128 v[194:197], v221 offset:816
	v_pk_mul_f32 v[202:203], v[72:73], v[76:77]
	v_pk_mul_f32 v[204:205], v[74:75], v[78:79]
	v_pk_mul_f32 v[206:207], v[60:61], v[76:77]
	v_pk_mul_f32 v[208:209], v[62:63], v[78:79]
	v_pk_mul_f32 v[210:211], v[48:49], v[76:77]
	v_pk_mul_f32 v[212:213], v[50:51], v[78:79]
	v_pk_mul_f32 v[214:215], v[32:33], v[76:77]
	v_pk_mul_f32 v[216:217], v[34:35], v[78:79]
	v_pk_fma_f32 v[202:203], v[68:69], v[80:81], v[202:203]
	v_pk_fma_f32 v[204:205], v[70:71], v[82:83], v[204:205]
	v_pk_fma_f32 v[206:207], v[52:53], v[80:81], v[206:207]
	v_pk_fma_f32 v[208:209], v[54:55], v[82:83], v[208:209]
	v_pk_fma_f32 v[210:211], v[40:41], v[80:81], v[210:211]
	v_pk_fma_f32 v[212:213], v[42:43], v[82:83], v[212:213]
	v_pk_fma_f32 v[214:215], v[24:25], v[80:81], v[214:215]
	v_pk_fma_f32 v[216:217], v[26:27], v[82:83], v[216:217]
	v_pk_fma_f32 v[202:203], v[64:65], v[84:85], v[202:203]
	v_pk_fma_f32 v[204:205], v[66:67], v[86:87], v[204:205]
	v_pk_fma_f32 v[206:207], v[44:45], v[84:85], v[206:207]
	v_pk_fma_f32 v[208:209], v[46:47], v[86:87], v[208:209]
	v_pk_fma_f32 v[210:211], v[28:29], v[84:85], v[210:211]
	v_pk_fma_f32 v[212:213], v[30:31], v[86:87], v[212:213]
	v_pk_fma_f32 v[214:215], v[16:17], v[84:85], v[214:215]
	v_pk_fma_f32 v[216:217], v[18:19], v[86:87], v[216:217]
	v_pk_fma_f32 v[202:203], v[56:57], v[88:89], v[202:203]
	v_pk_fma_f32 v[204:205], v[58:59], v[90:91], v[204:205]
	v_pk_fma_f32 v[206:207], v[36:37], v[88:89], v[206:207]
	v_pk_fma_f32 v[208:209], v[38:39], v[90:91], v[208:209]
	v_pk_fma_f32 v[210:211], v[20:21], v[88:89], v[210:211]
	v_pk_fma_f32 v[212:213], v[22:23], v[90:91], v[212:213]
	v_pk_fma_f32 v[214:215], v[12:13], v[88:89], v[214:215]
	v_pk_fma_f32 v[216:217], v[14:15], v[90:91], v[216:217]
	s_waitcnt lgkmcnt(5)
	v_pk_add_f32 v[202:203], v[202:203], v[204:205]
	v_pk_add_f32 v[206:207], v[206:207], v[208:209]
	v_pk_add_f32 v[210:211], v[210:211], v[212:213]
	v_pk_add_f32 v[214:215], v[214:215], v[216:217]
	v_add_f32_e32 v202, v202, v203
	v_add_f32_e32 v206, v206, v207
	v_add_f32_e32 v210, v210, v211
	v_add_f32_e32 v214, v214, v215
	v_add_f32_dpp v202, v202, v202 quad_perm:[1,0,3,2] row_mask:0xf bank_mask:0xf bound_ctrl:1
	v_add_f32_dpp v206, v206, v206 quad_perm:[1,0,3,2] row_mask:0xf bank_mask:0xf bound_ctrl:1
	v_add_f32_dpp v210, v210, v210 quad_perm:[1,0,3,2] row_mask:0xf bank_mask:0xf bound_ctrl:1
	v_add_f32_dpp v214, v214, v214 quad_perm:[1,0,3,2] row_mask:0xf bank_mask:0xf bound_ctrl:1
	v_add_f32_dpp v202, v202, v202 quad_perm:[2,3,0,1] row_mask:0xf bank_mask:0xf bound_ctrl:1
	v_add_f32_dpp v206, v206, v206 quad_perm:[2,3,0,1] row_mask:0xf bank_mask:0xf bound_ctrl:1
	v_add_f32_dpp v210, v210, v210 quad_perm:[2,3,0,1] row_mask:0xf bank_mask:0xf bound_ctrl:1
	v_add_f32_dpp v214, v214, v214 quad_perm:[2,3,0,1] row_mask:0xf bank_mask:0xf bound_ctrl:1
	v_pk_mul_f32 v[204:205], v[108:109], v[202:203] op_sel_hi:[1,0]
	v_pk_mul_f32 v[208:209], v[108:109], v[206:207] op_sel_hi:[1,0]
	v_pk_mul_f32 v[212:213], v[108:109], v[210:211] op_sel_hi:[1,0]
	v_pk_mul_f32 v[108:109], v[108:109], v[214:215] op_sel_hi:[1,0]
	v_pk_fma_f32 v[72:73], v[72:73], v[92:93], v[204:205]
	v_pk_fma_f32 v[60:61], v[60:61], v[92:93], v[208:209]
	v_pk_fma_f32 v[48:49], v[48:49], v[92:93], v[212:213]
	v_pk_fma_f32 v[32:33], v[32:33], v[92:93], v[108:109]
	v_pk_mul_f32 v[216:217], v[110:111], v[202:203] op_sel_hi:[1,0]
	v_pk_mul_f32 v[242:243], v[110:111], v[206:207] op_sel_hi:[1,0]
	v_pk_mul_f32 v[244:245], v[110:111], v[210:211] op_sel_hi:[1,0]
	v_pk_mul_f32 v[110:111], v[110:111], v[214:215] op_sel_hi:[1,0]
	v_pk_fma_f32 v[74:75], v[74:75], v[94:95], v[216:217]
	v_pk_fma_f32 v[62:63], v[62:63], v[94:95], v[242:243]
	v_pk_fma_f32 v[50:51], v[50:51], v[94:95], v[244:245]
	v_pk_fma_f32 v[34:35], v[34:35], v[94:95], v[110:111]
	v_pk_mul_f32 v[204:205], v[170:171], v[202:203] op_sel_hi:[1,0]
	v_pk_mul_f32 v[208:209], v[170:171], v[206:207] op_sel_hi:[1,0]
	v_pk_mul_f32 v[212:213], v[170:171], v[210:211] op_sel_hi:[1,0]
	v_pk_mul_f32 v[170:171], v[170:171], v[214:215] op_sel_hi:[1,0]
	v_pk_fma_f32 v[68:69], v[68:69], v[96:97], v[204:205]
	v_pk_fma_f32 v[52:53], v[52:53], v[96:97], v[208:209]
	v_pk_fma_f32 v[40:41], v[40:41], v[96:97], v[212:213]
	v_pk_fma_f32 v[24:25], v[24:25], v[96:97], v[170:171]
	v_pk_mul_f32 v[216:217], v[172:173], v[202:203] op_sel_hi:[1,0]
	v_pk_mul_f32 v[242:243], v[172:173], v[206:207] op_sel_hi:[1,0]
	v_pk_mul_f32 v[244:245], v[172:173], v[210:211] op_sel_hi:[1,0]
	v_pk_mul_f32 v[172:173], v[172:173], v[214:215] op_sel_hi:[1,0]
	v_pk_fma_f32 v[70:71], v[70:71], v[98:99], v[216:217]
	v_pk_fma_f32 v[54:55], v[54:55], v[98:99], v[242:243]
	v_pk_fma_f32 v[42:43], v[42:43], v[98:99], v[244:245]
	v_pk_fma_f32 v[26:27], v[26:27], v[98:99], v[172:173]
	v_pk_mul_f32 v[204:205], v[174:175], v[202:203] op_sel_hi:[1,0]
	v_pk_mul_f32 v[208:209], v[174:175], v[206:207] op_sel_hi:[1,0]
	v_pk_mul_f32 v[212:213], v[174:175], v[210:211] op_sel_hi:[1,0]
	v_pk_mul_f32 v[174:175], v[174:175], v[214:215] op_sel_hi:[1,0]
	v_pk_fma_f32 v[64:65], v[64:65], v[100:101], v[204:205]
	v_pk_fma_f32 v[44:45], v[44:45], v[100:101], v[208:209]
	v_pk_fma_f32 v[28:29], v[28:29], v[100:101], v[212:213]
	v_pk_fma_f32 v[16:17], v[16:17], v[100:101], v[174:175]
	v_pk_mul_f32 v[216:217], v[176:177], v[202:203] op_sel_hi:[1,0]
	v_pk_mul_f32 v[242:243], v[176:177], v[206:207] op_sel_hi:[1,0]
	v_pk_mul_f32 v[244:245], v[176:177], v[210:211] op_sel_hi:[1,0]
	v_pk_mul_f32 v[176:177], v[176:177], v[214:215] op_sel_hi:[1,0]
	v_pk_fma_f32 v[66:67], v[66:67], v[102:103], v[216:217]
	v_pk_fma_f32 v[46:47], v[46:47], v[102:103], v[242:243]
	v_pk_fma_f32 v[30:31], v[30:31], v[102:103], v[244:245]
	v_pk_fma_f32 v[18:19], v[18:19], v[102:103], v[176:177]
	v_pk_mul_f32 v[204:205], v[178:179], v[202:203] op_sel_hi:[1,0]
	v_pk_mul_f32 v[208:209], v[178:179], v[206:207] op_sel_hi:[1,0]
	v_pk_mul_f32 v[212:213], v[178:179], v[210:211] op_sel_hi:[1,0]
	v_pk_mul_f32 v[178:179], v[178:179], v[214:215] op_sel_hi:[1,0]
	v_pk_fma_f32 v[56:57], v[56:57], v[104:105], v[204:205]
	v_pk_fma_f32 v[36:37], v[36:37], v[104:105], v[208:209]
	v_pk_fma_f32 v[20:21], v[20:21], v[104:105], v[212:213]
	v_pk_fma_f32 v[12:13], v[12:13], v[104:105], v[178:179]
	v_pk_mul_f32 v[216:217], v[180:181], v[202:203] op_sel_hi:[1,0]
	v_pk_mul_f32 v[242:243], v[180:181], v[206:207] op_sel_hi:[1,0]
	v_pk_mul_f32 v[244:245], v[180:181], v[210:211] op_sel_hi:[1,0]
	v_pk_mul_f32 v[180:181], v[180:181], v[214:215] op_sel_hi:[1,0]
	v_pk_fma_f32 v[58:59], v[58:59], v[106:107], v[216:217]
	v_pk_fma_f32 v[38:39], v[38:39], v[106:107], v[242:243]
	v_pk_fma_f32 v[22:23], v[22:23], v[106:107], v[244:245]
	v_pk_fma_f32 v[14:15], v[14:15], v[106:107], v[180:181]
	ds_read_b128 v[92:95], v221 offset:1024
	ds_read_b128 v[96:99], v221 offset:1040
	ds_read_b128 v[100:103], v221 offset:1056
	ds_read_b128 v[104:107], v221 offset:1072
	s_waitcnt lgkmcnt(4)
	v_pk_fma_f32 v[72:73], v[198:199], v[182:183], v[72:73] op_sel_hi:[0,1,1]
	v_pk_fma_f32 v[60:61], v[198:199], v[182:183], v[60:61] op_sel:[1,0,0]
	v_pk_fma_f32 v[48:49], v[200:201], v[182:183], v[48:49] op_sel_hi:[0,1,1]
	v_pk_fma_f32 v[32:33], v[200:201], v[182:183], v[32:33] op_sel:[1,0,0]
	v_pk_fma_f32 v[74:75], v[198:199], v[184:185], v[74:75] op_sel_hi:[0,1,1]
	v_pk_fma_f32 v[62:63], v[198:199], v[184:185], v[62:63] op_sel:[1,0,0]
	v_pk_fma_f32 v[50:51], v[200:201], v[184:185], v[50:51] op_sel_hi:[0,1,1]
	v_pk_fma_f32 v[34:35], v[200:201], v[184:185], v[34:35] op_sel:[1,0,0]
	v_pk_fma_f32 v[68:69], v[198:199], v[186:187], v[68:69] op_sel_hi:[0,1,1]
	v_pk_fma_f32 v[52:53], v[198:199], v[186:187], v[52:53] op_sel:[1,0,0]
	v_pk_fma_f32 v[40:41], v[200:201], v[186:187], v[40:41] op_sel_hi:[0,1,1]
	v_pk_fma_f32 v[24:25], v[200:201], v[186:187], v[24:25] op_sel:[1,0,0]
	v_pk_fma_f32 v[70:71], v[198:199], v[188:189], v[70:71] op_sel_hi:[0,1,1]
	v_pk_fma_f32 v[54:55], v[198:199], v[188:189], v[54:55] op_sel:[1,0,0]
	v_pk_fma_f32 v[42:43], v[200:201], v[188:189], v[42:43] op_sel_hi:[0,1,1]
	v_pk_fma_f32 v[26:27], v[200:201], v[188:189], v[26:27] op_sel:[1,0,0]
	v_pk_fma_f32 v[64:65], v[198:199], v[190:191], v[64:65] op_sel_hi:[0,1,1]
	v_pk_fma_f32 v[44:45], v[198:199], v[190:191], v[44:45] op_sel:[1,0,0]
	v_pk_fma_f32 v[28:29], v[200:201], v[190:191], v[28:29] op_sel_hi:[0,1,1]
	v_pk_fma_f32 v[16:17], v[200:201], v[190:191], v[16:17] op_sel:[1,0,0]
	v_pk_fma_f32 v[66:67], v[198:199], v[192:193], v[66:67] op_sel_hi:[0,1,1]
	v_pk_fma_f32 v[46:47], v[198:199], v[192:193], v[46:47] op_sel:[1,0,0]
	v_pk_fma_f32 v[30:31], v[200:201], v[192:193], v[30:31] op_sel_hi:[0,1,1]
	v_pk_fma_f32 v[18:19], v[200:201], v[192:193], v[18:19] op_sel:[1,0,0]
	v_pk_fma_f32 v[56:57], v[198:199], v[194:195], v[56:57] op_sel_hi:[0,1,1]
	v_pk_fma_f32 v[36:37], v[198:199], v[194:195], v[36:37] op_sel:[1,0,0]
	v_pk_fma_f32 v[20:21], v[200:201], v[194:195], v[20:21] op_sel_hi:[0,1,1]
	v_pk_fma_f32 v[12:13], v[200:201], v[194:195], v[12:13] op_sel:[1,0,0]
	v_pk_fma_f32 v[58:59], v[198:199], v[196:197], v[58:59] op_sel_hi:[0,1,1]
	v_pk_fma_f32 v[38:39], v[198:199], v[196:197], v[38:39] op_sel:[1,0,0]
	v_pk_fma_f32 v[22:23], v[200:201], v[196:197], v[22:23] op_sel_hi:[0,1,1]
	v_pk_fma_f32 v[14:15], v[200:201], v[196:197], v[14:15] op_sel:[1,0,0]
	s_waitcnt lgkmcnt(0)
	v_pk_mul_f32 v[202:203], v[72:73], v[92:93]
	v_pk_mul_f32 v[204:205], v[74:75], v[94:95]
	v_pk_mul_f32 v[206:207], v[60:61], v[92:93]
	v_pk_mul_f32 v[208:209], v[62:63], v[94:95]
	v_pk_mul_f32 v[210:211], v[48:49], v[92:93]
	v_pk_mul_f32 v[212:213], v[50:51], v[94:95]
	v_pk_mul_f32 v[214:215], v[32:33], v[92:93]
	v_pk_mul_f32 v[216:217], v[34:35], v[94:95]
	v_pk_fma_f32 v[202:203], v[68:69], v[96:97], v[202:203]
	v_pk_fma_f32 v[204:205], v[70:71], v[98:99], v[204:205]
	v_pk_fma_f32 v[206:207], v[52:53], v[96:97], v[206:207]
	v_pk_fma_f32 v[208:209], v[54:55], v[98:99], v[208:209]
	v_pk_fma_f32 v[210:211], v[40:41], v[96:97], v[210:211]
	v_pk_fma_f32 v[212:213], v[42:43], v[98:99], v[212:213]
	v_pk_fma_f32 v[214:215], v[24:25], v[96:97], v[214:215]
	v_pk_fma_f32 v[216:217], v[26:27], v[98:99], v[216:217]
	v_pk_fma_f32 v[202:203], v[64:65], v[100:101], v[202:203]
	v_pk_fma_f32 v[204:205], v[66:67], v[102:103], v[204:205]
	v_pk_fma_f32 v[206:207], v[44:45], v[100:101], v[206:207]
	v_pk_fma_f32 v[208:209], v[46:47], v[102:103], v[208:209]
	v_pk_fma_f32 v[210:211], v[28:29], v[100:101], v[210:211]
	v_pk_fma_f32 v[212:213], v[30:31], v[102:103], v[212:213]
	v_pk_fma_f32 v[214:215], v[16:17], v[100:101], v[214:215]
	v_pk_fma_f32 v[216:217], v[18:19], v[102:103], v[216:217]
	v_pk_fma_f32 v[202:203], v[56:57], v[104:105], v[202:203]
	v_pk_fma_f32 v[204:205], v[58:59], v[106:107], v[204:205]
	v_pk_fma_f32 v[206:207], v[36:37], v[104:105], v[206:207]
	v_pk_fma_f32 v[208:209], v[38:39], v[106:107], v[208:209]
	v_pk_fma_f32 v[210:211], v[20:21], v[104:105], v[210:211]
	v_pk_fma_f32 v[212:213], v[22:23], v[106:107], v[212:213]
	v_pk_fma_f32 v[214:215], v[12:13], v[104:105], v[214:215]
	v_pk_fma_f32 v[216:217], v[14:15], v[106:107], v[216:217]
	v_pk_add_f32 v[202:203], v[202:203], v[204:205]
	v_pk_add_f32 v[206:207], v[206:207], v[208:209]
	v_pk_add_f32 v[210:211], v[210:211], v[212:213]
	v_pk_add_f32 v[214:215], v[214:215], v[216:217]
	v_add_f32_e32 v202, v202, v203
	v_add_f32_e32 v206, v206, v207
	v_add_f32_e32 v210, v210, v211
	v_add_f32_e32 v214, v214, v215
	v_add_f32_dpp v202, v202, v202 quad_perm:[1,0,3,2] row_mask:0xf bank_mask:0xf bound_ctrl:1
	v_add_f32_dpp v206, v206, v206 quad_perm:[1,0,3,2] row_mask:0xf bank_mask:0xf bound_ctrl:1
	v_add_f32_dpp v210, v210, v210 quad_perm:[1,0,3,2] row_mask:0xf bank_mask:0xf bound_ctrl:1
	v_add_f32_dpp v214, v214, v214 quad_perm:[1,0,3,2] row_mask:0xf bank_mask:0xf bound_ctrl:1
	v_add_f32_dpp v202, v202, v202 quad_perm:[2,3,0,1] row_mask:0xf bank_mask:0xf bound_ctrl:1
	v_add_f32_dpp v206, v206, v206 quad_perm:[2,3,0,1] row_mask:0xf bank_mask:0xf bound_ctrl:1
	v_add_f32_dpp v210, v210, v210 quad_perm:[2,3,0,1] row_mask:0xf bank_mask:0xf bound_ctrl:1
	v_add_f32_dpp v214, v214, v214 quad_perm:[2,3,0,1] row_mask:0xf bank_mask:0xf bound_ctrl:1
	s_nop 0
	v_cvt_pk_bf16_f32 v240, v202, v206
	v_cvt_pk_bf16_f32 v241, v210, v214
	s_mov_b64 exec, s[6:7]
	global_store_dwordx2 v[238:239], v[240:241], off
	s_mov_b64 exec, -1
	s_waitcnt lgkmcnt(0)

.LBB0_1018:
	s_add_i32 s82, s49, s98
	s_ashr_i32 s83, s82, 31
	s_lshl_b64 s[82:83], s[82:83], 7
	v_lshl_add_u64 v[250:251], v[92:93], 0, s[82:83]
	ds_read_b128 v[60:63], v218 offset:256
	ds_read_b128 v[64:67], v218 offset:272
	ds_read_b128 v[68:71], v218 offset:288
	ds_read_b128 v[72:75], v218 offset:304
	ds_read_b128 v[76:79], v218 offset:512
	ds_read_b128 v[80:83], v218 offset:528
	ds_read_b128 v[84:87], v218 offset:544
	ds_read_b128 v[88:91], v218 offset:560
	ds_read_b64 v[178:179], v222 offset:1280
	s_waitcnt lgkmcnt(9)
	ds_read_b128 v[202:205], v218 offset:768
	ds_read_b128 v[206:209], v218 offset:784
	ds_read_b128 v[210:213], v218 offset:800
	ds_read_b128 v[214:217], v218 offset:816
	v_pk_mul_f32 v[158:159], v[12:13], v[44:45]
	v_pk_mul_f32 v[160:161], v[14:15], v[46:47]
	v_pk_mul_f32 v[162:163], v[40:41], v[44:45]
	v_pk_mul_f32 v[164:165], v[42:43], v[46:47]
	v_pk_fma_f32 v[158:159], v[16:17], v[48:49], v[158:159]
	v_pk_fma_f32 v[160:161], v[18:19], v[50:51], v[160:161]
	v_pk_fma_f32 v[162:163], v[36:37], v[48:49], v[162:163]
	v_pk_fma_f32 v[164:165], v[38:39], v[50:51], v[164:165]
	v_pk_fma_f32 v[158:159], v[20:21], v[52:53], v[158:159]
	v_pk_fma_f32 v[160:161], v[22:23], v[54:55], v[160:161]
	v_pk_fma_f32 v[162:163], v[32:33], v[52:53], v[162:163]
	v_pk_fma_f32 v[164:165], v[34:35], v[54:55], v[164:165]
	v_pk_fma_f32 v[158:159], v[24:25], v[56:57], v[158:159]
	v_pk_fma_f32 v[160:161], v[26:27], v[58:59], v[160:161]
	v_pk_fma_f32 v[162:163], v[28:29], v[56:57], v[162:163]
	v_pk_fma_f32 v[164:165], v[30:31], v[58:59], v[164:165]
	v_pk_add_f32 v[158:159], v[158:159], v[160:161]
	v_pk_add_f32 v[162:163], v[162:163], v[164:165]
	s_waitcnt lgkmcnt(5)
	v_add_f32_e32 v158, v158, v159
	v_add_f32_e32 v162, v162, v163
	ds_read_b128 v[234:237], v218 offset:1024
	ds_read_b128 v[238:241], v218 offset:1040
	v_add_f32_dpp v158, v158, v158 quad_perm:[1,0,3,2] row_mask:0xf bank_mask:0xf bound_ctrl:1
	v_add_f32_dpp v162, v162, v162 quad_perm:[1,0,3,2] row_mask:0xf bank_mask:0xf bound_ctrl:1
	ds_read_b128 v[242:245], v218 offset:1056
	ds_read_b128 v[246:249], v218 offset:1072
	v_add_f32_dpp v158, v158, v158 quad_perm:[2,3,0,1] row_mask:0xf bank_mask:0xf bound_ctrl:1
	v_add_f32_dpp v162, v162, v162 quad_perm:[2,3,0,1] row_mask:0xf bank_mask:0xf bound_ctrl:1
	v_pk_mul_f32 v[170:171], v[76:77], v[158:159] op_sel_hi:[1,0]
	v_pk_mul_f32 v[76:77], v[76:77], v[162:163] op_sel_hi:[1,0]
	v_pk_fma_f32 v[12:13], v[12:13], v[60:61], v[170:171]
	v_pk_fma_f32 v[40:41], v[40:41], v[60:61], v[76:77]
	v_pk_mul_f32 v[172:173], v[78:79], v[158:159] op_sel_hi:[1,0]
	v_pk_mul_f32 v[78:79], v[78:79], v[162:163] op_sel_hi:[1,0]
	v_pk_fma_f32 v[14:15], v[14:15], v[62:63], v[172:173]
	v_pk_fma_f32 v[42:43], v[42:43], v[62:63], v[78:79]
	v_pk_mul_f32 v[174:175], v[80:81], v[158:159] op_sel_hi:[1,0]
	v_pk_mul_f32 v[80:81], v[80:81], v[162:163] op_sel_hi:[1,0]
	v_pk_fma_f32 v[16:17], v[16:17], v[64:65], v[174:175]
	v_pk_fma_f32 v[36:37], v[36:37], v[64:65], v[80:81]
	v_pk_mul_f32 v[176:177], v[82:83], v[158:159] op_sel_hi:[1,0]
	v_pk_mul_f32 v[82:83], v[82:83], v[162:163] op_sel_hi:[1,0]
	v_pk_fma_f32 v[18:19], v[18:19], v[66:67], v[176:177]
	v_pk_fma_f32 v[38:39], v[38:39], v[66:67], v[82:83]
	v_pk_mul_f32 v[170:171], v[84:85], v[158:159] op_sel_hi:[1,0]
	v_pk_mul_f32 v[84:85], v[84:85], v[162:163] op_sel_hi:[1,0]
	v_pk_fma_f32 v[20:21], v[20:21], v[68:69], v[170:171]
	v_pk_fma_f32 v[32:33], v[32:33], v[68:69], v[84:85]
	v_pk_mul_f32 v[172:173], v[86:87], v[158:159] op_sel_hi:[1,0]
	v_pk_mul_f32 v[86:87], v[86:87], v[162:163] op_sel_hi:[1,0]
	v_pk_fma_f32 v[22:23], v[22:23], v[70:71], v[172:173]
	v_pk_fma_f32 v[34:35], v[34:35], v[70:71], v[86:87]
	v_pk_mul_f32 v[174:175], v[88:89], v[158:159] op_sel_hi:[1,0]
	v_pk_mul_f32 v[88:89], v[88:89], v[162:163] op_sel_hi:[1,0]
	v_pk_fma_f32 v[24:25], v[24:25], v[72:73], v[174:175]
	v_pk_fma_f32 v[28:29], v[28:29], v[72:73], v[88:89]
	v_pk_mul_f32 v[176:177], v[90:91], v[158:159] op_sel_hi:[1,0]
	v_pk_mul_f32 v[90:91], v[90:91], v[162:163] op_sel_hi:[1,0]
	v_pk_fma_f32 v[26:27], v[26:27], v[74:75], v[176:177]
	v_pk_fma_f32 v[30:31], v[30:31], v[74:75], v[90:91]
	ds_read_b128 v[44:47], v219 offset:0
	ds_read_b128 v[48:51], v219 offset:16
	ds_read_b128 v[52:55], v219 offset:32
	ds_read_b128 v[56:59], v219 offset:48
	s_waitcnt lgkmcnt(8)
	v_pk_fma_f32 v[142:143], v[178:179], v[202:203], v[12:13] op_sel_hi:[0,1,1]
	v_pk_fma_f32 v[186:187], v[178:179], v[202:203], v[40:41] op_sel:[1,0,0]
	v_pk_fma_f32 v[144:145], v[178:179], v[204:205], v[14:15] op_sel_hi:[0,1,1]
	v_pk_fma_f32 v[188:189], v[178:179], v[204:205], v[42:43] op_sel:[1,0,0]
	v_pk_fma_f32 v[146:147], v[178:179], v[206:207], v[16:17] op_sel_hi:[0,1,1]
	v_pk_fma_f32 v[190:191], v[178:179], v[206:207], v[36:37] op_sel:[1,0,0]
	v_pk_fma_f32 v[148:149], v[178:179], v[208:209], v[18:19] op_sel_hi:[0,1,1]
	v_pk_fma_f32 v[192:193], v[178:179], v[208:209], v[38:39] op_sel:[1,0,0]
	v_pk_fma_f32 v[150:151], v[178:179], v[210:211], v[20:21] op_sel_hi:[0,1,1]
	v_pk_fma_f32 v[194:195], v[178:179], v[210:211], v[32:33] op_sel:[1,0,0]
	v_pk_fma_f32 v[152:153], v[178:179], v[212:213], v[22:23] op_sel_hi:[0,1,1]
	v_pk_fma_f32 v[196:197], v[178:179], v[212:213], v[34:35] op_sel:[1,0,0]
	v_pk_fma_f32 v[154:155], v[178:179], v[214:215], v[24:25] op_sel_hi:[0,1,1]
	v_pk_fma_f32 v[198:199], v[178:179], v[214:215], v[28:29] op_sel:[1,0,0]
	v_pk_fma_f32 v[156:157], v[178:179], v[216:217], v[26:27] op_sel_hi:[0,1,1]
	v_pk_fma_f32 v[200:201], v[178:179], v[216:217], v[30:31] op_sel:[1,0,0]
	s_waitcnt lgkmcnt(4)
	v_pk_mul_f32 v[170:171], v[142:143], v[234:235]
	v_pk_mul_f32 v[172:173], v[144:145], v[236:237]
	v_pk_mul_f32 v[174:175], v[186:187], v[234:235]
	v_pk_mul_f32 v[176:177], v[188:189], v[236:237]
	v_pk_fma_f32 v[170:171], v[146:147], v[238:239], v[170:171]
	v_pk_fma_f32 v[172:173], v[148:149], v[240:241], v[172:173]
	v_pk_fma_f32 v[174:175], v[190:191], v[238:239], v[174:175]
	v_pk_fma_f32 v[176:177], v[192:193], v[240:241], v[176:177]
	v_pk_fma_f32 v[170:171], v[150:151], v[242:243], v[170:171]
	v_pk_fma_f32 v[172:173], v[152:153], v[244:245], v[172:173]
	v_pk_fma_f32 v[174:175], v[194:195], v[242:243], v[174:175]
	v_pk_fma_f32 v[176:177], v[196:197], v[244:245], v[176:177]
	v_pk_fma_f32 v[170:171], v[154:155], v[246:247], v[170:171]
	v_pk_fma_f32 v[172:173], v[156:157], v[248:249], v[172:173]
	v_pk_fma_f32 v[174:175], v[198:199], v[246:247], v[174:175]
	v_pk_fma_f32 v[176:177], v[200:201], v[248:249], v[176:177]
	v_pk_add_f32 v[170:171], v[170:171], v[172:173]
	v_pk_add_f32 v[174:175], v[174:175], v[176:177]
	ds_read_b128 v[60:63], v219 offset:256
	v_add_f32_e32 v170, v170, v171
	v_add_f32_e32 v174, v174, v175
	ds_read_b128 v[64:67], v219 offset:272
	ds_read_b128 v[68:71], v219 offset:288
	v_add_f32_dpp v170, v170, v170 quad_perm:[1,0,3,2] row_mask:0xf bank_mask:0xf bound_ctrl:1
	v_add_f32_dpp v174, v174, v174 quad_perm:[1,0,3,2] row_mask:0xf bank_mask:0xf bound_ctrl:1
	ds_read_b128 v[72:75], v219 offset:304
	ds_read_b128 v[76:79], v219 offset:512
	v_add_f32_dpp v170, v170, v170 quad_perm:[2,3,0,1] row_mask:0xf bank_mask:0xf bound_ctrl:1
	v_add_f32_dpp v174, v174, v174 quad_perm:[2,3,0,1] row_mask:0xf bank_mask:0xf bound_ctrl:1
	ds_read_b128 v[80:83], v219 offset:528
	ds_read_b128 v[84:87], v219 offset:544
	v_cvt_pk_bf16_f32 v180, v170, v174
	s_mov_b64 exec, s[6:7]
	global_store_dword v[250:251], v180, off
	s_mov_b64 exec, -1
	ds_read_b128 v[88:91], v219 offset:560
	ds_read_b64 v[178:179], v223 offset:1280
	v_lshl_add_u64 v[250:251], v[250:251], 0, s[80:81]
	s_waitcnt lgkmcnt(9)
	ds_read_b128 v[202:205], v219 offset:768
	ds_read_b128 v[206:209], v219 offset:784
	ds_read_b128 v[210:213], v219 offset:800
	ds_read_b128 v[214:217], v219 offset:816
	v_pk_mul_f32 v[158:159], v[142:143], v[44:45]
	v_pk_mul_f32 v[160:161], v[144:145], v[46:47]
	v_pk_mul_f32 v[162:163], v[186:187], v[44:45]
	v_pk_mul_f32 v[164:165], v[188:189], v[46:47]
	v_pk_fma_f32 v[158:159], v[146:147], v[48:49], v[158:159]
	v_pk_fma_f32 v[160:161], v[148:149], v[50:51], v[160:161]
	v_pk_fma_f32 v[162:163], v[190:191], v[48:49], v[162:163]
	v_pk_fma_f32 v[164:165], v[192:193], v[50:51], v[164:165]
	v_pk_fma_f32 v[158:159], v[150:151], v[52:53], v[158:159]
	v_pk_fma_f32 v[160:161], v[152:153], v[54:55], v[160:161]
	v_pk_fma_f32 v[162:163], v[194:195], v[52:53], v[162:163]
	v_pk_fma_f32 v[164:165], v[196:197], v[54:55], v[164:165]
	v_pk_fma_f32 v[158:159], v[154:155], v[56:57], v[158:159]
	v_pk_fma_f32 v[160:161], v[156:157], v[58:59], v[160:161]
	v_pk_fma_f32 v[162:163], v[198:199], v[56:57], v[162:163]
	v_pk_fma_f32 v[164:165], v[200:201], v[58:59], v[164:165]
	v_pk_add_f32 v[158:159], v[158:159], v[160:161]
	v_pk_add_f32 v[162:163], v[162:163], v[164:165]
	s_waitcnt lgkmcnt(5)
	v_add_f32_e32 v158, v158, v159
	v_add_f32_e32 v162, v162, v163
	ds_read_b128 v[234:237], v219 offset:1024
	ds_read_b128 v[238:241], v219 offset:1040
	v_add_f32_dpp v158, v158, v158 quad_perm:[1,0,3,2] row_mask:0xf bank_mask:0xf bound_ctrl:1
	v_add_f32_dpp v162, v162, v162 quad_perm:[1,0,3,2] row_mask:0xf bank_mask:0xf bound_ctrl:1
	ds_read_b128 v[242:245], v219 offset:1056
	ds_read_b128 v[246:249], v219 offset:1072
	v_add_f32_dpp v158, v158, v158 quad_perm:[2,3,0,1] row_mask:0xf bank_mask:0xf bound_ctrl:1
	v_add_f32_dpp v162, v162, v162 quad_perm:[2,3,0,1] row_mask:0xf bank_mask:0xf bound_ctrl:1
	v_pk_mul_f32 v[170:171], v[76:77], v[158:159] op_sel_hi:[1,0]
	v_pk_mul_f32 v[76:77], v[76:77], v[162:163] op_sel_hi:[1,0]
	v_pk_fma_f32 v[142:143], v[142:143], v[60:61], v[170:171]
	v_pk_fma_f32 v[186:187], v[186:187], v[60:61], v[76:77]
	v_pk_mul_f32 v[172:173], v[78:79], v[158:159] op_sel_hi:[1,0]
	v_pk_mul_f32 v[78:79], v[78:79], v[162:163] op_sel_hi:[1,0]
	v_pk_fma_f32 v[144:145], v[144:145], v[62:63], v[172:173]
	v_pk_fma_f32 v[188:189], v[188:189], v[62:63], v[78:79]
	v_pk_mul_f32 v[174:175], v[80:81], v[158:159] op_sel_hi:[1,0]
	v_pk_mul_f32 v[80:81], v[80:81], v[162:163] op_sel_hi:[1,0]
	v_pk_fma_f32 v[146:147], v[146:147], v[64:65], v[174:175]
	v_pk_fma_f32 v[190:191], v[190:191], v[64:65], v[80:81]
	v_pk_mul_f32 v[176:177], v[82:83], v[158:159] op_sel_hi:[1,0]
	v_pk_mul_f32 v[82:83], v[82:83], v[162:163] op_sel_hi:[1,0]
	v_pk_fma_f32 v[148:149], v[148:149], v[66:67], v[176:177]
	v_pk_fma_f32 v[192:193], v[192:193], v[66:67], v[82:83]
	v_pk_mul_f32 v[170:171], v[84:85], v[158:159] op_sel_hi:[1,0]
	v_pk_mul_f32 v[84:85], v[84:85], v[162:163] op_sel_hi:[1,0]
	v_pk_fma_f32 v[150:151], v[150:151], v[68:69], v[170:171]
	v_pk_fma_f32 v[194:195], v[194:195], v[68:69], v[84:85]
	v_pk_mul_f32 v[172:173], v[86:87], v[158:159] op_sel_hi:[1,0]
	v_pk_mul_f32 v[86:87], v[86:87], v[162:163] op_sel_hi:[1,0]
	v_pk_fma_f32 v[152:153], v[152:153], v[70:71], v[172:173]
	v_pk_fma_f32 v[196:197], v[196:197], v[70:71], v[86:87]
	v_pk_mul_f32 v[174:175], v[88:89], v[158:159] op_sel_hi:[1,0]
	v_pk_mul_f32 v[88:89], v[88:89], v[162:163] op_sel_hi:[1,0]
	v_pk_fma_f32 v[154:155], v[154:155], v[72:73], v[174:175]
	v_pk_fma_f32 v[198:199], v[198:199], v[72:73], v[88:89]
	v_pk_mul_f32 v[176:177], v[90:91], v[158:159] op_sel_hi:[1,0]
	v_pk_mul_f32 v[90:91], v[90:91], v[162:163] op_sel_hi:[1,0]
	v_pk_fma_f32 v[156:157], v[156:157], v[74:75], v[176:177]
	v_pk_fma_f32 v[200:201], v[200:201], v[74:75], v[90:91]
	ds_read_b128 v[44:47], v220 offset:0
	ds_read_b128 v[48:51], v220 offset:16
	ds_read_b128 v[52:55], v220 offset:32
	ds_read_b128 v[56:59], v220 offset:48
	s_waitcnt lgkmcnt(8)
	v_pk_fma_f32 v[12:13], v[178:179], v[202:203], v[142:143] op_sel_hi:[0,1,1]
	v_pk_fma_f32 v[40:41], v[178:179], v[202:203], v[186:187] op_sel:[1,0,0]
	v_pk_fma_f32 v[14:15], v[178:179], v[204:205], v[144:145] op_sel_hi:[0,1,1]
	v_pk_fma_f32 v[42:43], v[178:179], v[204:205], v[188:189] op_sel:[1,0,0]
	v_pk_fma_f32 v[16:17], v[178:179], v[206:207], v[146:147] op_sel_hi:[0,1,1]
	v_pk_fma_f32 v[36:37], v[178:179], v[206:207], v[190:191] op_sel:[1,0,0]
	v_pk_fma_f32 v[18:19], v[178:179], v[208:209], v[148:149] op_sel_hi:[0,1,1]
	v_pk_fma_f32 v[38:39], v[178:179], v[208:209], v[192:193] op_sel:[1,0,0]
	v_pk_fma_f32 v[20:21], v[178:179], v[210:211], v[150:151] op_sel_hi:[0,1,1]
	v_pk_fma_f32 v[32:33], v[178:179], v[210:211], v[194:195] op_sel:[1,0,0]
	v_pk_fma_f32 v[22:23], v[178:179], v[212:213], v[152:153] op_sel_hi:[0,1,1]
	v_pk_fma_f32 v[34:35], v[178:179], v[212:213], v[196:197] op_sel:[1,0,0]
	v_pk_fma_f32 v[24:25], v[178:179], v[214:215], v[154:155] op_sel_hi:[0,1,1]
	v_pk_fma_f32 v[28:29], v[178:179], v[214:215], v[198:199] op_sel:[1,0,0]
	v_pk_fma_f32 v[26:27], v[178:179], v[216:217], v[156:157] op_sel_hi:[0,1,1]
	v_pk_fma_f32 v[30:31], v[178:179], v[216:217], v[200:201] op_sel:[1,0,0]
	s_waitcnt lgkmcnt(4)
	v_pk_mul_f32 v[170:171], v[12:13], v[234:235]
	v_pk_mul_f32 v[172:173], v[14:15], v[236:237]
	v_pk_mul_f32 v[174:175], v[40:41], v[234:235]
	v_pk_mul_f32 v[176:177], v[42:43], v[236:237]
	v_pk_fma_f32 v[170:171], v[16:17], v[238:239], v[170:171]
	v_pk_fma_f32 v[172:173], v[18:19], v[240:241], v[172:173]
	v_pk_fma_f32 v[174:175], v[36:37], v[238:239], v[174:175]
	v_pk_fma_f32 v[176:177], v[38:39], v[240:241], v[176:177]
	v_pk_fma_f32 v[170:171], v[20:21], v[242:243], v[170:171]
	v_pk_fma_f32 v[172:173], v[22:23], v[244:245], v[172:173]
	v_pk_fma_f32 v[174:175], v[32:33], v[242:243], v[174:175]
	v_pk_fma_f32 v[176:177], v[34:35], v[244:245], v[176:177]
	v_pk_fma_f32 v[170:171], v[24:25], v[246:247], v[170:171]
	v_pk_fma_f32 v[172:173], v[26:27], v[248:249], v[172:173]
	v_pk_fma_f32 v[174:175], v[28:29], v[246:247], v[174:175]
	v_pk_fma_f32 v[176:177], v[30:31], v[248:249], v[176:177]
	v_pk_add_f32 v[170:171], v[170:171], v[172:173]
	v_pk_add_f32 v[174:175], v[174:175], v[176:177]
	ds_read_b128 v[60:63], v220 offset:256
	v_add_f32_e32 v170, v170, v171
	v_add_f32_e32 v174, v174, v175
	ds_read_b128 v[64:67], v220 offset:272
	ds_read_b128 v[68:71], v220 offset:288
	v_add_f32_dpp v170, v170, v170 quad_perm:[1,0,3,2] row_mask:0xf bank_mask:0xf bound_ctrl:1
	v_add_f32_dpp v174, v174, v174 quad_perm:[1,0,3,2] row_mask:0xf bank_mask:0xf bound_ctrl:1
	ds_read_b128 v[72:75], v220 offset:304
	ds_read_b128 v[76:79], v220 offset:512
	v_add_f32_dpp v170, v170, v170 quad_perm:[2,3,0,1] row_mask:0xf bank_mask:0xf bound_ctrl:1
	v_add_f32_dpp v174, v174, v174 quad_perm:[2,3,0,1] row_mask:0xf bank_mask:0xf bound_ctrl:1
	ds_read_b128 v[80:83], v220 offset:528
	ds_read_b128 v[84:87], v220 offset:544
	v_cvt_pk_bf16_f32 v180, v170, v174
	s_mov_b64 exec, s[6:7]
	global_store_dword v[250:251], v180, off
	s_mov_b64 exec, -1
	ds_read_b128 v[88:91], v220 offset:560
	ds_read_b64 v[178:179], v224 offset:1280
	v_lshl_add_u64 v[250:251], v[250:251], 0, s[80:81]
	s_waitcnt lgkmcnt(9)
	ds_read_b128 v[202:205], v220 offset:768
	ds_read_b128 v[206:209], v220 offset:784
	ds_read_b128 v[210:213], v220 offset:800
	ds_read_b128 v[214:217], v220 offset:816
	v_pk_mul_f32 v[158:159], v[12:13], v[44:45]
	v_pk_mul_f32 v[160:161], v[14:15], v[46:47]
	v_pk_mul_f32 v[162:163], v[40:41], v[44:45]
	v_pk_mul_f32 v[164:165], v[42:43], v[46:47]
	v_pk_fma_f32 v[158:159], v[16:17], v[48:49], v[158:159]
	v_pk_fma_f32 v[160:161], v[18:19], v[50:51], v[160:161]
	v_pk_fma_f32 v[162:163], v[36:37], v[48:49], v[162:163]
	v_pk_fma_f32 v[164:165], v[38:39], v[50:51], v[164:165]
	v_pk_fma_f32 v[158:159], v[20:21], v[52:53], v[158:159]
	v_pk_fma_f32 v[160:161], v[22:23], v[54:55], v[160:161]
	v_pk_fma_f32 v[162:163], v[32:33], v[52:53], v[162:163]
	v_pk_fma_f32 v[164:165], v[34:35], v[54:55], v[164:165]
	v_pk_fma_f32 v[158:159], v[24:25], v[56:57], v[158:159]
	v_pk_fma_f32 v[160:161], v[26:27], v[58:59], v[160:161]
	v_pk_fma_f32 v[162:163], v[28:29], v[56:57], v[162:163]
	v_pk_fma_f32 v[164:165], v[30:31], v[58:59], v[164:165]
	v_pk_add_f32 v[158:159], v[158:159], v[160:161]
	v_pk_add_f32 v[162:163], v[162:163], v[164:165]
	s_waitcnt lgkmcnt(5)
	v_add_f32_e32 v158, v158, v159
	v_add_f32_e32 v162, v162, v163
	ds_read_b128 v[234:237], v220 offset:1024
	ds_read_b128 v[238:241], v220 offset:1040
	v_add_f32_dpp v158, v158, v158 quad_perm:[1,0,3,2] row_mask:0xf bank_mask:0xf bound_ctrl:1
	v_add_f32_dpp v162, v162, v162 quad_perm:[1,0,3,2] row_mask:0xf bank_mask:0xf bound_ctrl:1
	ds_read_b128 v[242:245], v220 offset:1056
	ds_read_b128 v[246:249], v220 offset:1072
	v_add_f32_dpp v158, v158, v158 quad_perm:[2,3,0,1] row_mask:0xf bank_mask:0xf bound_ctrl:1
	v_add_f32_dpp v162, v162, v162 quad_perm:[2,3,0,1] row_mask:0xf bank_mask:0xf bound_ctrl:1
	v_pk_mul_f32 v[170:171], v[76:77], v[158:159] op_sel_hi:[1,0]
	v_pk_mul_f32 v[76:77], v[76:77], v[162:163] op_sel_hi:[1,0]
	v_pk_fma_f32 v[12:13], v[12:13], v[60:61], v[170:171]
	v_pk_fma_f32 v[40:41], v[40:41], v[60:61], v[76:77]
	v_pk_mul_f32 v[172:173], v[78:79], v[158:159] op_sel_hi:[1,0]
	v_pk_mul_f32 v[78:79], v[78:79], v[162:163] op_sel_hi:[1,0]
	v_pk_fma_f32 v[14:15], v[14:15], v[62:63], v[172:173]
	v_pk_fma_f32 v[42:43], v[42:43], v[62:63], v[78:79]
	v_pk_mul_f32 v[174:175], v[80:81], v[158:159] op_sel_hi:[1,0]
	v_pk_mul_f32 v[80:81], v[80:81], v[162:163] op_sel_hi:[1,0]
	v_pk_fma_f32 v[16:17], v[16:17], v[64:65], v[174:175]
	v_pk_fma_f32 v[36:37], v[36:37], v[64:65], v[80:81]
	v_pk_mul_f32 v[176:177], v[82:83], v[158:159] op_sel_hi:[1,0]
	v_pk_mul_f32 v[82:83], v[82:83], v[162:163] op_sel_hi:[1,0]
	v_pk_fma_f32 v[18:19], v[18:19], v[66:67], v[176:177]
	v_pk_fma_f32 v[38:39], v[38:39], v[66:67], v[82:83]
	v_pk_mul_f32 v[170:171], v[84:85], v[158:159] op_sel_hi:[1,0]
	v_pk_mul_f32 v[84:85], v[84:85], v[162:163] op_sel_hi:[1,0]
	v_pk_fma_f32 v[20:21], v[20:21], v[68:69], v[170:171]
	v_pk_fma_f32 v[32:33], v[32:33], v[68:69], v[84:85]
	v_pk_mul_f32 v[172:173], v[86:87], v[158:159] op_sel_hi:[1,0]
	v_pk_mul_f32 v[86:87], v[86:87], v[162:163] op_sel_hi:[1,0]
	v_pk_fma_f32 v[22:23], v[22:23], v[70:71], v[172:173]
	v_pk_fma_f32 v[34:35], v[34:35], v[70:71], v[86:87]
	v_pk_mul_f32 v[174:175], v[88:89], v[158:159] op_sel_hi:[1,0]
	v_pk_mul_f32 v[88:89], v[88:89], v[162:163] op_sel_hi:[1,0]
	v_pk_fma_f32 v[24:25], v[24:25], v[72:73], v[174:175]
	v_pk_fma_f32 v[28:29], v[28:29], v[72:73], v[88:89]
	v_pk_mul_f32 v[176:177], v[90:91], v[158:159] op_sel_hi:[1,0]
	v_pk_mul_f32 v[90:91], v[90:91], v[162:163] op_sel_hi:[1,0]
	v_pk_fma_f32 v[26:27], v[26:27], v[74:75], v[176:177]
	v_pk_fma_f32 v[30:31], v[30:31], v[74:75], v[90:91]
	ds_read_b128 v[44:47], v221 offset:0
	ds_read_b128 v[48:51], v221 offset:16
	ds_read_b128 v[52:55], v221 offset:32
	ds_read_b128 v[56:59], v221 offset:48
	s_waitcnt lgkmcnt(8)
	v_pk_fma_f32 v[142:143], v[178:179], v[202:203], v[12:13] op_sel_hi:[0,1,1]
	v_pk_fma_f32 v[186:187], v[178:179], v[202:203], v[40:41] op_sel:[1,0,0]
	v_pk_fma_f32 v[144:145], v[178:179], v[204:205], v[14:15] op_sel_hi:[0,1,1]
	v_pk_fma_f32 v[188:189], v[178:179], v[204:205], v[42:43] op_sel:[1,0,0]
	v_pk_fma_f32 v[146:147], v[178:179], v[206:207], v[16:17] op_sel_hi:[0,1,1]
	v_pk_fma_f32 v[190:191], v[178:179], v[206:207], v[36:37] op_sel:[1,0,0]
	v_pk_fma_f32 v[148:149], v[178:179], v[208:209], v[18:19] op_sel_hi:[0,1,1]
	v_pk_fma_f32 v[192:193], v[178:179], v[208:209], v[38:39] op_sel:[1,0,0]
	v_pk_fma_f32 v[150:151], v[178:179], v[210:211], v[20:21] op_sel_hi:[0,1,1]
	v_pk_fma_f32 v[194:195], v[178:179], v[210:211], v[32:33] op_sel:[1,0,0]
	v_pk_fma_f32 v[152:153], v[178:179], v[212:213], v[22:23] op_sel_hi:[0,1,1]
	v_pk_fma_f32 v[196:197], v[178:179], v[212:213], v[34:35] op_sel:[1,0,0]
	v_pk_fma_f32 v[154:155], v[178:179], v[214:215], v[24:25] op_sel_hi:[0,1,1]
	v_pk_fma_f32 v[198:199], v[178:179], v[214:215], v[28:29] op_sel:[1,0,0]
	v_pk_fma_f32 v[156:157], v[178:179], v[216:217], v[26:27] op_sel_hi:[0,1,1]
	v_pk_fma_f32 v[200:201], v[178:179], v[216:217], v[30:31] op_sel:[1,0,0]
	s_waitcnt lgkmcnt(4)
	v_pk_mul_f32 v[170:171], v[142:143], v[234:235]
	v_pk_mul_f32 v[172:173], v[144:145], v[236:237]
	v_pk_mul_f32 v[174:175], v[186:187], v[234:235]
	v_pk_mul_f32 v[176:177], v[188:189], v[236:237]
	v_pk_fma_f32 v[170:171], v[146:147], v[238:239], v[170:171]
	v_pk_fma_f32 v[172:173], v[148:149], v[240:241], v[172:173]
	v_pk_fma_f32 v[174:175], v[190:191], v[238:239], v[174:175]
	v_pk_fma_f32 v[176:177], v[192:193], v[240:241], v[176:177]
	v_pk_fma_f32 v[170:171], v[150:151], v[242:243], v[170:171]
	v_pk_fma_f32 v[172:173], v[152:153], v[244:245], v[172:173]
	v_pk_fma_f32 v[174:175], v[194:195], v[242:243], v[174:175]
	v_pk_fma_f32 v[176:177], v[196:197], v[244:245], v[176:177]
	v_pk_fma_f32 v[170:171], v[154:155], v[246:247], v[170:171]
	v_pk_fma_f32 v[172:173], v[156:157], v[248:249], v[172:173]
	v_pk_fma_f32 v[174:175], v[198:199], v[246:247], v[174:175]
	v_pk_fma_f32 v[176:177], v[200:201], v[248:249], v[176:177]
	v_pk_add_f32 v[170:171], v[170:171], v[172:173]
	v_pk_add_f32 v[174:175], v[174:175], v[176:177]
	ds_read_b128 v[60:63], v221 offset:256
	v_add_f32_e32 v170, v170, v171
	v_add_f32_e32 v174, v174, v175
	ds_read_b128 v[64:67], v221 offset:272
	ds_read_b128 v[68:71], v221 offset:288
	v_add_f32_dpp v170, v170, v170 quad_perm:[1,0,3,2] row_mask:0xf bank_mask:0xf bound_ctrl:1
	v_add_f32_dpp v174, v174, v174 quad_perm:[1,0,3,2] row_mask:0xf bank_mask:0xf bound_ctrl:1
	ds_read_b128 v[72:75], v221 offset:304
	ds_read_b128 v[76:79], v221 offset:512
	v_add_f32_dpp v170, v170, v170 quad_perm:[2,3,0,1] row_mask:0xf bank_mask:0xf bound_ctrl:1
	v_add_f32_dpp v174, v174, v174 quad_perm:[2,3,0,1] row_mask:0xf bank_mask:0xf bound_ctrl:1
	ds_read_b128 v[80:83], v221 offset:528
	ds_read_b128 v[84:87], v221 offset:544
	v_cvt_pk_bf16_f32 v180, v170, v174
	s_mov_b64 exec, s[6:7]
	global_store_dword v[250:251], v180, off
	s_mov_b64 exec, -1
	ds_read_b128 v[88:91], v221 offset:560
	ds_read_b64 v[178:179], v228 offset:1280
	v_lshl_add_u64 v[250:251], v[250:251], 0, s[80:81]
	s_waitcnt lgkmcnt(9)
	ds_read_b128 v[202:205], v221 offset:768
	ds_read_b128 v[206:209], v221 offset:784
	ds_read_b128 v[210:213], v221 offset:800
	ds_read_b128 v[214:217], v221 offset:816
	v_pk_mul_f32 v[158:159], v[142:143], v[44:45]
	v_pk_mul_f32 v[160:161], v[144:145], v[46:47]
	v_pk_mul_f32 v[162:163], v[186:187], v[44:45]
	v_pk_mul_f32 v[164:165], v[188:189], v[46:47]
	v_pk_fma_f32 v[158:159], v[146:147], v[48:49], v[158:159]
	v_pk_fma_f32 v[160:161], v[148:149], v[50:51], v[160:161]
	v_pk_fma_f32 v[162:163], v[190:191], v[48:49], v[162:163]
	v_pk_fma_f32 v[164:165], v[192:193], v[50:51], v[164:165]
	v_pk_fma_f32 v[158:159], v[150:151], v[52:53], v[158:159]
	v_pk_fma_f32 v[160:161], v[152:153], v[54:55], v[160:161]
	v_pk_fma_f32 v[162:163], v[194:195], v[52:53], v[162:163]
	v_pk_fma_f32 v[164:165], v[196:197], v[54:55], v[164:165]
	v_pk_fma_f32 v[158:159], v[154:155], v[56:57], v[158:159]
	v_pk_fma_f32 v[160:161], v[156:157], v[58:59], v[160:161]
	v_pk_fma_f32 v[162:163], v[198:199], v[56:57], v[162:163]
	v_pk_fma_f32 v[164:165], v[200:201], v[58:59], v[164:165]
	v_pk_add_f32 v[158:159], v[158:159], v[160:161]
	v_pk_add_f32 v[162:163], v[162:163], v[164:165]
	s_waitcnt lgkmcnt(5)
	v_add_f32_e32 v158, v158, v159
	v_add_f32_e32 v162, v162, v163
	ds_read_b128 v[234:237], v221 offset:1024
	ds_read_b128 v[238:241], v221 offset:1040
	v_add_f32_dpp v158, v158, v158 quad_perm:[1,0,3,2] row_mask:0xf bank_mask:0xf bound_ctrl:1
	v_add_f32_dpp v162, v162, v162 quad_perm:[1,0,3,2] row_mask:0xf bank_mask:0xf bound_ctrl:1
	ds_read_b128 v[242:245], v221 offset:1056
	ds_read_b128 v[246:249], v221 offset:1072
	v_add_f32_dpp v158, v158, v158 quad_perm:[2,3,0,1] row_mask:0xf bank_mask:0xf bound_ctrl:1
	v_add_f32_dpp v162, v162, v162 quad_perm:[2,3,0,1] row_mask:0xf bank_mask:0xf bound_ctrl:1
	v_pk_mul_f32 v[170:171], v[76:77], v[158:159] op_sel_hi:[1,0]
	v_pk_mul_f32 v[76:77], v[76:77], v[162:163] op_sel_hi:[1,0]
	v_pk_fma_f32 v[142:143], v[142:143], v[60:61], v[170:171]
	v_pk_fma_f32 v[186:187], v[186:187], v[60:61], v[76:77]
	v_pk_mul_f32 v[172:173], v[78:79], v[158:159] op_sel_hi:[1,0]
	v_pk_mul_f32 v[78:79], v[78:79], v[162:163] op_sel_hi:[1,0]
	v_pk_fma_f32 v[144:145], v[144:145], v[62:63], v[172:173]
	v_pk_fma_f32 v[188:189], v[188:189], v[62:63], v[78:79]
	v_pk_mul_f32 v[174:175], v[80:81], v[158:159] op_sel_hi:[1,0]
	v_pk_mul_f32 v[80:81], v[80:81], v[162:163] op_sel_hi:[1,0]
	v_pk_fma_f32 v[146:147], v[146:147], v[64:65], v[174:175]
	v_pk_fma_f32 v[190:191], v[190:191], v[64:65], v[80:81]
	v_pk_mul_f32 v[176:177], v[82:83], v[158:159] op_sel_hi:[1,0]
	v_pk_mul_f32 v[82:83], v[82:83], v[162:163] op_sel_hi:[1,0]
	v_pk_fma_f32 v[148:149], v[148:149], v[66:67], v[176:177]
	v_pk_fma_f32 v[192:193], v[192:193], v[66:67], v[82:83]
	v_pk_mul_f32 v[170:171], v[84:85], v[158:159] op_sel_hi:[1,0]
	v_pk_mul_f32 v[84:85], v[84:85], v[162:163] op_sel_hi:[1,0]
	v_pk_fma_f32 v[150:151], v[150:151], v[68:69], v[170:171]
	v_pk_fma_f32 v[194:195], v[194:195], v[68:69], v[84:85]
	v_pk_mul_f32 v[172:173], v[86:87], v[158:159] op_sel_hi:[1,0]
	v_pk_mul_f32 v[86:87], v[86:87], v[162:163] op_sel_hi:[1,0]
	v_pk_fma_f32 v[152:153], v[152:153], v[70:71], v[172:173]
	v_pk_fma_f32 v[196:197], v[196:197], v[70:71], v[86:87]
	v_pk_mul_f32 v[174:175], v[88:89], v[158:159] op_sel_hi:[1,0]
	v_pk_mul_f32 v[88:89], v[88:89], v[162:163] op_sel_hi:[1,0]
	v_pk_fma_f32 v[154:155], v[154:155], v[72:73], v[174:175]
	v_pk_fma_f32 v[198:199], v[198:199], v[72:73], v[88:89]
	v_pk_mul_f32 v[176:177], v[90:91], v[158:159] op_sel_hi:[1,0]
	v_pk_mul_f32 v[90:91], v[90:91], v[162:163] op_sel_hi:[1,0]
	v_pk_fma_f32 v[156:157], v[156:157], v[74:75], v[176:177]
	v_pk_fma_f32 v[200:201], v[200:201], v[74:75], v[90:91]
	s_waitcnt lgkmcnt(4)
	v_pk_fma_f32 v[12:13], v[178:179], v[202:203], v[142:143] op_sel_hi:[0,1,1]
	v_pk_fma_f32 v[40:41], v[178:179], v[202:203], v[186:187] op_sel:[1,0,0]
	v_pk_fma_f32 v[14:15], v[178:179], v[204:205], v[144:145] op_sel_hi:[0,1,1]
	v_pk_fma_f32 v[42:43], v[178:179], v[204:205], v[188:189] op_sel:[1,0,0]
	v_pk_fma_f32 v[16:17], v[178:179], v[206:207], v[146:147] op_sel_hi:[0,1,1]
	v_pk_fma_f32 v[36:37], v[178:179], v[206:207], v[190:191] op_sel:[1,0,0]
	v_pk_fma_f32 v[18:19], v[178:179], v[208:209], v[148:149] op_sel_hi:[0,1,1]
	v_pk_fma_f32 v[38:39], v[178:179], v[208:209], v[192:193] op_sel:[1,0,0]
	v_pk_fma_f32 v[20:21], v[178:179], v[210:211], v[150:151] op_sel_hi:[0,1,1]
	v_pk_fma_f32 v[32:33], v[178:179], v[210:211], v[194:195] op_sel:[1,0,0]
	v_pk_fma_f32 v[22:23], v[178:179], v[212:213], v[152:153] op_sel_hi:[0,1,1]
	v_pk_fma_f32 v[34:35], v[178:179], v[212:213], v[196:197] op_sel:[1,0,0]
	v_pk_fma_f32 v[24:25], v[178:179], v[214:215], v[154:155] op_sel_hi:[0,1,1]
	v_pk_fma_f32 v[28:29], v[178:179], v[214:215], v[198:199] op_sel:[1,0,0]
	v_pk_fma_f32 v[26:27], v[178:179], v[216:217], v[156:157] op_sel_hi:[0,1,1]
	v_pk_fma_f32 v[30:31], v[178:179], v[216:217], v[200:201] op_sel:[1,0,0]
	s_waitcnt lgkmcnt(0)
	v_pk_mul_f32 v[170:171], v[12:13], v[234:235]
	v_pk_mul_f32 v[172:173], v[14:15], v[236:237]
	v_pk_mul_f32 v[174:175], v[40:41], v[234:235]
	v_pk_mul_f32 v[176:177], v[42:43], v[236:237]
	v_pk_fma_f32 v[170:171], v[16:17], v[238:239], v[170:171]
	v_pk_fma_f32 v[172:173], v[18:19], v[240:241], v[172:173]
	v_pk_fma_f32 v[174:175], v[36:37], v[238:239], v[174:175]
	v_pk_fma_f32 v[176:177], v[38:39], v[240:241], v[176:177]
	v_pk_fma_f32 v[170:171], v[20:21], v[242:243], v[170:171]
	v_pk_fma_f32 v[172:173], v[22:23], v[244:245], v[172:173]
	v_pk_fma_f32 v[174:175], v[32:33], v[242:243], v[174:175]
	v_pk_fma_f32 v[176:177], v[34:35], v[244:245], v[176:177]
	v_pk_fma_f32 v[170:171], v[24:25], v[246:247], v[170:171]
	v_pk_fma_f32 v[172:173], v[26:27], v[248:249], v[172:173]
	v_pk_fma_f32 v[174:175], v[28:29], v[246:247], v[174:175]
	v_pk_fma_f32 v[176:177], v[30:31], v[248:249], v[176:177]
	v_pk_add_f32 v[170:171], v[170:171], v[172:173]
	v_pk_add_f32 v[174:175], v[174:175], v[176:177]
	s_nop 0
	v_add_f32_e32 v170, v170, v171
	v_add_f32_e32 v174, v174, v175
	s_nop 0
	s_nop 0
	v_add_f32_dpp v170, v170, v170 quad_perm:[1,0,3,2] row_mask:0xf bank_mask:0xf bound_ctrl:1
	v_add_f32_dpp v174, v174, v174 quad_perm:[1,0,3,2] row_mask:0xf bank_mask:0xf bound_ctrl:1
	s_nop 0
	s_nop 0
	v_add_f32_dpp v170, v170, v170 quad_perm:[2,3,0,1] row_mask:0xf bank_mask:0xf bound_ctrl:1
	v_add_f32_dpp v174, v174, v174 quad_perm:[2,3,0,1] row_mask:0xf bank_mask:0xf bound_ctrl:1
	s_nop 0
	s_nop 0
	v_cvt_pk_bf16_f32 v180, v170, v174
	s_mov_b64 exec, s[6:7]
	global_store_dword v[250:251], v180, off
	s_mov_b64 exec, -1
	s_waitcnt lgkmcnt(0)

.LBB0_1031:
	s_add_i32 s82, s43, s98
	s_ashr_i32 s83, s82, 31
	s_lshl_b64 s[82:83], s[82:83], 7
	v_lshl_add_u64 v[250:251], v[92:93], 0, s[82:83]
	ds_read_b128 v[60:63], v218 offset:256
	ds_read_b128 v[64:67], v218 offset:272
	ds_read_b128 v[68:71], v218 offset:288
	ds_read_b128 v[72:75], v218 offset:304
	ds_read_b128 v[76:79], v218 offset:512
	ds_read_b128 v[80:83], v218 offset:528
	ds_read_b128 v[84:87], v218 offset:544
	ds_read_b128 v[88:91], v218 offset:560
	ds_read_b64 v[178:179], v222 offset:1280
	s_waitcnt lgkmcnt(9)
	ds_read_b128 v[202:205], v218 offset:768
	ds_read_b128 v[206:209], v218 offset:784
	ds_read_b128 v[210:213], v218 offset:800
	ds_read_b128 v[214:217], v218 offset:816
	v_pk_mul_f32 v[158:159], v[12:13], v[44:45]
	v_pk_mul_f32 v[160:161], v[14:15], v[46:47]
	v_pk_mul_f32 v[162:163], v[40:41], v[44:45]
	v_pk_mul_f32 v[164:165], v[42:43], v[46:47]
	v_pk_fma_f32 v[158:159], v[16:17], v[48:49], v[158:159]
	v_pk_fma_f32 v[160:161], v[18:19], v[50:51], v[160:161]
	v_pk_fma_f32 v[162:163], v[36:37], v[48:49], v[162:163]
	v_pk_fma_f32 v[164:165], v[38:39], v[50:51], v[164:165]
	v_pk_fma_f32 v[158:159], v[20:21], v[52:53], v[158:159]
	v_pk_fma_f32 v[160:161], v[22:23], v[54:55], v[160:161]
	v_pk_fma_f32 v[162:163], v[32:33], v[52:53], v[162:163]
	v_pk_fma_f32 v[164:165], v[34:35], v[54:55], v[164:165]
	v_pk_fma_f32 v[158:159], v[24:25], v[56:57], v[158:159]
	v_pk_fma_f32 v[160:161], v[26:27], v[58:59], v[160:161]
	v_pk_fma_f32 v[162:163], v[28:29], v[56:57], v[162:163]
	v_pk_fma_f32 v[164:165], v[30:31], v[58:59], v[164:165]
	v_pk_add_f32 v[158:159], v[158:159], v[160:161]
	v_pk_add_f32 v[162:163], v[162:163], v[164:165]
	s_waitcnt lgkmcnt(5)
	v_add_f32_e32 v158, v158, v159
	v_add_f32_e32 v162, v162, v163
	ds_read_b128 v[234:237], v218 offset:1024
	ds_read_b128 v[238:241], v218 offset:1040
	v_add_f32_dpp v158, v158, v158 quad_perm:[1,0,3,2] row_mask:0xf bank_mask:0xf bound_ctrl:1
	v_add_f32_dpp v162, v162, v162 quad_perm:[1,0,3,2] row_mask:0xf bank_mask:0xf bound_ctrl:1
	ds_read_b128 v[242:245], v218 offset:1056
	ds_read_b128 v[246:249], v218 offset:1072
	v_add_f32_dpp v158, v158, v158 quad_perm:[2,3,0,1] row_mask:0xf bank_mask:0xf bound_ctrl:1
	v_add_f32_dpp v162, v162, v162 quad_perm:[2,3,0,1] row_mask:0xf bank_mask:0xf bound_ctrl:1
	v_pk_mul_f32 v[170:171], v[76:77], v[158:159] op_sel_hi:[1,0]
	v_pk_mul_f32 v[76:77], v[76:77], v[162:163] op_sel_hi:[1,0]
	v_pk_fma_f32 v[12:13], v[12:13], v[60:61], v[170:171]
	v_pk_fma_f32 v[40:41], v[40:41], v[60:61], v[76:77]
	v_pk_mul_f32 v[172:173], v[78:79], v[158:159] op_sel_hi:[1,0]
	v_pk_mul_f32 v[78:79], v[78:79], v[162:163] op_sel_hi:[1,0]
	v_pk_fma_f32 v[14:15], v[14:15], v[62:63], v[172:173]
	v_pk_fma_f32 v[42:43], v[42:43], v[62:63], v[78:79]
	v_pk_mul_f32 v[174:175], v[80:81], v[158:159] op_sel_hi:[1,0]
	v_pk_mul_f32 v[80:81], v[80:81], v[162:163] op_sel_hi:[1,0]
	v_pk_fma_f32 v[16:17], v[16:17], v[64:65], v[174:175]
	v_pk_fma_f32 v[36:37], v[36:37], v[64:65], v[80:81]
	v_pk_mul_f32 v[176:177], v[82:83], v[158:159] op_sel_hi:[1,0]
	v_pk_mul_f32 v[82:83], v[82:83], v[162:163] op_sel_hi:[1,0]
	v_pk_fma_f32 v[18:19], v[18:19], v[66:67], v[176:177]
	v_pk_fma_f32 v[38:39], v[38:39], v[66:67], v[82:83]
	v_pk_mul_f32 v[170:171], v[84:85], v[158:159] op_sel_hi:[1,0]
	v_pk_mul_f32 v[84:85], v[84:85], v[162:163] op_sel_hi:[1,0]
	v_pk_fma_f32 v[20:21], v[20:21], v[68:69], v[170:171]
	v_pk_fma_f32 v[32:33], v[32:33], v[68:69], v[84:85]
	v_pk_mul_f32 v[172:173], v[86:87], v[158:159] op_sel_hi:[1,0]
	v_pk_mul_f32 v[86:87], v[86:87], v[162:163] op_sel_hi:[1,0]
	v_pk_fma_f32 v[22:23], v[22:23], v[70:71], v[172:173]
	v_pk_fma_f32 v[34:35], v[34:35], v[70:71], v[86:87]
	v_pk_mul_f32 v[174:175], v[88:89], v[158:159] op_sel_hi:[1,0]
	v_pk_mul_f32 v[88:89], v[88:89], v[162:163] op_sel_hi:[1,0]
	v_pk_fma_f32 v[24:25], v[24:25], v[72:73], v[174:175]
	v_pk_fma_f32 v[28:29], v[28:29], v[72:73], v[88:89]
	v_pk_mul_f32 v[176:177], v[90:91], v[158:159] op_sel_hi:[1,0]
	v_pk_mul_f32 v[90:91], v[90:91], v[162:163] op_sel_hi:[1,0]
	v_pk_fma_f32 v[26:27], v[26:27], v[74:75], v[176:177]
	v_pk_fma_f32 v[30:31], v[30:31], v[74:75], v[90:91]
	ds_read_b128 v[44:47], v219 offset:0
	ds_read_b128 v[48:51], v219 offset:16
	ds_read_b128 v[52:55], v219 offset:32
	ds_read_b128 v[56:59], v219 offset:48
	s_waitcnt lgkmcnt(8)
	v_pk_fma_f32 v[142:143], v[178:179], v[202:203], v[12:13] op_sel_hi:[0,1,1]
	v_pk_fma_f32 v[186:187], v[178:179], v[202:203], v[40:41] op_sel:[1,0,0]
	v_pk_fma_f32 v[144:145], v[178:179], v[204:205], v[14:15] op_sel_hi:[0,1,1]
	v_pk_fma_f32 v[188:189], v[178:179], v[204:205], v[42:43] op_sel:[1,0,0]
	v_pk_fma_f32 v[146:147], v[178:179], v[206:207], v[16:17] op_sel_hi:[0,1,1]
	v_pk_fma_f32 v[190:191], v[178:179], v[206:207], v[36:37] op_sel:[1,0,0]
	v_pk_fma_f32 v[148:149], v[178:179], v[208:209], v[18:19] op_sel_hi:[0,1,1]
	v_pk_fma_f32 v[192:193], v[178:179], v[208:209], v[38:39] op_sel:[1,0,0]
	v_pk_fma_f32 v[150:151], v[178:179], v[210:211], v[20:21] op_sel_hi:[0,1,1]
	v_pk_fma_f32 v[194:195], v[178:179], v[210:211], v[32:33] op_sel:[1,0,0]
	v_pk_fma_f32 v[152:153], v[178:179], v[212:213], v[22:23] op_sel_hi:[0,1,1]
	v_pk_fma_f32 v[196:197], v[178:179], v[212:213], v[34:35] op_sel:[1,0,0]
	v_pk_fma_f32 v[154:155], v[178:179], v[214:215], v[24:25] op_sel_hi:[0,1,1]
	v_pk_fma_f32 v[198:199], v[178:179], v[214:215], v[28:29] op_sel:[1,0,0]
	v_pk_fma_f32 v[156:157], v[178:179], v[216:217], v[26:27] op_sel_hi:[0,1,1]
	v_pk_fma_f32 v[200:201], v[178:179], v[216:217], v[30:31] op_sel:[1,0,0]
	s_waitcnt lgkmcnt(4)
	v_pk_mul_f32 v[170:171], v[142:143], v[234:235]
	v_pk_mul_f32 v[172:173], v[144:145], v[236:237]
	v_pk_mul_f32 v[174:175], v[186:187], v[234:235]
	v_pk_mul_f32 v[176:177], v[188:189], v[236:237]
	v_pk_fma_f32 v[170:171], v[146:147], v[238:239], v[170:171]
	v_pk_fma_f32 v[172:173], v[148:149], v[240:241], v[172:173]
	v_pk_fma_f32 v[174:175], v[190:191], v[238:239], v[174:175]
	v_pk_fma_f32 v[176:177], v[192:193], v[240:241], v[176:177]
	v_pk_fma_f32 v[170:171], v[150:151], v[242:243], v[170:171]
	v_pk_fma_f32 v[172:173], v[152:153], v[244:245], v[172:173]
	v_pk_fma_f32 v[174:175], v[194:195], v[242:243], v[174:175]
	v_pk_fma_f32 v[176:177], v[196:197], v[244:245], v[176:177]
	v_pk_fma_f32 v[170:171], v[154:155], v[246:247], v[170:171]
	v_pk_fma_f32 v[172:173], v[156:157], v[248:249], v[172:173]
	v_pk_fma_f32 v[174:175], v[198:199], v[246:247], v[174:175]
	v_pk_fma_f32 v[176:177], v[200:201], v[248:249], v[176:177]
	v_pk_add_f32 v[170:171], v[170:171], v[172:173]
	v_pk_add_f32 v[174:175], v[174:175], v[176:177]
	ds_read_b128 v[60:63], v219 offset:256
	v_add_f32_e32 v170, v170, v171
	v_add_f32_e32 v174, v174, v175
	ds_read_b128 v[64:67], v219 offset:272
	ds_read_b128 v[68:71], v219 offset:288
	v_add_f32_dpp v170, v170, v170 quad_perm:[1,0,3,2] row_mask:0xf bank_mask:0xf bound_ctrl:1
	v_add_f32_dpp v174, v174, v174 quad_perm:[1,0,3,2] row_mask:0xf bank_mask:0xf bound_ctrl:1
	ds_read_b128 v[72:75], v219 offset:304
	ds_read_b128 v[76:79], v219 offset:512
	v_add_f32_dpp v170, v170, v170 quad_perm:[2,3,0,1] row_mask:0xf bank_mask:0xf bound_ctrl:1
	v_add_f32_dpp v174, v174, v174 quad_perm:[2,3,0,1] row_mask:0xf bank_mask:0xf bound_ctrl:1
	ds_read_b128 v[80:83], v219 offset:528
	ds_read_b128 v[84:87], v219 offset:544
	v_cvt_pk_bf16_f32 v180, v170, v174
	s_mov_b64 exec, s[6:7]
	global_store_dword v[250:251], v180, off
	s_mov_b64 exec, -1
	ds_read_b128 v[88:91], v219 offset:560
	ds_read_b64 v[178:179], v223 offset:1280
	v_lshl_add_u64 v[250:251], v[250:251], 0, s[80:81]
	s_waitcnt lgkmcnt(9)
	ds_read_b128 v[202:205], v219 offset:768
	ds_read_b128 v[206:209], v219 offset:784
	ds_read_b128 v[210:213], v219 offset:800
	ds_read_b128 v[214:217], v219 offset:816
	v_pk_mul_f32 v[158:159], v[142:143], v[44:45]
	v_pk_mul_f32 v[160:161], v[144:145], v[46:47]
	v_pk_mul_f32 v[162:163], v[186:187], v[44:45]
	v_pk_mul_f32 v[164:165], v[188:189], v[46:47]
	v_pk_fma_f32 v[158:159], v[146:147], v[48:49], v[158:159]
	v_pk_fma_f32 v[160:161], v[148:149], v[50:51], v[160:161]
	v_pk_fma_f32 v[162:163], v[190:191], v[48:49], v[162:163]
	v_pk_fma_f32 v[164:165], v[192:193], v[50:51], v[164:165]
	v_pk_fma_f32 v[158:159], v[150:151], v[52:53], v[158:159]
	v_pk_fma_f32 v[160:161], v[152:153], v[54:55], v[160:161]
	v_pk_fma_f32 v[162:163], v[194:195], v[52:53], v[162:163]
	v_pk_fma_f32 v[164:165], v[196:197], v[54:55], v[164:165]
	v_pk_fma_f32 v[158:159], v[154:155], v[56:57], v[158:159]
	v_pk_fma_f32 v[160:161], v[156:157], v[58:59], v[160:161]
	v_pk_fma_f32 v[162:163], v[198:199], v[56:57], v[162:163]
	v_pk_fma_f32 v[164:165], v[200:201], v[58:59], v[164:165]
	v_pk_add_f32 v[158:159], v[158:159], v[160:161]
	v_pk_add_f32 v[162:163], v[162:163], v[164:165]
	s_waitcnt lgkmcnt(5)
	v_add_f32_e32 v158, v158, v159
	v_add_f32_e32 v162, v162, v163
	ds_read_b128 v[234:237], v219 offset:1024
	ds_read_b128 v[238:241], v219 offset:1040
	v_add_f32_dpp v158, v158, v158 quad_perm:[1,0,3,2] row_mask:0xf bank_mask:0xf bound_ctrl:1
	v_add_f32_dpp v162, v162, v162 quad_perm:[1,0,3,2] row_mask:0xf bank_mask:0xf bound_ctrl:1
	ds_read_b128 v[242:245], v219 offset:1056
	ds_read_b128 v[246:249], v219 offset:1072
	v_add_f32_dpp v158, v158, v158 quad_perm:[2,3,0,1] row_mask:0xf bank_mask:0xf bound_ctrl:1
	v_add_f32_dpp v162, v162, v162 quad_perm:[2,3,0,1] row_mask:0xf bank_mask:0xf bound_ctrl:1
	v_pk_mul_f32 v[170:171], v[76:77], v[158:159] op_sel_hi:[1,0]
	v_pk_mul_f32 v[76:77], v[76:77], v[162:163] op_sel_hi:[1,0]
	v_pk_fma_f32 v[142:143], v[142:143], v[60:61], v[170:171]
	v_pk_fma_f32 v[186:187], v[186:187], v[60:61], v[76:77]
	v_pk_mul_f32 v[172:173], v[78:79], v[158:159] op_sel_hi:[1,0]
	v_pk_mul_f32 v[78:79], v[78:79], v[162:163] op_sel_hi:[1,0]
	v_pk_fma_f32 v[144:145], v[144:145], v[62:63], v[172:173]
	v_pk_fma_f32 v[188:189], v[188:189], v[62:63], v[78:79]
	v_pk_mul_f32 v[174:175], v[80:81], v[158:159] op_sel_hi:[1,0]
	v_pk_mul_f32 v[80:81], v[80:81], v[162:163] op_sel_hi:[1,0]
	v_pk_fma_f32 v[146:147], v[146:147], v[64:65], v[174:175]
	v_pk_fma_f32 v[190:191], v[190:191], v[64:65], v[80:81]
	v_pk_mul_f32 v[176:177], v[82:83], v[158:159] op_sel_hi:[1,0]
	v_pk_mul_f32 v[82:83], v[82:83], v[162:163] op_sel_hi:[1,0]
	v_pk_fma_f32 v[148:149], v[148:149], v[66:67], v[176:177]
	v_pk_fma_f32 v[192:193], v[192:193], v[66:67], v[82:83]
	v_pk_mul_f32 v[170:171], v[84:85], v[158:159] op_sel_hi:[1,0]
	v_pk_mul_f32 v[84:85], v[84:85], v[162:163] op_sel_hi:[1,0]
	v_pk_fma_f32 v[150:151], v[150:151], v[68:69], v[170:171]
	v_pk_fma_f32 v[194:195], v[194:195], v[68:69], v[84:85]
	v_pk_mul_f32 v[172:173], v[86:87], v[158:159] op_sel_hi:[1,0]
	v_pk_mul_f32 v[86:87], v[86:87], v[162:163] op_sel_hi:[1,0]
	v_pk_fma_f32 v[152:153], v[152:153], v[70:71], v[172:173]
	v_pk_fma_f32 v[196:197], v[196:197], v[70:71], v[86:87]
	v_pk_mul_f32 v[174:175], v[88:89], v[158:159] op_sel_hi:[1,0]
	v_pk_mul_f32 v[88:89], v[88:89], v[162:163] op_sel_hi:[1,0]
	v_pk_fma_f32 v[154:155], v[154:155], v[72:73], v[174:175]
	v_pk_fma_f32 v[198:199], v[198:199], v[72:73], v[88:89]
	v_pk_mul_f32 v[176:177], v[90:91], v[158:159] op_sel_hi:[1,0]
	v_pk_mul_f32 v[90:91], v[90:91], v[162:163] op_sel_hi:[1,0]
	v_pk_fma_f32 v[156:157], v[156:157], v[74:75], v[176:177]
	v_pk_fma_f32 v[200:201], v[200:201], v[74:75], v[90:91]
	ds_read_b128 v[44:47], v220 offset:0
	ds_read_b128 v[48:51], v220 offset:16
	ds_read_b128 v[52:55], v220 offset:32
	ds_read_b128 v[56:59], v220 offset:48
	s_waitcnt lgkmcnt(8)
	v_pk_fma_f32 v[12:13], v[178:179], v[202:203], v[142:143] op_sel_hi:[0,1,1]
	v_pk_fma_f32 v[40:41], v[178:179], v[202:203], v[186:187] op_sel:[1,0,0]
	v_pk_fma_f32 v[14:15], v[178:179], v[204:205], v[144:145] op_sel_hi:[0,1,1]
	v_pk_fma_f32 v[42:43], v[178:179], v[204:205], v[188:189] op_sel:[1,0,0]
	v_pk_fma_f32 v[16:17], v[178:179], v[206:207], v[146:147] op_sel_hi:[0,1,1]
	v_pk_fma_f32 v[36:37], v[178:179], v[206:207], v[190:191] op_sel:[1,0,0]
	v_pk_fma_f32 v[18:19], v[178:179], v[208:209], v[148:149] op_sel_hi:[0,1,1]
	v_pk_fma_f32 v[38:39], v[178:179], v[208:209], v[192:193] op_sel:[1,0,0]
	v_pk_fma_f32 v[20:21], v[178:179], v[210:211], v[150:151] op_sel_hi:[0,1,1]
	v_pk_fma_f32 v[32:33], v[178:179], v[210:211], v[194:195] op_sel:[1,0,0]
	v_pk_fma_f32 v[22:23], v[178:179], v[212:213], v[152:153] op_sel_hi:[0,1,1]
	v_pk_fma_f32 v[34:35], v[178:179], v[212:213], v[196:197] op_sel:[1,0,0]
	v_pk_fma_f32 v[24:25], v[178:179], v[214:215], v[154:155] op_sel_hi:[0,1,1]
	v_pk_fma_f32 v[28:29], v[178:179], v[214:215], v[198:199] op_sel:[1,0,0]
	v_pk_fma_f32 v[26:27], v[178:179], v[216:217], v[156:157] op_sel_hi:[0,1,1]
	v_pk_fma_f32 v[30:31], v[178:179], v[216:217], v[200:201] op_sel:[1,0,0]
	s_waitcnt lgkmcnt(4)
	v_pk_mul_f32 v[170:171], v[12:13], v[234:235]
	v_pk_mul_f32 v[172:173], v[14:15], v[236:237]
	v_pk_mul_f32 v[174:175], v[40:41], v[234:235]
	v_pk_mul_f32 v[176:177], v[42:43], v[236:237]
	v_pk_fma_f32 v[170:171], v[16:17], v[238:239], v[170:171]
	v_pk_fma_f32 v[172:173], v[18:19], v[240:241], v[172:173]
	v_pk_fma_f32 v[174:175], v[36:37], v[238:239], v[174:175]
	v_pk_fma_f32 v[176:177], v[38:39], v[240:241], v[176:177]
	v_pk_fma_f32 v[170:171], v[20:21], v[242:243], v[170:171]
	v_pk_fma_f32 v[172:173], v[22:23], v[244:245], v[172:173]
	v_pk_fma_f32 v[174:175], v[32:33], v[242:243], v[174:175]
	v_pk_fma_f32 v[176:177], v[34:35], v[244:245], v[176:177]
	v_pk_fma_f32 v[170:171], v[24:25], v[246:247], v[170:171]
	v_pk_fma_f32 v[172:173], v[26:27], v[248:249], v[172:173]
	v_pk_fma_f32 v[174:175], v[28:29], v[246:247], v[174:175]
	v_pk_fma_f32 v[176:177], v[30:31], v[248:249], v[176:177]
	v_pk_add_f32 v[170:171], v[170:171], v[172:173]
	v_pk_add_f32 v[174:175], v[174:175], v[176:177]
	ds_read_b128 v[60:63], v220 offset:256
	v_add_f32_e32 v170, v170, v171
	v_add_f32_e32 v174, v174, v175
	ds_read_b128 v[64:67], v220 offset:272
	ds_read_b128 v[68:71], v220 offset:288
	v_add_f32_dpp v170, v170, v170 quad_perm:[1,0,3,2] row_mask:0xf bank_mask:0xf bound_ctrl:1
	v_add_f32_dpp v174, v174, v174 quad_perm:[1,0,3,2] row_mask:0xf bank_mask:0xf bound_ctrl:1
	ds_read_b128 v[72:75], v220 offset:304
	ds_read_b128 v[76:79], v220 offset:512
	v_add_f32_dpp v170, v170, v170 quad_perm:[2,3,0,1] row_mask:0xf bank_mask:0xf bound_ctrl:1
	v_add_f32_dpp v174, v174, v174 quad_perm:[2,3,0,1] row_mask:0xf bank_mask:0xf bound_ctrl:1
	ds_read_b128 v[80:83], v220 offset:528
	ds_read_b128 v[84:87], v220 offset:544
	v_cvt_pk_bf16_f32 v180, v170, v174
	s_mov_b64 exec, s[6:7]
	global_store_dword v[250:251], v180, off
	s_mov_b64 exec, -1
	ds_read_b128 v[88:91], v220 offset:560
	ds_read_b64 v[178:179], v224 offset:1280
	v_lshl_add_u64 v[250:251], v[250:251], 0, s[80:81]
	s_waitcnt lgkmcnt(9)
	ds_read_b128 v[202:205], v220 offset:768
	ds_read_b128 v[206:209], v220 offset:784
	ds_read_b128 v[210:213], v220 offset:800
	ds_read_b128 v[214:217], v220 offset:816
	v_pk_mul_f32 v[158:159], v[12:13], v[44:45]
	v_pk_mul_f32 v[160:161], v[14:15], v[46:47]
	v_pk_mul_f32 v[162:163], v[40:41], v[44:45]
	v_pk_mul_f32 v[164:165], v[42:43], v[46:47]
	v_pk_fma_f32 v[158:159], v[16:17], v[48:49], v[158:159]
	v_pk_fma_f32 v[160:161], v[18:19], v[50:51], v[160:161]
	v_pk_fma_f32 v[162:163], v[36:37], v[48:49], v[162:163]
	v_pk_fma_f32 v[164:165], v[38:39], v[50:51], v[164:165]
	v_pk_fma_f32 v[158:159], v[20:21], v[52:53], v[158:159]
	v_pk_fma_f32 v[160:161], v[22:23], v[54:55], v[160:161]
	v_pk_fma_f32 v[162:163], v[32:33], v[52:53], v[162:163]
	v_pk_fma_f32 v[164:165], v[34:35], v[54:55], v[164:165]
	v_pk_fma_f32 v[158:159], v[24:25], v[56:57], v[158:159]
	v_pk_fma_f32 v[160:161], v[26:27], v[58:59], v[160:161]
	v_pk_fma_f32 v[162:163], v[28:29], v[56:57], v[162:163]
	v_pk_fma_f32 v[164:165], v[30:31], v[58:59], v[164:165]
	v_pk_add_f32 v[158:159], v[158:159], v[160:161]
	v_pk_add_f32 v[162:163], v[162:163], v[164:165]
	s_waitcnt lgkmcnt(5)
	v_add_f32_e32 v158, v158, v159
	v_add_f32_e32 v162, v162, v163
	ds_read_b128 v[234:237], v220 offset:1024
	ds_read_b128 v[238:241], v220 offset:1040
	v_add_f32_dpp v158, v158, v158 quad_perm:[1,0,3,2] row_mask:0xf bank_mask:0xf bound_ctrl:1
	v_add_f32_dpp v162, v162, v162 quad_perm:[1,0,3,2] row_mask:0xf bank_mask:0xf bound_ctrl:1
	ds_read_b128 v[242:245], v220 offset:1056
	ds_read_b128 v[246:249], v220 offset:1072
	v_add_f32_dpp v158, v158, v158 quad_perm:[2,3,0,1] row_mask:0xf bank_mask:0xf bound_ctrl:1
	v_add_f32_dpp v162, v162, v162 quad_perm:[2,3,0,1] row_mask:0xf bank_mask:0xf bound_ctrl:1
	v_pk_mul_f32 v[170:171], v[76:77], v[158:159] op_sel_hi:[1,0]
	v_pk_mul_f32 v[76:77], v[76:77], v[162:163] op_sel_hi:[1,0]
	v_pk_fma_f32 v[12:13], v[12:13], v[60:61], v[170:171]
	v_pk_fma_f32 v[40:41], v[40:41], v[60:61], v[76:77]
	v_pk_mul_f32 v[172:173], v[78:79], v[158:159] op_sel_hi:[1,0]
	v_pk_mul_f32 v[78:79], v[78:79], v[162:163] op_sel_hi:[1,0]
	v_pk_fma_f32 v[14:15], v[14:15], v[62:63], v[172:173]
	v_pk_fma_f32 v[42:43], v[42:43], v[62:63], v[78:79]
	v_pk_mul_f32 v[174:175], v[80:81], v[158:159] op_sel_hi:[1,0]
	v_pk_mul_f32 v[80:81], v[80:81], v[162:163] op_sel_hi:[1,0]
	v_pk_fma_f32 v[16:17], v[16:17], v[64:65], v[174:175]
	v_pk_fma_f32 v[36:37], v[36:37], v[64:65], v[80:81]
	v_pk_mul_f32 v[176:177], v[82:83], v[158:159] op_sel_hi:[1,0]
	v_pk_mul_f32 v[82:83], v[82:83], v[162:163] op_sel_hi:[1,0]
	v_pk_fma_f32 v[18:19], v[18:19], v[66:67], v[176:177]
	v_pk_fma_f32 v[38:39], v[38:39], v[66:67], v[82:83]
	v_pk_mul_f32 v[170:171], v[84:85], v[158:159] op_sel_hi:[1,0]
	v_pk_mul_f32 v[84:85], v[84:85], v[162:163] op_sel_hi:[1,0]
	v_pk_fma_f32 v[20:21], v[20:21], v[68:69], v[170:171]
	v_pk_fma_f32 v[32:33], v[32:33], v[68:69], v[84:85]
	v_pk_mul_f32 v[172:173], v[86:87], v[158:159] op_sel_hi:[1,0]
	v_pk_mul_f32 v[86:87], v[86:87], v[162:163] op_sel_hi:[1,0]
	v_pk_fma_f32 v[22:23], v[22:23], v[70:71], v[172:173]
	v_pk_fma_f32 v[34:35], v[34:35], v[70:71], v[86:87]
	v_pk_mul_f32 v[174:175], v[88:89], v[158:159] op_sel_hi:[1,0]
	v_pk_mul_f32 v[88:89], v[88:89], v[162:163] op_sel_hi:[1,0]
	v_pk_fma_f32 v[24:25], v[24:25], v[72:73], v[174:175]
	v_pk_fma_f32 v[28:29], v[28:29], v[72:73], v[88:89]
	v_pk_mul_f32 v[176:177], v[90:91], v[158:159] op_sel_hi:[1,0]
	v_pk_mul_f32 v[90:91], v[90:91], v[162:163] op_sel_hi:[1,0]
	v_pk_fma_f32 v[26:27], v[26:27], v[74:75], v[176:177]
	v_pk_fma_f32 v[30:31], v[30:31], v[74:75], v[90:91]
	ds_read_b128 v[44:47], v221 offset:0
	ds_read_b128 v[48:51], v221 offset:16
	ds_read_b128 v[52:55], v221 offset:32
	ds_read_b128 v[56:59], v221 offset:48
	s_waitcnt lgkmcnt(8)
	v_pk_fma_f32 v[142:143], v[178:179], v[202:203], v[12:13] op_sel_hi:[0,1,1]
	v_pk_fma_f32 v[186:187], v[178:179], v[202:203], v[40:41] op_sel:[1,0,0]
	v_pk_fma_f32 v[144:145], v[178:179], v[204:205], v[14:15] op_sel_hi:[0,1,1]
	v_pk_fma_f32 v[188:189], v[178:179], v[204:205], v[42:43] op_sel:[1,0,0]
	v_pk_fma_f32 v[146:147], v[178:179], v[206:207], v[16:17] op_sel_hi:[0,1,1]
	v_pk_fma_f32 v[190:191], v[178:179], v[206:207], v[36:37] op_sel:[1,0,0]
	v_pk_fma_f32 v[148:149], v[178:179], v[208:209], v[18:19] op_sel_hi:[0,1,1]
	v_pk_fma_f32 v[192:193], v[178:179], v[208:209], v[38:39] op_sel:[1,0,0]
	v_pk_fma_f32 v[150:151], v[178:179], v[210:211], v[20:21] op_sel_hi:[0,1,1]
	v_pk_fma_f32 v[194:195], v[178:179], v[210:211], v[32:33] op_sel:[1,0,0]
	v_pk_fma_f32 v[152:153], v[178:179], v[212:213], v[22:23] op_sel_hi:[0,1,1]
	v_pk_fma_f32 v[196:197], v[178:179], v[212:213], v[34:35] op_sel:[1,0,0]
	v_pk_fma_f32 v[154:155], v[178:179], v[214:215], v[24:25] op_sel_hi:[0,1,1]
	v_pk_fma_f32 v[198:199], v[178:179], v[214:215], v[28:29] op_sel:[1,0,0]
	v_pk_fma_f32 v[156:157], v[178:179], v[216:217], v[26:27] op_sel_hi:[0,1,1]
	v_pk_fma_f32 v[200:201], v[178:179], v[216:217], v[30:31] op_sel:[1,0,0]
	s_waitcnt lgkmcnt(4)
	v_pk_mul_f32 v[170:171], v[142:143], v[234:235]
	v_pk_mul_f32 v[172:173], v[144:145], v[236:237]
	v_pk_mul_f32 v[174:175], v[186:187], v[234:235]
	v_pk_mul_f32 v[176:177], v[188:189], v[236:237]
	v_pk_fma_f32 v[170:171], v[146:147], v[238:239], v[170:171]
	v_pk_fma_f32 v[172:173], v[148:149], v[240:241], v[172:173]
	v_pk_fma_f32 v[174:175], v[190:191], v[238:239], v[174:175]
	v_pk_fma_f32 v[176:177], v[192:193], v[240:241], v[176:177]
	v_pk_fma_f32 v[170:171], v[150:151], v[242:243], v[170:171]
	v_pk_fma_f32 v[172:173], v[152:153], v[244:245], v[172:173]
	v_pk_fma_f32 v[174:175], v[194:195], v[242:243], v[174:175]
	v_pk_fma_f32 v[176:177], v[196:197], v[244:245], v[176:177]
	v_pk_fma_f32 v[170:171], v[154:155], v[246:247], v[170:171]
	v_pk_fma_f32 v[172:173], v[156:157], v[248:249], v[172:173]
	v_pk_fma_f32 v[174:175], v[198:199], v[246:247], v[174:175]
	v_pk_fma_f32 v[176:177], v[200:201], v[248:249], v[176:177]
	v_pk_add_f32 v[170:171], v[170:171], v[172:173]
	v_pk_add_f32 v[174:175], v[174:175], v[176:177]
	ds_read_b128 v[60:63], v221 offset:256
	v_add_f32_e32 v170, v170, v171
	v_add_f32_e32 v174, v174, v175
	ds_read_b128 v[64:67], v221 offset:272
	ds_read_b128 v[68:71], v221 offset:288
	v_add_f32_dpp v170, v170, v170 quad_perm:[1,0,3,2] row_mask:0xf bank_mask:0xf bound_ctrl:1
	v_add_f32_dpp v174, v174, v174 quad_perm:[1,0,3,2] row_mask:0xf bank_mask:0xf bound_ctrl:1
	ds_read_b128 v[72:75], v221 offset:304
	ds_read_b128 v[76:79], v221 offset:512
	v_add_f32_dpp v170, v170, v170 quad_perm:[2,3,0,1] row_mask:0xf bank_mask:0xf bound_ctrl:1
	v_add_f32_dpp v174, v174, v174 quad_perm:[2,3,0,1] row_mask:0xf bank_mask:0xf bound_ctrl:1
	ds_read_b128 v[80:83], v221 offset:528
	ds_read_b128 v[84:87], v221 offset:544
	v_cvt_pk_bf16_f32 v180, v170, v174
	s_mov_b64 exec, s[6:7]
	global_store_dword v[250:251], v180, off
	s_mov_b64 exec, -1
	ds_read_b128 v[88:91], v221 offset:560
	ds_read_b64 v[178:179], v228 offset:1280
	v_lshl_add_u64 v[250:251], v[250:251], 0, s[80:81]
	s_waitcnt lgkmcnt(9)
	ds_read_b128 v[202:205], v221 offset:768
	ds_read_b128 v[206:209], v221 offset:784
	ds_read_b128 v[210:213], v221 offset:800
	ds_read_b128 v[214:217], v221 offset:816
	v_pk_mul_f32 v[158:159], v[142:143], v[44:45]
	v_pk_mul_f32 v[160:161], v[144:145], v[46:47]
	v_pk_mul_f32 v[162:163], v[186:187], v[44:45]
	v_pk_mul_f32 v[164:165], v[188:189], v[46:47]
	v_pk_fma_f32 v[158:159], v[146:147], v[48:49], v[158:159]
	v_pk_fma_f32 v[160:161], v[148:149], v[50:51], v[160:161]
	v_pk_fma_f32 v[162:163], v[190:191], v[48:49], v[162:163]
	v_pk_fma_f32 v[164:165], v[192:193], v[50:51], v[164:165]
	v_pk_fma_f32 v[158:159], v[150:151], v[52:53], v[158:159]
	v_pk_fma_f32 v[160:161], v[152:153], v[54:55], v[160:161]
	v_pk_fma_f32 v[162:163], v[194:195], v[52:53], v[162:163]
	v_pk_fma_f32 v[164:165], v[196:197], v[54:55], v[164:165]
	v_pk_fma_f32 v[158:159], v[154:155], v[56:57], v[158:159]
	v_pk_fma_f32 v[160:161], v[156:157], v[58:59], v[160:161]
	v_pk_fma_f32 v[162:163], v[198:199], v[56:57], v[162:163]
	v_pk_fma_f32 v[164:165], v[200:201], v[58:59], v[164:165]
	v_pk_add_f32 v[158:159], v[158:159], v[160:161]
	v_pk_add_f32 v[162:163], v[162:163], v[164:165]
	s_waitcnt lgkmcnt(5)
	v_add_f32_e32 v158, v158, v159
	v_add_f32_e32 v162, v162, v163
	ds_read_b128 v[234:237], v221 offset:1024
	ds_read_b128 v[238:241], v221 offset:1040
	v_add_f32_dpp v158, v158, v158 quad_perm:[1,0,3,2] row_mask:0xf bank_mask:0xf bound_ctrl:1
	v_add_f32_dpp v162, v162, v162 quad_perm:[1,0,3,2] row_mask:0xf bank_mask:0xf bound_ctrl:1
	ds_read_b128 v[242:245], v221 offset:1056
	ds_read_b128 v[246:249], v221 offset:1072
	v_add_f32_dpp v158, v158, v158 quad_perm:[2,3,0,1] row_mask:0xf bank_mask:0xf bound_ctrl:1
	v_add_f32_dpp v162, v162, v162 quad_perm:[2,3,0,1] row_mask:0xf bank_mask:0xf bound_ctrl:1
	v_pk_mul_f32 v[170:171], v[76:77], v[158:159] op_sel_hi:[1,0]
	v_pk_mul_f32 v[76:77], v[76:77], v[162:163] op_sel_hi:[1,0]
	v_pk_fma_f32 v[142:143], v[142:143], v[60:61], v[170:171]
	v_pk_fma_f32 v[186:187], v[186:187], v[60:61], v[76:77]
	v_pk_mul_f32 v[172:173], v[78:79], v[158:159] op_sel_hi:[1,0]
	v_pk_mul_f32 v[78:79], v[78:79], v[162:163] op_sel_hi:[1,0]
	v_pk_fma_f32 v[144:145], v[144:145], v[62:63], v[172:173]
	v_pk_fma_f32 v[188:189], v[188:189], v[62:63], v[78:79]
	v_pk_mul_f32 v[174:175], v[80:81], v[158:159] op_sel_hi:[1,0]
	v_pk_mul_f32 v[80:81], v[80:81], v[162:163] op_sel_hi:[1,0]
	v_pk_fma_f32 v[146:147], v[146:147], v[64:65], v[174:175]
	v_pk_fma_f32 v[190:191], v[190:191], v[64:65], v[80:81]
	v_pk_mul_f32 v[176:177], v[82:83], v[158:159] op_sel_hi:[1,0]
	v_pk_mul_f32 v[82:83], v[82:83], v[162:163] op_sel_hi:[1,0]
	v_pk_fma_f32 v[148:149], v[148:149], v[66:67], v[176:177]
	v_pk_fma_f32 v[192:193], v[192:193], v[66:67], v[82:83]
	v_pk_mul_f32 v[170:171], v[84:85], v[158:159] op_sel_hi:[1,0]
	v_pk_mul_f32 v[84:85], v[84:85], v[162:163] op_sel_hi:[1,0]
	v_pk_fma_f32 v[150:151], v[150:151], v[68:69], v[170:171]
	v_pk_fma_f32 v[194:195], v[194:195], v[68:69], v[84:85]
	v_pk_mul_f32 v[172:173], v[86:87], v[158:159] op_sel_hi:[1,0]
	v_pk_mul_f32 v[86:87], v[86:87], v[162:163] op_sel_hi:[1,0]
	v_pk_fma_f32 v[152:153], v[152:153], v[70:71], v[172:173]
	v_pk_fma_f32 v[196:197], v[196:197], v[70:71], v[86:87]
	v_pk_mul_f32 v[174:175], v[88:89], v[158:159] op_sel_hi:[1,0]
	v_pk_mul_f32 v[88:89], v[88:89], v[162:163] op_sel_hi:[1,0]
	v_pk_fma_f32 v[154:155], v[154:155], v[72:73], v[174:175]
	v_pk_fma_f32 v[198:199], v[198:199], v[72:73], v[88:89]
	v_pk_mul_f32 v[176:177], v[90:91], v[158:159] op_sel_hi:[1,0]
	v_pk_mul_f32 v[90:91], v[90:91], v[162:163] op_sel_hi:[1,0]
	v_pk_fma_f32 v[156:157], v[156:157], v[74:75], v[176:177]
	v_pk_fma_f32 v[200:201], v[200:201], v[74:75], v[90:91]
	s_waitcnt lgkmcnt(4)
	v_pk_fma_f32 v[12:13], v[178:179], v[202:203], v[142:143] op_sel_hi:[0,1,1]
	v_pk_fma_f32 v[40:41], v[178:179], v[202:203], v[186:187] op_sel:[1,0,0]
	v_pk_fma_f32 v[14:15], v[178:179], v[204:205], v[144:145] op_sel_hi:[0,1,1]
	v_pk_fma_f32 v[42:43], v[178:179], v[204:205], v[188:189] op_sel:[1,0,0]
	v_pk_fma_f32 v[16:17], v[178:179], v[206:207], v[146:147] op_sel_hi:[0,1,1]
	v_pk_fma_f32 v[36:37], v[178:179], v[206:207], v[190:191] op_sel:[1,0,0]
	v_pk_fma_f32 v[18:19], v[178:179], v[208:209], v[148:149] op_sel_hi:[0,1,1]
	v_pk_fma_f32 v[38:39], v[178:179], v[208:209], v[192:193] op_sel:[1,0,0]
	v_pk_fma_f32 v[20:21], v[178:179], v[210:211], v[150:151] op_sel_hi:[0,1,1]
	v_pk_fma_f32 v[32:33], v[178:179], v[210:211], v[194:195] op_sel:[1,0,0]
	v_pk_fma_f32 v[22:23], v[178:179], v[212:213], v[152:153] op_sel_hi:[0,1,1]
	v_pk_fma_f32 v[34:35], v[178:179], v[212:213], v[196:197] op_sel:[1,0,0]
	v_pk_fma_f32 v[24:25], v[178:179], v[214:215], v[154:155] op_sel_hi:[0,1,1]
	v_pk_fma_f32 v[28:29], v[178:179], v[214:215], v[198:199] op_sel:[1,0,0]
	v_pk_fma_f32 v[26:27], v[178:179], v[216:217], v[156:157] op_sel_hi:[0,1,1]
	v_pk_fma_f32 v[30:31], v[178:179], v[216:217], v[200:201] op_sel:[1,0,0]
	s_waitcnt lgkmcnt(0)
	v_pk_mul_f32 v[170:171], v[12:13], v[234:235]
	v_pk_mul_f32 v[172:173], v[14:15], v[236:237]
	v_pk_mul_f32 v[174:175], v[40:41], v[234:235]
	v_pk_mul_f32 v[176:177], v[42:43], v[236:237]
	v_pk_fma_f32 v[170:171], v[16:17], v[238:239], v[170:171]
	v_pk_fma_f32 v[172:173], v[18:19], v[240:241], v[172:173]
	v_pk_fma_f32 v[174:175], v[36:37], v[238:239], v[174:175]
	v_pk_fma_f32 v[176:177], v[38:39], v[240:241], v[176:177]
	v_pk_fma_f32 v[170:171], v[20:21], v[242:243], v[170:171]
	v_pk_fma_f32 v[172:173], v[22:23], v[244:245], v[172:173]
	v_pk_fma_f32 v[174:175], v[32:33], v[242:243], v[174:175]
	v_pk_fma_f32 v[176:177], v[34:35], v[244:245], v[176:177]
	v_pk_fma_f32 v[170:171], v[24:25], v[246:247], v[170:171]
	v_pk_fma_f32 v[172:173], v[26:27], v[248:249], v[172:173]
	v_pk_fma_f32 v[174:175], v[28:29], v[246:247], v[174:175]
	v_pk_fma_f32 v[176:177], v[30:31], v[248:249], v[176:177]
	v_pk_add_f32 v[170:171], v[170:171], v[172:173]
	v_pk_add_f32 v[174:175], v[174:175], v[176:177]
	s_nop 0
	v_add_f32_e32 v170, v170, v171
	v_add_f32_e32 v174, v174, v175
	s_nop 0
	s_nop 0
	v_add_f32_dpp v170, v170, v170 quad_perm:[1,0,3,2] row_mask:0xf bank_mask:0xf bound_ctrl:1
	v_add_f32_dpp v174, v174, v174 quad_perm:[1,0,3,2] row_mask:0xf bank_mask:0xf bound_ctrl:1
	s_nop 0
	s_nop 0
	v_add_f32_dpp v170, v170, v170 quad_perm:[2,3,0,1] row_mask:0xf bank_mask:0xf bound_ctrl:1
	v_add_f32_dpp v174, v174, v174 quad_perm:[2,3,0,1] row_mask:0xf bank_mask:0xf bound_ctrl:1
	s_nop 0
	s_nop 0
	v_cvt_pk_bf16_f32 v180, v170, v174
	s_mov_b64 exec, s[6:7]
	global_store_dword v[250:251], v180, off
	s_mov_b64 exec, -1
	s_waitcnt lgkmcnt(0)
